# GEMM K loops: loop-carried pointer/counter updates and the exit test moved in front of the loop-back barrier (back-edge rotation)
# speedup vs baseline: 1.0016x; 1.0016x over previous
; #define PG8_STAGE(bufoff, gbase, voff) do { _Pragma("unroll") for (int _i = 0; _i < 2; ++_i) \
;         __builtin_amdgcn_global_load_lds((const unsigned*)((const char*)(gbase) + (voff)[_i]), (PG8_LAS unsigned*)(lds + (bufoff) + ldsw + _i * 8192), 16, 0, 0); } while (0)
; #define PG8_LDA(dst, b, h) do { _Pragma("unroll") for (int m = 0; m < 4; ++m) _Pragma("unroll") for (int k = 0; k < 2; ++k) dst[m][k] = *(const PG8_LAS bf16x8*)(lds + PG8_SA(b, h) + aoff + m * 2048 + k * 1024); } while (0)
; #define PG8_LDB(dst, b, h) do { _Pragma("unroll") for (int n = 0; n < 2; ++n) _Pragma("unroll") for (int k = 0; k < 2; ++k) dst[n][k] = *(const PG8_LAS bf16x8*)(lds + PG8_SB(b, h) + boff + n * 2048 + k * 1024); } while (0)
; #define PG8_MMA(ai, bj, At, Bt) do { __builtin_amdgcn_s_setprio(1); _Pragma("unroll") for (int m = 0; m < 4; ++m) _Pragma("unroll") for (int n = 0; n < 2; ++n) _Pragma("unroll") for (int k = 0; k < 2; ++k) \
;         acc[ai][bj][m][n] = __builtin_amdgcn_mfma_f32_16x16x32_bf16(Bt[n][k], At[m][k], acc[ai][bj][m][n], 0, 0, 0); __builtin_amdgcn_s_setprio(0); } while (0)
; #define PG8_WAIT_V(n) asm volatile("s_waitcnt vmcnt(" #n ")" ::: "memory")
; #define PG8_WAIT_L(n) asm volatile("s_waitcnt lgkmcnt(" #n ")" ::: "memory")
; #define PG8_BAR __builtin_amdgcn_s_barrier()
; #define PG8_SCHED __builtin_amdgcn_sched_barrier(0)
; template <class Epi, class Sched, bool ALIGN_EPI = false, bool SP2 = false>
; __device__ __forceinline__ void gemm_phase(PG8_LAS unsigned char* lds, const Gemm g, const Sched& S, const Epi& E, const int tid_in) {
;     ...
;             PG8_LDB(B0, 0, 0); PG8_LDB(B1, 0, 1); PG8_SCHED; PG8_LDA(At, 0, 0); PG8_STAGE(PG8_SA(1, 1), a1 + hstep, voffA);
;             PG8_WAIT_V(8); PG8_WAIT_L(0); PG8_BAR; PG8_MMA(0, 0, At, B0); PG8_MMA(0, 1, At, B1); PG8_BAR; PG8_SCHED;
;             PG8_LDA(At, 0, 1); PG8_STAGE(PG8_SB(0, 0), b2, voffB); PG8_STAGE(PG8_SB(0, 1), b2 + hstep, voffB); PG8_STAGE(PG8_SA(0, 0), a2, voffA);
;             PG8_WAIT_V(8); PG8_WAIT_L(0); PG8_BAR; PG8_MMA(1, 0, At, B0); PG8_MMA(1, 1, At, B1); PG8_BAR; PG8_SCHED;
.LBB0_127:
	ds_read_b128 v[128:131], v190
	ds_read_b128 v[132:135], v190 offset:1024
	ds_read_b128 v[136:139], v190 offset:2048
	ds_read_b128 v[140:143], v190 offset:3072
	ds_read_b128 v[166:169], v191
	ds_read_b128 v[194:197], v191 offset:1024
	ds_read_b128 v[198:201], v191 offset:2048
	ds_read_b128 v[202:205], v191 offset:3072
	s_add_u32 s34, s0, 0xfffc0080
	s_addc_u32 s35, s1, -1
	s_cmp_eq_u32 s59, 12
	s_cselect_b32 s37, s5, s35
	s_cselect_b32 s36, s25, s34
	s_cselect_b32 s35, s23, s58
	s_cselect_b32 s34, s56, s57
	v_lshl_add_u64 v[170:171], s[0:1], 0, v[158:159]
	s_add_i32 m0, s31, 0xc000
	ds_read_b128 v[206:209], v192
	ds_read_b128 v[210:213], v192 offset:1024
	ds_read_b128 v[214:217], v192 offset:2048
	ds_read_b128 v[218:221], v192 offset:3072
	ds_read_b128 v[222:225], v192 offset:4096
	ds_read_b128 v[226:229], v192 offset:5120
	ds_read_b128 v[230:233], v192 offset:6144
	ds_read_b128 v[234:237], v192 offset:7168
	global_load_lds_dwordx4 v[170:171], off
	v_lshl_add_u64 v[170:171], s[0:1], 0, v[160:161]
	s_add_i32 m0, s31, 0xe000
	s_nop 0
	global_load_lds_dwordx4 v[170:171], off
	s_waitcnt vmcnt(8)
	s_waitcnt lgkmcnt(0)
	s_barrier
	s_waitcnt lgkmcnt(0)
	v_mfma_f32_16x16x32_bf16 v[124:127], v[128:131], v[206:209], v[124:127]
	v_mfma_f32_16x16x32_bf16 v[120:123], v[136:139], v[206:209], v[120:123]
	v_mfma_f32_16x16x32_bf16 v[108:111], v[128:131], v[214:217], v[108:111]
	v_mfma_f32_16x16x32_bf16 v[104:107], v[136:139], v[214:217], v[104:107]
	v_mfma_f32_16x16x32_bf16 v[92:95], v[128:131], v[222:225], v[92:95]
	v_mfma_f32_16x16x32_bf16 v[88:91], v[136:139], v[222:225], v[88:91]
	v_mfma_f32_16x16x32_bf16 v[76:79], v[128:131], v[230:233], v[76:79]
	v_mfma_f32_16x16x32_bf16 v[72:75], v[136:139], v[230:233], v[72:75]
	v_mfma_f32_16x16x32_bf16 v[124:127], v[132:135], v[210:213], v[124:127]
	v_mfma_f32_16x16x32_bf16 v[120:123], v[140:143], v[210:213], v[120:123]
	v_mfma_f32_16x16x32_bf16 v[108:111], v[132:135], v[218:221], v[108:111]
	v_mfma_f32_16x16x32_bf16 v[104:107], v[140:143], v[218:221], v[104:107]
	v_mfma_f32_16x16x32_bf16 v[92:95], v[132:135], v[226:229], v[92:95]
	v_mfma_f32_16x16x32_bf16 v[88:91], v[140:143], v[226:229], v[88:91]
	v_mfma_f32_16x16x32_bf16 v[76:79], v[132:135], v[234:237], v[76:79]
	v_mfma_f32_16x16x32_bf16 v[72:75], v[140:143], v[234:237], v[72:75]
	v_mfma_f32_16x16x32_bf16 v[116:119], v[166:169], v[206:209], v[116:119]
	v_mfma_f32_16x16x32_bf16 v[112:115], v[198:201], v[206:209], v[112:115]
	v_mfma_f32_16x16x32_bf16 v[100:103], v[166:169], v[214:217], v[100:103]
	v_mfma_f32_16x16x32_bf16 v[96:99], v[198:201], v[214:217], v[96:99]
	v_mfma_f32_16x16x32_bf16 v[84:87], v[166:169], v[222:225], v[84:87]
	v_mfma_f32_16x16x32_bf16 v[80:83], v[198:201], v[222:225], v[80:83]
	v_mfma_f32_16x16x32_bf16 v[68:71], v[166:169], v[230:233], v[68:71]
	v_mfma_f32_16x16x32_bf16 v[64:67], v[198:201], v[230:233], v[64:67]
	v_mfma_f32_16x16x32_bf16 v[116:119], v[194:197], v[210:213], v[116:119]
	v_mfma_f32_16x16x32_bf16 v[112:115], v[202:205], v[210:213], v[112:115]
	v_mfma_f32_16x16x32_bf16 v[100:103], v[194:197], v[218:221], v[100:103]
	v_mfma_f32_16x16x32_bf16 v[96:99], v[202:205], v[218:221], v[96:99]
	v_mfma_f32_16x16x32_bf16 v[84:87], v[194:197], v[226:229], v[84:87]
	v_mfma_f32_16x16x32_bf16 v[80:83], v[202:205], v[226:229], v[80:83]
	v_mfma_f32_16x16x32_bf16 v[68:71], v[194:197], v[234:237], v[68:71]
	v_mfma_f32_16x16x32_bf16 v[64:67], v[202:205], v[234:237], v[64:67]
	s_barrier
	s_add_i32 s60, s49, s41
	v_lshl_add_u64 v[170:171], s[34:35], 0, v[146:147]
	s_mov_b32 m0, s60
	ds_read_b128 v[206:209], v192 offset:16384
	ds_read_b128 v[210:213], v192 offset:17408
	ds_read_b128 v[214:217], v192 offset:18432
	ds_read_b128 v[218:221], v192 offset:19456
	ds_read_b128 v[222:225], v192 offset:20480
	ds_read_b128 v[226:229], v192 offset:21504
	ds_read_b128 v[230:233], v192 offset:22528
	ds_read_b128 v[234:237], v192 offset:23552
	global_load_lds_dwordx4 v[170:171], off
	s_add_i32 m0, s60, 0x2000
	s_add_u32 s60, s34, 0x40000
	v_lshl_add_u64 v[238:239], s[34:35], 0, v[150:151]
	s_addc_u32 s61, s35, 0
	s_add_i32 s62, s52, s41
	global_load_lds_dwordx4 v[238:239], off
	v_lshl_add_u64 v[240:241], s[60:61], 0, v[146:147]
	s_mov_b32 m0, s62
	v_lshl_add_u64 v[242:243], s[36:37], 0, v[148:149]
	global_load_lds_dwordx4 v[240:241], off
	v_lshl_add_u64 v[240:241], s[60:61], 0, v[150:151]
	s_add_i32 m0, s62, 0x2000
	s_nop 0
	global_load_lds_dwordx4 v[240:241], off
	v_lshl_add_u64 v[240:241], s[36:37], 0, v[144:145]
	s_mov_b32 m0, s31
	s_nop 0
	global_load_lds_dwordx4 v[240:241], off
	s_mov_b32 m0, s42
	s_nop 0
	global_load_lds_dwordx4 v[242:243], off
	s_waitcnt vmcnt(8)
	s_waitcnt lgkmcnt(0)
	s_barrier
; #define PG8_STAGE(bufoff, gbase, voff) do { _Pragma("unroll") for (int _i = 0; _i < 2; ++_i) \
;         __builtin_amdgcn_global_load_lds((const unsigned*)((const char*)(gbase) + (voff)[_i]), (PG8_LAS unsigned*)(lds + (bufoff) + ldsw + _i * 8192), 16, 0, 0); } while (0)
; #define PG8_LDA(dst, b, h) do { _Pragma("unroll") for (int m = 0; m < 4; ++m) _Pragma("unroll") for (int k = 0; k < 2; ++k) dst[m][k] = *(const PG8_LAS bf16x8*)(lds + PG8_SA(b, h) + aoff + m * 2048 + k * 1024); } while (0)
; #define PG8_LDB(dst, b, h) do { _Pragma("unroll") for (int n = 0; n < 2; ++n) _Pragma("unroll") for (int k = 0; k < 2; ++k) dst[n][k] = *(const PG8_LAS bf16x8*)(lds + PG8_SB(b, h) + boff + n * 2048 + k * 1024); } while (0)
; #define PG8_MMA(ai, bj, At, Bt) do { __builtin_amdgcn_s_setprio(1); _Pragma("unroll") for (int m = 0; m < 4; ++m) _Pragma("unroll") for (int n = 0; n < 2; ++n) _Pragma("unroll") for (int k = 0; k < 2; ++k) \
;         acc[ai][bj][m][n] = __builtin_amdgcn_mfma_f32_16x16x32_bf16(Bt[n][k], At[m][k], acc[ai][bj][m][n], 0, 0, 0); __builtin_amdgcn_s_setprio(0); } while (0)
; #define PG8_WAIT_V(n) asm volatile("s_waitcnt vmcnt(" #n ")" ::: "memory")
; #define PG8_WAIT_L(n) asm volatile("s_waitcnt lgkmcnt(" #n ")" ::: "memory")
; #define PG8_BAR __builtin_amdgcn_s_barrier()
; #define PG8_SCHED __builtin_amdgcn_sched_barrier(0)
; template <class Epi, class Sched, bool ALIGN_EPI = false, bool SP2 = false>
; __device__ __forceinline__ void gemm_phase(PG8_LAS unsigned char* lds, const Gemm g, const Sched& S, const Epi& E, const int tid_in) {
;     ...
;             PG8_WAIT_V(8); PG8_WAIT_L(0); PG8_BAR; PG8_MMA(1, 0, At, B0); PG8_MMA(1, 1, At, B1); PG8_BAR; PG8_SCHED;
;             PG8_LDB(B0, 1, 0); PG8_LDB(B1, 1, 1); PG8_SCHED; PG8_LDA(At, 1, 0); PG8_STAGE(PG8_SA(0, 1), a2 + hstep, voffA);
;             PG8_WAIT_V(8); PG8_WAIT_L(0); PG8_BAR; PG8_MMA(0, 0, At, B0); PG8_MMA(0, 1, At, B1); PG8_BAR; PG8_SCHED;
	s_waitcnt lgkmcnt(0)
	v_mfma_f32_16x16x32_bf16 v[60:63], v[128:131], v[206:209], v[60:63]
	v_mfma_f32_16x16x32_bf16 v[56:59], v[136:139], v[206:209], v[56:59]
	v_mfma_f32_16x16x32_bf16 v[44:47], v[128:131], v[214:217], v[44:47]
	v_mfma_f32_16x16x32_bf16 v[40:43], v[136:139], v[214:217], v[40:43]
	v_mfma_f32_16x16x32_bf16 v[28:31], v[128:131], v[222:225], v[28:31]
	v_mfma_f32_16x16x32_bf16 v[24:27], v[136:139], v[222:225], v[24:27]
	v_mfma_f32_16x16x32_bf16 v[12:15], v[128:131], v[230:233], v[12:15]
	v_mfma_f32_16x16x32_bf16 v[8:11], v[136:139], v[230:233], v[8:11]
	v_mfma_f32_16x16x32_bf16 v[60:63], v[132:135], v[210:213], v[60:63]
	v_mfma_f32_16x16x32_bf16 v[56:59], v[140:143], v[210:213], v[56:59]
	v_mfma_f32_16x16x32_bf16 v[44:47], v[132:135], v[218:221], v[44:47]
	v_mfma_f32_16x16x32_bf16 v[40:43], v[140:143], v[218:221], v[40:43]
	v_mfma_f32_16x16x32_bf16 v[28:31], v[132:135], v[226:229], v[28:31]
	v_mfma_f32_16x16x32_bf16 v[24:27], v[140:143], v[226:229], v[24:27]
	v_mfma_f32_16x16x32_bf16 v[12:15], v[132:135], v[234:237], v[12:15]
	v_mfma_f32_16x16x32_bf16 v[8:11], v[140:143], v[234:237], v[8:11]
	v_mfma_f32_16x16x32_bf16 v[52:55], v[166:169], v[206:209], v[52:55]
	v_mfma_f32_16x16x32_bf16 v[48:51], v[198:201], v[206:209], v[48:51]
	v_mfma_f32_16x16x32_bf16 v[36:39], v[166:169], v[214:217], v[36:39]
	v_mfma_f32_16x16x32_bf16 v[32:35], v[198:201], v[214:217], v[32:35]
	v_mfma_f32_16x16x32_bf16 v[20:23], v[166:169], v[222:225], v[20:23]
	v_mfma_f32_16x16x32_bf16 v[16:19], v[198:201], v[222:225], v[16:19]
	v_mfma_f32_16x16x32_bf16 v[4:7], v[166:169], v[230:233], v[4:7]
	v_mfma_f32_16x16x32_bf16 v[0:3], v[198:201], v[230:233], v[0:3]
	v_mfma_f32_16x16x32_bf16 v[52:55], v[194:197], v[210:213], v[52:55]
	v_mfma_f32_16x16x32_bf16 v[48:51], v[202:205], v[210:213], v[48:51]
	v_mfma_f32_16x16x32_bf16 v[36:39], v[194:197], v[218:221], v[36:39]
	v_mfma_f32_16x16x32_bf16 v[32:35], v[202:205], v[218:221], v[32:35]
	v_mfma_f32_16x16x32_bf16 v[20:23], v[194:197], v[226:229], v[20:23]
	v_mfma_f32_16x16x32_bf16 v[16:19], v[202:205], v[226:229], v[16:19]
	v_mfma_f32_16x16x32_bf16 v[4:7], v[194:197], v[234:237], v[4:7]
	v_mfma_f32_16x16x32_bf16 v[0:3], v[202:205], v[234:237], v[0:3]
	s_barrier
	s_add_i32 s60, 0, 0x18000
	s_add_i32 s61, 0, 0x1c000
	v_add_u32_e32 v140, s60, v188
	v_add_u32_e32 v152, s61, v188
	ds_read_b128 v[128:131], v140
	ds_read_b128 v[132:135], v140 offset:1024
	ds_read_b128 v[136:139], v140 offset:2048
	ds_read_b128 v[140:143], v140 offset:3072
	ds_read_b128 v[166:169], v152
	ds_read_b128 v[194:197], v152 offset:1024
	ds_read_b128 v[198:201], v152 offset:2048
	ds_read_b128 v[202:205], v152 offset:3072
	s_add_u32 s36, s36, 0x40000
	s_addc_u32 s37, s37, 0
	s_mov_b32 m0, s43
	v_lshl_add_u64 v[244:245], s[36:37], 0, v[144:145]
	ds_read_b128 v[206:209], v192 offset:32768
	ds_read_b128 v[210:213], v192 offset:33792
	ds_read_b128 v[214:217], v192 offset:34816
	ds_read_b128 v[218:221], v192 offset:35840
	ds_read_b128 v[222:225], v192 offset:36864
	ds_read_b128 v[226:229], v192 offset:37888
	ds_read_b128 v[230:233], v192 offset:38912
	ds_read_b128 v[234:237], v192 offset:39936
	global_load_lds_dwordx4 v[244:245], off
	v_lshl_add_u64 v[244:245], s[36:37], 0, v[148:149]
	s_mov_b32 m0, s44
	s_nop 0
	global_load_lds_dwordx4 v[244:245], off
	s_waitcnt vmcnt(8)
	s_waitcnt lgkmcnt(0)
	s_barrier
	s_waitcnt lgkmcnt(0)
	v_mfma_f32_16x16x32_bf16 v[124:127], v[128:131], v[206:209], v[124:127]
	v_mfma_f32_16x16x32_bf16 v[120:123], v[136:139], v[206:209], v[120:123]
	v_mfma_f32_16x16x32_bf16 v[108:111], v[128:131], v[214:217], v[108:111]
	v_mfma_f32_16x16x32_bf16 v[104:107], v[136:139], v[214:217], v[104:107]
	v_mfma_f32_16x16x32_bf16 v[92:95], v[128:131], v[222:225], v[92:95]
	v_mfma_f32_16x16x32_bf16 v[88:91], v[136:139], v[222:225], v[88:91]
	v_mfma_f32_16x16x32_bf16 v[76:79], v[128:131], v[230:233], v[76:79]
	v_mfma_f32_16x16x32_bf16 v[72:75], v[136:139], v[230:233], v[72:75]
	v_mfma_f32_16x16x32_bf16 v[124:127], v[132:135], v[210:213], v[124:127]
	v_mfma_f32_16x16x32_bf16 v[120:123], v[140:143], v[210:213], v[120:123]
	v_mfma_f32_16x16x32_bf16 v[108:111], v[132:135], v[218:221], v[108:111]
	v_mfma_f32_16x16x32_bf16 v[104:107], v[140:143], v[218:221], v[104:107]
	v_mfma_f32_16x16x32_bf16 v[92:95], v[132:135], v[226:229], v[92:95]
	v_mfma_f32_16x16x32_bf16 v[88:91], v[140:143], v[226:229], v[88:91]
	v_mfma_f32_16x16x32_bf16 v[76:79], v[132:135], v[234:237], v[76:79]
	v_mfma_f32_16x16x32_bf16 v[72:75], v[140:143], v[234:237], v[72:75]
	v_mfma_f32_16x16x32_bf16 v[116:119], v[166:169], v[206:209], v[116:119]
	v_mfma_f32_16x16x32_bf16 v[112:115], v[198:201], v[206:209], v[112:115]
	v_mfma_f32_16x16x32_bf16 v[100:103], v[166:169], v[214:217], v[100:103]
	v_mfma_f32_16x16x32_bf16 v[96:99], v[198:201], v[214:217], v[96:99]
	v_mfma_f32_16x16x32_bf16 v[84:87], v[166:169], v[222:225], v[84:87]
	v_mfma_f32_16x16x32_bf16 v[80:83], v[198:201], v[222:225], v[80:83]
	v_mfma_f32_16x16x32_bf16 v[68:71], v[166:169], v[230:233], v[68:71]
	v_mfma_f32_16x16x32_bf16 v[64:67], v[198:201], v[230:233], v[64:67]
	v_mfma_f32_16x16x32_bf16 v[116:119], v[194:197], v[210:213], v[116:119]
	v_mfma_f32_16x16x32_bf16 v[112:115], v[202:205], v[210:213], v[112:115]
	v_mfma_f32_16x16x32_bf16 v[100:103], v[194:197], v[218:221], v[100:103]
	v_mfma_f32_16x16x32_bf16 v[96:99], v[202:205], v[218:221], v[96:99]
	v_mfma_f32_16x16x32_bf16 v[84:87], v[194:197], v[226:229], v[84:87]
	v_mfma_f32_16x16x32_bf16 v[80:83], v[202:205], v[226:229], v[80:83]
	v_mfma_f32_16x16x32_bf16 v[68:71], v[194:197], v[234:237], v[68:71]
	v_mfma_f32_16x16x32_bf16 v[64:67], v[202:205], v[234:237], v[64:67]
	s_barrier
; #define PG8_STAGE(bufoff, gbase, voff) do { _Pragma("unroll") for (int _i = 0; _i < 2; ++_i) \
;         __builtin_amdgcn_global_load_lds((const unsigned*)((const char*)(gbase) + (voff)[_i]), (PG8_LAS unsigned*)(lds + (bufoff) + ldsw + _i * 8192), 16, 0, 0); } while (0)
; #define PG8_LDA(dst, b, h) do { _Pragma("unroll") for (int m = 0; m < 4; ++m) _Pragma("unroll") for (int k = 0; k < 2; ++k) dst[m][k] = *(const PG8_LAS bf16x8*)(lds + PG8_SA(b, h) + aoff + m * 2048 + k * 1024); } while (0)
; #define PG8_MMA(ai, bj, At, Bt) do { __builtin_amdgcn_s_setprio(1); _Pragma("unroll") for (int m = 0; m < 4; ++m) _Pragma("unroll") for (int n = 0; n < 2; ++n) _Pragma("unroll") for (int k = 0; k < 2; ++k) \
;         acc[ai][bj][m][n] = __builtin_amdgcn_mfma_f32_16x16x32_bf16(Bt[n][k], At[m][k], acc[ai][bj][m][n], 0, 0, 0); __builtin_amdgcn_s_setprio(0); } while (0)
; #define PG8_WAIT_V(n) asm volatile("s_waitcnt vmcnt(" #n ")" ::: "memory")
; #define PG8_WAIT_L(n) asm volatile("s_waitcnt lgkmcnt(" #n ")" ::: "memory")
; #define PG8_BAR __builtin_amdgcn_s_barrier()
; #define PG8_SCHED __builtin_amdgcn_sched_barrier(0)
; template <class Epi, class Sched, bool ALIGN_EPI = false, bool SP2 = false>
; __device__ __forceinline__ void gemm_phase(PG8_LAS unsigned char* lds, const Gemm g, const Sched& S, const Epi& E, const int tid_in) {
;     ...
;         for (int t = 0; t < nt; t += 2) {
;             const bool last = (t == nt - 2);
;             const char* a1 = cA + (size_t)(t + 1) * kstep;
;             const char* a2 = last ? nA : cA + (size_t)(t + 2) * kstep; const char* b2 = last ? nB : cB + (size_t)(t + 2) * kstep;
;     ...
;             PG8_LDA(At, 1, 1); PG8_STAGE(PG8_SB(1, 0), b3, voffB); PG8_STAGE(PG8_SB(1, 1), b3 + hstep, voffB); PG8_STAGE(PG8_SA(1, 0), a3, voffA);
;             PG8_WAIT_V(8); PG8_WAIT_L(0); PG8_BAR; PG8_MMA(1, 0, At, B0); PG8_MMA(1, 1, At, B1); PG8_BAR; PG8_SCHED;
	s_add_i32 s36, s60, s41
	v_lshl_add_u64 v[170:171], v[170:171], 0, s[18:19]
	s_mov_b32 m0, s36
	ds_read_b128 v[206:209], v192 offset:49152
	ds_read_b128 v[210:213], v192 offset:50176
	ds_read_b128 v[214:217], v192 offset:51200
	ds_read_b128 v[218:221], v192 offset:52224
	ds_read_b128 v[222:225], v192 offset:53248
	ds_read_b128 v[226:229], v192 offset:54272
	ds_read_b128 v[230:233], v192 offset:55296
	ds_read_b128 v[234:237], v192 offset:56320
	global_load_lds_dwordx4 v[170:171], off
	s_add_i32 m0, s36, 0x2000
	s_add_u32 s34, s34, 0x40080
	v_lshl_add_u64 v[170:171], v[238:239], 0, s[18:19]
	s_addc_u32 s35, s35, 0
	s_add_i32 s36, s61, s41
	global_load_lds_dwordx4 v[170:171], off
	v_lshl_add_u64 v[170:171], s[34:35], 0, v[146:147]
	s_mov_b32 m0, s36
	s_nop 0
	global_load_lds_dwordx4 v[170:171], off
	v_lshl_add_u64 v[170:171], s[34:35], 0, v[150:151]
	s_add_i32 m0, s36, 0x2000
	s_nop 0
	global_load_lds_dwordx4 v[170:171], off
	v_lshl_add_u64 v[170:171], v[240:241], 0, s[18:19]
	s_mov_b32 m0, s46
	s_nop 0
	global_load_lds_dwordx4 v[170:171], off
	v_lshl_add_u64 v[170:171], v[242:243], 0, s[18:19]
	s_mov_b32 m0, s47
	s_nop 0
	global_load_lds_dwordx4 v[170:171], off
	s_waitcnt vmcnt(8)
	s_waitcnt lgkmcnt(0)
	s_barrier
	s_waitcnt lgkmcnt(0)
	v_mfma_f32_16x16x32_bf16 v[60:63], v[128:131], v[206:209], v[60:63]
	v_mfma_f32_16x16x32_bf16 v[56:59], v[136:139], v[206:209], v[56:59]
	v_mfma_f32_16x16x32_bf16 v[44:47], v[128:131], v[214:217], v[44:47]
	v_mfma_f32_16x16x32_bf16 v[40:43], v[136:139], v[214:217], v[40:43]
	v_mfma_f32_16x16x32_bf16 v[28:31], v[128:131], v[222:225], v[28:31]
	v_mfma_f32_16x16x32_bf16 v[24:27], v[136:139], v[222:225], v[24:27]
	v_mfma_f32_16x16x32_bf16 v[12:15], v[128:131], v[230:233], v[12:15]
	v_mfma_f32_16x16x32_bf16 v[8:11], v[136:139], v[230:233], v[8:11]
	v_mfma_f32_16x16x32_bf16 v[60:63], v[132:135], v[210:213], v[60:63]
	v_mfma_f32_16x16x32_bf16 v[56:59], v[140:143], v[210:213], v[56:59]
	v_mfma_f32_16x16x32_bf16 v[44:47], v[132:135], v[218:221], v[44:47]
	v_mfma_f32_16x16x32_bf16 v[40:43], v[140:143], v[218:221], v[40:43]
	v_mfma_f32_16x16x32_bf16 v[28:31], v[132:135], v[226:229], v[28:31]
	v_mfma_f32_16x16x32_bf16 v[24:27], v[140:143], v[226:229], v[24:27]
	v_mfma_f32_16x16x32_bf16 v[12:15], v[132:135], v[234:237], v[12:15]
	v_mfma_f32_16x16x32_bf16 v[8:11], v[140:143], v[234:237], v[8:11]
	v_mfma_f32_16x16x32_bf16 v[52:55], v[166:169], v[206:209], v[52:55]
	v_mfma_f32_16x16x32_bf16 v[48:51], v[198:201], v[206:209], v[48:51]
	v_mfma_f32_16x16x32_bf16 v[36:39], v[166:169], v[214:217], v[36:39]
	v_mfma_f32_16x16x32_bf16 v[32:35], v[198:201], v[214:217], v[32:35]
	v_mfma_f32_16x16x32_bf16 v[20:23], v[166:169], v[222:225], v[20:23]
	v_mfma_f32_16x16x32_bf16 v[16:19], v[198:201], v[222:225], v[16:19]
	v_mfma_f32_16x16x32_bf16 v[4:7], v[166:169], v[230:233], v[4:7]
	v_mfma_f32_16x16x32_bf16 v[0:3], v[198:201], v[230:233], v[0:3]
	v_mfma_f32_16x16x32_bf16 v[52:55], v[194:197], v[210:213], v[52:55]
	v_mfma_f32_16x16x32_bf16 v[48:51], v[202:205], v[210:213], v[48:51]
	v_mfma_f32_16x16x32_bf16 v[36:39], v[194:197], v[218:221], v[36:39]
	v_mfma_f32_16x16x32_bf16 v[32:35], v[202:205], v[218:221], v[32:35]
	v_mfma_f32_16x16x32_bf16 v[20:23], v[194:197], v[226:229], v[20:23]
	v_mfma_f32_16x16x32_bf16 v[16:19], v[202:205], v[226:229], v[16:19]
	v_mfma_f32_16x16x32_bf16 v[4:7], v[194:197], v[234:237], v[4:7]
	v_mfma_f32_16x16x32_bf16 v[0:3], v[202:205], v[234:237], v[0:3]
	s_add_i32 s59, s59, 2
	s_add_u32 s0, s0, 0x100
	s_addc_u32 s1, s1, 0
	s_add_u32 s57, s57, 0x100
	s_addc_u32 s58, s58, 0
	s_cmp_gt_u32 s59, 13
	s_barrier
	s_cbranch_scc0 .LBB0_127
	s_and_b64 vcc, exec, s[20:21]
	s_cbranch_vccz .LBB0_130
	s_barrier

; #define PG8_STAGE(bufoff, gbase, voff) do { _Pragma("unroll") for (int _i = 0; _i < 2; ++_i) \
;         __builtin_amdgcn_global_load_lds((const unsigned*)((const char*)(gbase) + (voff)[_i]), (PG8_LAS unsigned*)(lds + (bufoff) + ldsw + _i * 8192), 16, 0, 0); } while (0)
; #define PG8_LDA(dst, b, h) do { _Pragma("unroll") for (int m = 0; m < 4; ++m) _Pragma("unroll") for (int k = 0; k < 2; ++k) dst[m][k] = *(const PG8_LAS bf16x8*)(lds + PG8_SA(b, h) + aoff + m * 2048 + k * 1024); } while (0)
; #define PG8_LDB(dst, b, h) do { _Pragma("unroll") for (int n = 0; n < 2; ++n) _Pragma("unroll") for (int k = 0; k < 2; ++k) dst[n][k] = *(const PG8_LAS bf16x8*)(lds + PG8_SB(b, h) + boff + n * 2048 + k * 1024); } while (0)
; #define PG8_MMA(ai, bj, At, Bt) do { __builtin_amdgcn_s_setprio(1); _Pragma("unroll") for (int m = 0; m < 4; ++m) _Pragma("unroll") for (int n = 0; n < 2; ++n) _Pragma("unroll") for (int k = 0; k < 2; ++k) \
;         acc[ai][bj][m][n] = __builtin_amdgcn_mfma_f32_16x16x32_bf16(Bt[n][k], At[m][k], acc[ai][bj][m][n], 0, 0, 0); __builtin_amdgcn_s_setprio(0); } while (0)
; #define PG8_WAIT_V(n) asm volatile("s_waitcnt vmcnt(" #n ")" ::: "memory")
; #define PG8_WAIT_L(n) asm volatile("s_waitcnt lgkmcnt(" #n ")" ::: "memory")
;     __device__ __forceinline__ void operator()(const f32x4 (&acc)[2][2][4][2], const Unit& u, int wr, int wc, int fr, int fq) const {
;     ...
;                     else { b0 = *(const f32x4*)((const float*)base + off + bj * HALF); b1 = *(const f32x4*)((const float*)base + off + bj * HALF + 4); }
; template <class Epi, class Sched, bool ALIGN_EPI = false, bool SP2 = false>
; __device__ __forceinline__ void gemm_phase(PG8_LAS unsigned char* lds, const Gemm g, const Sched& S, const Epi& E, const int tid_in) {
;     ...
;             PG8_WAIT_V(8); PG8_WAIT_L(0); PG8_BAR; PG8_MMA(0, 0, At, B0); PG8_MMA(0, 1, At, B1); PG8_BAR; PG8_SCHED;
;             PG8_LDA(At, 0, 1); PG8_STAGE(PG8_SB(0, 0), b2, voffB); PG8_STAGE(PG8_SB(0, 1), b2 + hstep, voffB); PG8_STAGE(PG8_SA(0, 0), a2, voffA);
;             PG8_WAIT_V(8); PG8_WAIT_L(0); PG8_BAR; PG8_MMA(1, 0, At, B0); PG8_MMA(1, 1, At, B1); PG8_BAR; PG8_SCHED;
;             PG8_LDB(B0, 1, 0); PG8_LDB(B1, 1, 1); PG8_SCHED; PG8_LDA(At, 1, 0); PG8_STAGE(PG8_SA(0, 1), a2 + hstep, voffA);
;             PG8_WAIT_V(8); PG8_WAIT_L(0); PG8_BAR; PG8_MMA(0, 0, At, B0); PG8_MMA(0, 1, At, B1); PG8_BAR; PG8_SCHED;
.Lmy_ra_done:
	s_barrier
	s_waitcnt lgkmcnt(0)
	v_mfma_f32_16x16x32_bf16 v[124:127], v[144:147], v[184:187], v[124:127]
	v_mfma_f32_16x16x32_bf16 v[120:123], v[160:163], v[184:187], v[120:123]
	v_mfma_f32_16x16x32_bf16 v[108:111], v[144:147], v[192:195], v[108:111]
	v_mfma_f32_16x16x32_bf16 v[104:107], v[160:163], v[192:195], v[104:107]
	v_mfma_f32_16x16x32_bf16 v[92:95], v[144:147], v[200:203], v[92:95]
	v_mfma_f32_16x16x32_bf16 v[88:91], v[160:163], v[200:203], v[88:91]
	v_mfma_f32_16x16x32_bf16 v[76:79], v[144:147], v[208:211], v[76:79]
	v_mfma_f32_16x16x32_bf16 v[72:75], v[160:163], v[208:211], v[72:75]
	v_mfma_f32_16x16x32_bf16 v[124:127], v[156:159], v[188:191], v[124:127]
	v_mfma_f32_16x16x32_bf16 v[120:123], v[164:167], v[188:191], v[120:123]
	v_mfma_f32_16x16x32_bf16 v[108:111], v[156:159], v[196:199], v[108:111]
	v_mfma_f32_16x16x32_bf16 v[104:107], v[164:167], v[196:199], v[104:107]
	v_mfma_f32_16x16x32_bf16 v[92:95], v[156:159], v[204:207], v[92:95]
	v_mfma_f32_16x16x32_bf16 v[88:91], v[164:167], v[204:207], v[88:91]
	v_mfma_f32_16x16x32_bf16 v[76:79], v[156:159], v[212:215], v[76:79]
	v_mfma_f32_16x16x32_bf16 v[72:75], v[164:167], v[212:215], v[72:75]
	v_mfma_f32_16x16x32_bf16 v[116:119], v[168:171], v[184:187], v[116:119]
	v_mfma_f32_16x16x32_bf16 v[112:115], v[176:179], v[184:187], v[112:115]
	v_mfma_f32_16x16x32_bf16 v[100:103], v[168:171], v[192:195], v[100:103]
	v_mfma_f32_16x16x32_bf16 v[96:99], v[176:179], v[192:195], v[96:99]
	v_mfma_f32_16x16x32_bf16 v[84:87], v[168:171], v[200:203], v[84:87]
	v_mfma_f32_16x16x32_bf16 v[80:83], v[176:179], v[200:203], v[80:83]
	v_mfma_f32_16x16x32_bf16 v[68:71], v[168:171], v[208:211], v[68:71]
	v_mfma_f32_16x16x32_bf16 v[64:67], v[176:179], v[208:211], v[64:67]
	v_mfma_f32_16x16x32_bf16 v[116:119], v[172:175], v[188:191], v[116:119]
	v_mfma_f32_16x16x32_bf16 v[112:115], v[180:183], v[188:191], v[112:115]
	v_mfma_f32_16x16x32_bf16 v[100:103], v[172:175], v[196:199], v[100:103]
	v_mfma_f32_16x16x32_bf16 v[96:99], v[180:183], v[196:199], v[96:99]
	v_mfma_f32_16x16x32_bf16 v[84:87], v[172:175], v[204:207], v[84:87]
	v_mfma_f32_16x16x32_bf16 v[80:83], v[180:183], v[204:207], v[80:83]
	v_mfma_f32_16x16x32_bf16 v[68:71], v[172:175], v[212:215], v[68:71]
	v_mfma_f32_16x16x32_bf16 v[64:67], v[180:183], v[212:215], v[64:67]
	s_barrier
	s_add_i32 s63, s53, s43
	v_lshl_add_u64 v[148:149], s[36:37], 0, v[132:133]
	s_mov_b32 m0, s63
	ds_read_b128 v[184:187], v155 offset:16384
	ds_read_b128 v[188:191], v155 offset:17408
	ds_read_b128 v[192:195], v155 offset:18432
	ds_read_b128 v[196:199], v155 offset:19456
	ds_read_b128 v[200:203], v155 offset:20480
	ds_read_b128 v[204:207], v155 offset:21504
	ds_read_b128 v[208:211], v155 offset:22528
	ds_read_b128 v[212:215], v155 offset:23552
	global_load_lds_dwordx4 v[148:149], off
	s_add_i32 m0, s63, 0x2000
	s_add_u32 s64, s36, 0x40000
	v_lshl_add_u64 v[216:217], s[36:37], 0, v[128:129]
	s_addc_u32 s65, s37, 0
	s_add_i32 s63, s56, s43
	global_load_lds_dwordx4 v[216:217], off
	v_lshl_add_u64 v[218:219], s[64:65], 0, v[132:133]
	s_mov_b32 m0, s63
	v_lshl_add_u64 v[220:221], s[38:39], 0, v[130:131]
	global_load_lds_dwordx4 v[218:219], off
	v_lshl_add_u64 v[218:219], s[64:65], 0, v[128:129]
	s_add_i32 m0, s63, 0x2000
	s_nop 0
	global_load_lds_dwordx4 v[218:219], off
	v_lshl_add_u64 v[218:219], s[38:39], 0, v[134:135]
	s_mov_b32 m0, s35
	s_nop 0
	global_load_lds_dwordx4 v[218:219], off
	s_mov_b32 m0, s45
	s_nop 0
	global_load_lds_dwordx4 v[220:221], off
	s_waitcnt vmcnt(8)
	s_waitcnt lgkmcnt(0)
	global_load_dwordx4 v[228:231], v[224:225], off
	global_load_dwordx4 v[232:235], v[224:225], off offset:16
	global_load_dwordx4 v[236:239], v[224:225], off offset:512
	global_load_dwordx4 v[240:243], v[224:225], off offset:528
	s_mov_b32 s98, 0x10000
	s_cmp_eq_u32 s62, 4
	s_cselect_b32 s98, 0x50000, s98
	v_add_co_u32_e32 v224, vcc, s98, v224
	s_nop 1
	v_addc_co_u32_e32 v225, vcc, 0, v225, vcc
	s_barrier
	s_waitcnt lgkmcnt(0)
	v_mfma_f32_16x16x32_bf16 v[60:63], v[144:147], v[184:187], v[60:63]
	v_mfma_f32_16x16x32_bf16 v[56:59], v[160:163], v[184:187], v[56:59]
	v_mfma_f32_16x16x32_bf16 v[44:47], v[144:147], v[192:195], v[44:47]
	v_mfma_f32_16x16x32_bf16 v[40:43], v[160:163], v[192:195], v[40:43]
	v_mfma_f32_16x16x32_bf16 v[28:31], v[144:147], v[200:203], v[28:31]
	v_mfma_f32_16x16x32_bf16 v[24:27], v[160:163], v[200:203], v[24:27]
	v_mfma_f32_16x16x32_bf16 v[12:15], v[144:147], v[208:211], v[12:15]
	v_mfma_f32_16x16x32_bf16 v[8:11], v[160:163], v[208:211], v[8:11]
	v_mfma_f32_16x16x32_bf16 v[60:63], v[156:159], v[188:191], v[60:63]
	v_mfma_f32_16x16x32_bf16 v[56:59], v[164:167], v[188:191], v[56:59]
	v_mfma_f32_16x16x32_bf16 v[44:47], v[156:159], v[196:199], v[44:47]
	v_mfma_f32_16x16x32_bf16 v[40:43], v[164:167], v[196:199], v[40:43]
	v_mfma_f32_16x16x32_bf16 v[28:31], v[156:159], v[204:207], v[28:31]
	v_mfma_f32_16x16x32_bf16 v[24:27], v[164:167], v[204:207], v[24:27]
	v_mfma_f32_16x16x32_bf16 v[12:15], v[156:159], v[212:215], v[12:15]
	v_mfma_f32_16x16x32_bf16 v[8:11], v[164:167], v[212:215], v[8:11]
	v_mfma_f32_16x16x32_bf16 v[52:55], v[168:171], v[184:187], v[52:55]
	v_mfma_f32_16x16x32_bf16 v[48:51], v[176:179], v[184:187], v[48:51]
	v_mfma_f32_16x16x32_bf16 v[36:39], v[168:171], v[192:195], v[36:39]
	v_mfma_f32_16x16x32_bf16 v[32:35], v[176:179], v[192:195], v[32:35]
	v_mfma_f32_16x16x32_bf16 v[20:23], v[168:171], v[200:203], v[20:23]
	v_mfma_f32_16x16x32_bf16 v[16:19], v[176:179], v[200:203], v[16:19]
	v_mfma_f32_16x16x32_bf16 v[4:7], v[168:171], v[208:211], v[4:7]
	v_mfma_f32_16x16x32_bf16 v[0:3], v[176:179], v[208:211], v[0:3]
	v_mfma_f32_16x16x32_bf16 v[52:55], v[172:175], v[188:191], v[52:55]
	v_mfma_f32_16x16x32_bf16 v[48:51], v[180:183], v[188:191], v[48:51]
	v_mfma_f32_16x16x32_bf16 v[36:39], v[172:175], v[196:199], v[36:39]
	v_mfma_f32_16x16x32_bf16 v[32:35], v[180:183], v[196:199], v[32:35]
	v_mfma_f32_16x16x32_bf16 v[20:23], v[172:175], v[204:207], v[20:23]
	v_mfma_f32_16x16x32_bf16 v[16:19], v[180:183], v[204:207], v[16:19]
	v_mfma_f32_16x16x32_bf16 v[4:7], v[172:175], v[212:215], v[4:7]
	v_mfma_f32_16x16x32_bf16 v[0:3], v[180:183], v[212:215], v[0:3]
	s_barrier
; #define PG8_STAGE(bufoff, gbase, voff) do { _Pragma("unroll") for (int _i = 0; _i < 2; ++_i) \
;         __builtin_amdgcn_global_load_lds((const unsigned*)((const char*)(gbase) + (voff)[_i]), (PG8_LAS unsigned*)(lds + (bufoff) + ldsw + _i * 8192), 16, 0, 0); } while (0)
; #define PG8_LDA(dst, b, h) do { _Pragma("unroll") for (int m = 0; m < 4; ++m) _Pragma("unroll") for (int k = 0; k < 2; ++k) dst[m][k] = *(const PG8_LAS bf16x8*)(lds + PG8_SA(b, h) + aoff + m * 2048 + k * 1024); } while (0)
; #define PG8_LDB(dst, b, h) do { _Pragma("unroll") for (int n = 0; n < 2; ++n) _Pragma("unroll") for (int k = 0; k < 2; ++k) dst[n][k] = *(const PG8_LAS bf16x8*)(lds + PG8_SB(b, h) + boff + n * 2048 + k * 1024); } while (0)
; #define PG8_MMA(ai, bj, At, Bt) do { __builtin_amdgcn_s_setprio(1); _Pragma("unroll") for (int m = 0; m < 4; ++m) _Pragma("unroll") for (int n = 0; n < 2; ++n) _Pragma("unroll") for (int k = 0; k < 2; ++k) \
;         acc[ai][bj][m][n] = __builtin_amdgcn_mfma_f32_16x16x32_bf16(Bt[n][k], At[m][k], acc[ai][bj][m][n], 0, 0, 0); __builtin_amdgcn_s_setprio(0); } while (0)
; #define PG8_WAIT_V(n) asm volatile("s_waitcnt vmcnt(" #n ")" ::: "memory")
; #define PG8_WAIT_L(n) asm volatile("s_waitcnt lgkmcnt(" #n ")" ::: "memory")
; #define PG8_BAR __builtin_amdgcn_s_barrier()
; #define PG8_SCHED __builtin_amdgcn_sched_barrier(0)
; template <class Epi, class Sched, bool ALIGN_EPI = false, bool SP2 = false>
; __device__ __forceinline__ void gemm_phase(PG8_LAS unsigned char* lds, const Gemm g, const Sched& S, const Epi& E, const int tid_in) {
;     ...
;             PG8_WAIT_V(8); PG8_WAIT_L(0); PG8_BAR; PG8_MMA(1, 0, At, B0); PG8_MMA(1, 1, At, B1); PG8_BAR; PG8_SCHED;
;             PG8_LDB(B0, 1, 0); PG8_LDB(B1, 1, 1); PG8_SCHED; PG8_LDA(At, 1, 0); PG8_STAGE(PG8_SA(0, 1), a2 + hstep, voffA);
;             PG8_WAIT_V(8); PG8_WAIT_L(0); PG8_BAR; PG8_MMA(0, 0, At, B0); PG8_MMA(0, 1, At, B1); PG8_BAR; PG8_SCHED;
	s_add_i32 s63, 0, 0x18000
	s_add_i32 s64, 0, 0x1c000
	v_add_u32_e32 v164, s63, v151
	v_add_u32_e32 v180, s64, v151
	ds_read_b128 v[144:147], v164
	ds_read_b128 v[156:159], v164 offset:1024
	ds_read_b128 v[160:163], v164 offset:2048
	ds_read_b128 v[164:167], v164 offset:3072
	ds_read_b128 v[168:171], v180
	ds_read_b128 v[172:175], v180 offset:1024
	ds_read_b128 v[176:179], v180 offset:2048
	ds_read_b128 v[180:183], v180 offset:3072
	s_add_u32 s38, s38, 0x40000
	s_addc_u32 s39, s39, 0
	s_mov_b32 m0, s46
	v_lshl_add_u64 v[222:223], s[38:39], 0, v[134:135]
	ds_read_b128 v[184:187], v155 offset:32768
	ds_read_b128 v[188:191], v155 offset:33792
	ds_read_b128 v[192:195], v155 offset:34816
	ds_read_b128 v[196:199], v155 offset:35840
	ds_read_b128 v[200:203], v155 offset:36864
	ds_read_b128 v[204:207], v155 offset:37888
	ds_read_b128 v[208:211], v155 offset:38912
	ds_read_b128 v[212:215], v155 offset:39936
	global_load_lds_dwordx4 v[222:223], off
	v_lshl_add_u64 v[222:223], s[38:39], 0, v[130:131]
	s_mov_b32 m0, s47
	s_nop 0
	global_load_lds_dwordx4 v[222:223], off
	s_waitcnt vmcnt(12)
	s_waitcnt lgkmcnt(0)
	s_barrier
	s_waitcnt lgkmcnt(0)
	v_mfma_f32_16x16x32_bf16 v[124:127], v[144:147], v[184:187], v[124:127]
	v_mfma_f32_16x16x32_bf16 v[120:123], v[160:163], v[184:187], v[120:123]
	v_mfma_f32_16x16x32_bf16 v[108:111], v[144:147], v[192:195], v[108:111]
	v_mfma_f32_16x16x32_bf16 v[104:107], v[160:163], v[192:195], v[104:107]
	v_mfma_f32_16x16x32_bf16 v[92:95], v[144:147], v[200:203], v[92:95]
	v_mfma_f32_16x16x32_bf16 v[88:91], v[160:163], v[200:203], v[88:91]
	v_mfma_f32_16x16x32_bf16 v[76:79], v[144:147], v[208:211], v[76:79]
	v_mfma_f32_16x16x32_bf16 v[72:75], v[160:163], v[208:211], v[72:75]
	v_mfma_f32_16x16x32_bf16 v[124:127], v[156:159], v[188:191], v[124:127]
	v_mfma_f32_16x16x32_bf16 v[120:123], v[164:167], v[188:191], v[120:123]
	v_mfma_f32_16x16x32_bf16 v[108:111], v[156:159], v[196:199], v[108:111]
	v_mfma_f32_16x16x32_bf16 v[104:107], v[164:167], v[196:199], v[104:107]
	v_mfma_f32_16x16x32_bf16 v[92:95], v[156:159], v[204:207], v[92:95]
	v_mfma_f32_16x16x32_bf16 v[88:91], v[164:167], v[204:207], v[88:91]
	v_mfma_f32_16x16x32_bf16 v[76:79], v[156:159], v[212:215], v[76:79]
	v_mfma_f32_16x16x32_bf16 v[72:75], v[164:167], v[212:215], v[72:75]
	v_mfma_f32_16x16x32_bf16 v[116:119], v[168:171], v[184:187], v[116:119]
	v_mfma_f32_16x16x32_bf16 v[112:115], v[176:179], v[184:187], v[112:115]
	v_mfma_f32_16x16x32_bf16 v[100:103], v[168:171], v[192:195], v[100:103]
	v_mfma_f32_16x16x32_bf16 v[96:99], v[176:179], v[192:195], v[96:99]
	v_mfma_f32_16x16x32_bf16 v[84:87], v[168:171], v[200:203], v[84:87]
	v_mfma_f32_16x16x32_bf16 v[80:83], v[176:179], v[200:203], v[80:83]
	v_mfma_f32_16x16x32_bf16 v[68:71], v[168:171], v[208:211], v[68:71]
	v_mfma_f32_16x16x32_bf16 v[64:67], v[176:179], v[208:211], v[64:67]
	v_mfma_f32_16x16x32_bf16 v[116:119], v[172:175], v[188:191], v[116:119]
	v_mfma_f32_16x16x32_bf16 v[112:115], v[180:183], v[188:191], v[112:115]
	v_mfma_f32_16x16x32_bf16 v[100:103], v[172:175], v[196:199], v[100:103]
	v_mfma_f32_16x16x32_bf16 v[96:99], v[180:183], v[196:199], v[96:99]
	v_mfma_f32_16x16x32_bf16 v[84:87], v[172:175], v[204:207], v[84:87]
	v_mfma_f32_16x16x32_bf16 v[80:83], v[180:183], v[204:207], v[80:83]
	v_mfma_f32_16x16x32_bf16 v[68:71], v[172:175], v[212:215], v[68:71]
	v_mfma_f32_16x16x32_bf16 v[64:67], v[180:183], v[212:215], v[64:67]
	s_barrier
; #define PG8_STAGE(bufoff, gbase, voff) do { _Pragma("unroll") for (int _i = 0; _i < 2; ++_i) \
;         __builtin_amdgcn_global_load_lds((const unsigned*)((const char*)(gbase) + (voff)[_i]), (PG8_LAS unsigned*)(lds + (bufoff) + ldsw + _i * 8192), 16, 0, 0); } while (0)
; #define PG8_LDA(dst, b, h) do { _Pragma("unroll") for (int m = 0; m < 4; ++m) _Pragma("unroll") for (int k = 0; k < 2; ++k) dst[m][k] = *(const PG8_LAS bf16x8*)(lds + PG8_SA(b, h) + aoff + m * 2048 + k * 1024); } while (0)
; #define PG8_MMA(ai, bj, At, Bt) do { __builtin_amdgcn_s_setprio(1); _Pragma("unroll") for (int m = 0; m < 4; ++m) _Pragma("unroll") for (int n = 0; n < 2; ++n) _Pragma("unroll") for (int k = 0; k < 2; ++k) \
;         acc[ai][bj][m][n] = __builtin_amdgcn_mfma_f32_16x16x32_bf16(Bt[n][k], At[m][k], acc[ai][bj][m][n], 0, 0, 0); __builtin_amdgcn_s_setprio(0); } while (0)
; #define PG8_WAIT_V(n) asm volatile("s_waitcnt vmcnt(" #n ")" ::: "memory")
; #define PG8_WAIT_L(n) asm volatile("s_waitcnt lgkmcnt(" #n ")" ::: "memory")
; #define PG8_BAR __builtin_amdgcn_s_barrier()
; #define PG8_SCHED __builtin_amdgcn_sched_barrier(0)
; template <class Epi, class Sched, bool ALIGN_EPI = false, bool SP2 = false>
; __device__ __forceinline__ void gemm_phase(PG8_LAS unsigned char* lds, const Gemm g, const Sched& S, const Epi& E, const int tid_in) {
;     ...
;         for (int t = 0; t < nt; t += 2) {
;             const bool last = (t == nt - 2);
;             const char* a1 = cA + (size_t)(t + 1) * kstep;
;             const char* a2 = last ? nA : cA + (size_t)(t + 2) * kstep; const char* b2 = last ? nB : cB + (size_t)(t + 2) * kstep;
;     ...
;             PG8_LDA(At, 1, 1); PG8_STAGE(PG8_SB(1, 0), b3, voffB); PG8_STAGE(PG8_SB(1, 1), b3 + hstep, voffB); PG8_STAGE(PG8_SA(1, 0), a3, voffA);
;             PG8_WAIT_V(8); PG8_WAIT_L(0); PG8_BAR; PG8_MMA(1, 0, At, B0); PG8_MMA(1, 1, At, B1); PG8_BAR; PG8_SCHED;
	s_add_i32 s38, s63, s43
	v_lshl_add_u64 v[148:149], v[148:149], 0, s[12:13]
	s_mov_b32 m0, s38
	ds_read_b128 v[184:187], v155 offset:49152
	ds_read_b128 v[188:191], v155 offset:50176
	ds_read_b128 v[192:195], v155 offset:51200
	ds_read_b128 v[196:199], v155 offset:52224
	ds_read_b128 v[200:203], v155 offset:53248
	ds_read_b128 v[204:207], v155 offset:54272
	ds_read_b128 v[208:211], v155 offset:55296
	ds_read_b128 v[212:215], v155 offset:56320
	global_load_lds_dwordx4 v[148:149], off
	s_add_i32 m0, s38, 0x2000
	s_add_u32 s36, s36, 0x40080
	v_lshl_add_u64 v[148:149], v[216:217], 0, s[12:13]
	s_addc_u32 s37, s37, 0
	s_add_i32 s38, s64, s43
	global_load_lds_dwordx4 v[148:149], off
	v_lshl_add_u64 v[148:149], s[36:37], 0, v[132:133]
	s_mov_b32 m0, s38
	s_nop 0
	global_load_lds_dwordx4 v[148:149], off
	v_lshl_add_u64 v[148:149], s[36:37], 0, v[128:129]
	s_add_i32 m0, s38, 0x2000
	s_nop 0
	global_load_lds_dwordx4 v[148:149], off
	v_lshl_add_u64 v[148:149], v[218:219], 0, s[12:13]
	s_mov_b32 m0, s50
	s_nop 0
	global_load_lds_dwordx4 v[148:149], off
	v_lshl_add_u64 v[148:149], v[220:221], 0, s[12:13]
	s_mov_b32 m0, s51
	s_nop 0
	global_load_lds_dwordx4 v[148:149], off
	s_waitcnt vmcnt(12)
	s_waitcnt lgkmcnt(0)
	s_barrier
	s_waitcnt lgkmcnt(0)
	v_mfma_f32_16x16x32_bf16 v[60:63], v[144:147], v[184:187], v[60:63]
	v_mfma_f32_16x16x32_bf16 v[56:59], v[160:163], v[184:187], v[56:59]
	v_mfma_f32_16x16x32_bf16 v[44:47], v[144:147], v[192:195], v[44:47]
	v_mfma_f32_16x16x32_bf16 v[40:43], v[160:163], v[192:195], v[40:43]
	v_mfma_f32_16x16x32_bf16 v[28:31], v[144:147], v[200:203], v[28:31]
	v_mfma_f32_16x16x32_bf16 v[24:27], v[160:163], v[200:203], v[24:27]
	v_mfma_f32_16x16x32_bf16 v[12:15], v[144:147], v[208:211], v[12:15]
	v_mfma_f32_16x16x32_bf16 v[8:11], v[160:163], v[208:211], v[8:11]
	v_mfma_f32_16x16x32_bf16 v[60:63], v[156:159], v[188:191], v[60:63]
	v_mfma_f32_16x16x32_bf16 v[56:59], v[164:167], v[188:191], v[56:59]
	v_mfma_f32_16x16x32_bf16 v[44:47], v[156:159], v[196:199], v[44:47]
	v_mfma_f32_16x16x32_bf16 v[40:43], v[164:167], v[196:199], v[40:43]
	v_mfma_f32_16x16x32_bf16 v[28:31], v[156:159], v[204:207], v[28:31]
	v_mfma_f32_16x16x32_bf16 v[24:27], v[164:167], v[204:207], v[24:27]
	v_mfma_f32_16x16x32_bf16 v[12:15], v[156:159], v[212:215], v[12:15]
	v_mfma_f32_16x16x32_bf16 v[8:11], v[164:167], v[212:215], v[8:11]
	v_mfma_f32_16x16x32_bf16 v[52:55], v[168:171], v[184:187], v[52:55]
	v_mfma_f32_16x16x32_bf16 v[48:51], v[176:179], v[184:187], v[48:51]
	v_mfma_f32_16x16x32_bf16 v[36:39], v[168:171], v[192:195], v[36:39]
	v_mfma_f32_16x16x32_bf16 v[32:35], v[176:179], v[192:195], v[32:35]
	v_mfma_f32_16x16x32_bf16 v[20:23], v[168:171], v[200:203], v[20:23]
	v_mfma_f32_16x16x32_bf16 v[16:19], v[176:179], v[200:203], v[16:19]
	v_mfma_f32_16x16x32_bf16 v[4:7], v[168:171], v[208:211], v[4:7]
	v_mfma_f32_16x16x32_bf16 v[0:3], v[176:179], v[208:211], v[0:3]
	v_mfma_f32_16x16x32_bf16 v[52:55], v[172:175], v[188:191], v[52:55]
	v_mfma_f32_16x16x32_bf16 v[48:51], v[180:183], v[188:191], v[48:51]
	v_mfma_f32_16x16x32_bf16 v[36:39], v[172:175], v[196:199], v[36:39]
	v_mfma_f32_16x16x32_bf16 v[32:35], v[180:183], v[196:199], v[32:35]
	v_mfma_f32_16x16x32_bf16 v[20:23], v[172:175], v[204:207], v[20:23]
	v_mfma_f32_16x16x32_bf16 v[16:19], v[180:183], v[204:207], v[16:19]
	v_mfma_f32_16x16x32_bf16 v[4:7], v[172:175], v[212:215], v[4:7]
	v_mfma_f32_16x16x32_bf16 v[0:3], v[180:183], v[212:215], v[0:3]
	s_add_i32 s62, s62, 2
	s_add_u32 s0, s0, 0x100
	s_addc_u32 s1, s1, 0
	s_add_u32 s60, s60, 0x100
	s_addc_u32 s61, s61, 0
	s_cmp_gt_u32 s62, 13
	s_barrier
	s_cbranch_scc0 .LBB0_316
	s_and_b64 vcc, exec, s[14:15]
	s_cbranch_vccz .LBB0_319
	s_barrier

; #define PG8_STAGE(bufoff, gbase, voff) do { _Pragma("unroll") for (int _i = 0; _i < 2; ++_i) \
;         __builtin_amdgcn_global_load_lds((const unsigned*)((const char*)(gbase) + (voff)[_i]), (PG8_LAS unsigned*)(lds + (bufoff) + ldsw + _i * 8192), 16, 0, 0); } while (0)
; #define PG8_LDA(dst, b, h) do { _Pragma("unroll") for (int m = 0; m < 4; ++m) _Pragma("unroll") for (int k = 0; k < 2; ++k) dst[m][k] = *(const PG8_LAS bf16x8*)(lds + PG8_SA(b, h) + aoff + m * 2048 + k * 1024); } while (0)
; #define PG8_LDB(dst, b, h) do { _Pragma("unroll") for (int n = 0; n < 2; ++n) _Pragma("unroll") for (int k = 0; k < 2; ++k) dst[n][k] = *(const PG8_LAS bf16x8*)(lds + PG8_SB(b, h) + boff + n * 2048 + k * 1024); } while (0)
; #define PG8_MMA(ai, bj, At, Bt) do { __builtin_amdgcn_s_setprio(1); _Pragma("unroll") for (int m = 0; m < 4; ++m) _Pragma("unroll") for (int n = 0; n < 2; ++n) _Pragma("unroll") for (int k = 0; k < 2; ++k) \
;         acc[ai][bj][m][n] = __builtin_amdgcn_mfma_f32_16x16x32_bf16(Bt[n][k], At[m][k], acc[ai][bj][m][n], 0, 0, 0); __builtin_amdgcn_s_setprio(0); } while (0)
; #define PG8_WAIT_V(n) asm volatile("s_waitcnt vmcnt(" #n ")" ::: "memory")
; #define PG8_WAIT_L(n) asm volatile("s_waitcnt lgkmcnt(" #n ")" ::: "memory")
; #define PG8_BAR __builtin_amdgcn_s_barrier()
; #define PG8_SCHED __builtin_amdgcn_sched_barrier(0)
; template <class Epi, class Sched, bool ALIGN_EPI = false, bool SP2 = false>
; __device__ __forceinline__ void gemm_phase(PG8_LAS unsigned char* lds, const Gemm g, const Sched& S, const Epi& E, const int tid_in) {
;     ...
;             PG8_LDB(B0, 0, 0); PG8_LDB(B1, 0, 1); PG8_SCHED; PG8_LDA(At, 0, 0); PG8_STAGE(PG8_SA(1, 1), a1 + hstep, voffA);
;             PG8_WAIT_V(8); PG8_WAIT_L(0); PG8_BAR; PG8_MMA(0, 0, At, B0); PG8_MMA(0, 1, At, B1); PG8_BAR; PG8_SCHED;
;             PG8_LDA(At, 0, 1); PG8_STAGE(PG8_SB(0, 0), b2, voffB); PG8_STAGE(PG8_SB(0, 1), b2 + hstep, voffB); PG8_STAGE(PG8_SA(0, 0), a2, voffA);
;             PG8_WAIT_V(8); PG8_WAIT_L(0); PG8_BAR; PG8_MMA(1, 0, At, B0); PG8_MMA(1, 1, At, B1); PG8_BAR; PG8_SCHED;
.LBB0_391:
	ds_read_b128 v[144:147], v153
	ds_read_b128 v[156:159], v153 offset:1024
	ds_read_b128 v[160:163], v153 offset:2048
	ds_read_b128 v[164:167], v153 offset:3072
	ds_read_b128 v[168:171], v154
	ds_read_b128 v[172:175], v154 offset:1024
	ds_read_b128 v[176:179], v154 offset:2048
	ds_read_b128 v[180:183], v154 offset:3072
	s_add_u32 s38, s0, 0xfffc0080
	s_addc_u32 s39, s1, -1
	s_cmp_eq_u32 s62, 12
	s_cselect_b32 s41, s29, s39
	s_cselect_b32 s40, s58, s38
	s_cselect_b32 s39, s27, s61
	s_cselect_b32 s38, s59, s60
	v_lshl_add_u64 v[148:149], s[0:1], 0, v[136:137]
	s_add_i32 m0, s37, 0xc000
	ds_read_b128 v[184:187], v155
	ds_read_b128 v[188:191], v155 offset:1024
	ds_read_b128 v[192:195], v155 offset:2048
	ds_read_b128 v[196:199], v155 offset:3072
	ds_read_b128 v[200:203], v155 offset:4096
	ds_read_b128 v[204:207], v155 offset:5120
	ds_read_b128 v[208:211], v155 offset:6144
	ds_read_b128 v[212:215], v155 offset:7168
	global_load_lds_dwordx4 v[148:149], off
	v_lshl_add_u64 v[148:149], s[0:1], 0, v[138:139]
	s_add_i32 m0, s37, 0xe000
	s_nop 0
	global_load_lds_dwordx4 v[148:149], off
	s_waitcnt vmcnt(8)
	s_waitcnt lgkmcnt(0)
	s_barrier
	s_waitcnt lgkmcnt(0)
	v_mfma_f32_16x16x32_bf16 v[124:127], v[144:147], v[184:187], v[124:127]
	v_mfma_f32_16x16x32_bf16 v[120:123], v[160:163], v[184:187], v[120:123]
	v_mfma_f32_16x16x32_bf16 v[108:111], v[144:147], v[192:195], v[108:111]
	v_mfma_f32_16x16x32_bf16 v[104:107], v[160:163], v[192:195], v[104:107]
	v_mfma_f32_16x16x32_bf16 v[92:95], v[144:147], v[200:203], v[92:95]
	v_mfma_f32_16x16x32_bf16 v[88:91], v[160:163], v[200:203], v[88:91]
	v_mfma_f32_16x16x32_bf16 v[76:79], v[144:147], v[208:211], v[76:79]
	v_mfma_f32_16x16x32_bf16 v[72:75], v[160:163], v[208:211], v[72:75]
	v_mfma_f32_16x16x32_bf16 v[124:127], v[156:159], v[188:191], v[124:127]
	v_mfma_f32_16x16x32_bf16 v[120:123], v[164:167], v[188:191], v[120:123]
	v_mfma_f32_16x16x32_bf16 v[108:111], v[156:159], v[196:199], v[108:111]
	v_mfma_f32_16x16x32_bf16 v[104:107], v[164:167], v[196:199], v[104:107]
	v_mfma_f32_16x16x32_bf16 v[92:95], v[156:159], v[204:207], v[92:95]
	v_mfma_f32_16x16x32_bf16 v[88:91], v[164:167], v[204:207], v[88:91]
	v_mfma_f32_16x16x32_bf16 v[76:79], v[156:159], v[212:215], v[76:79]
	v_mfma_f32_16x16x32_bf16 v[72:75], v[164:167], v[212:215], v[72:75]
	v_mfma_f32_16x16x32_bf16 v[116:119], v[168:171], v[184:187], v[116:119]
	v_mfma_f32_16x16x32_bf16 v[112:115], v[176:179], v[184:187], v[112:115]
	v_mfma_f32_16x16x32_bf16 v[100:103], v[168:171], v[192:195], v[100:103]
	v_mfma_f32_16x16x32_bf16 v[96:99], v[176:179], v[192:195], v[96:99]
	v_mfma_f32_16x16x32_bf16 v[84:87], v[168:171], v[200:203], v[84:87]
	v_mfma_f32_16x16x32_bf16 v[80:83], v[176:179], v[200:203], v[80:83]
	v_mfma_f32_16x16x32_bf16 v[68:71], v[168:171], v[208:211], v[68:71]
	v_mfma_f32_16x16x32_bf16 v[64:67], v[176:179], v[208:211], v[64:67]
	v_mfma_f32_16x16x32_bf16 v[116:119], v[172:175], v[188:191], v[116:119]
	v_mfma_f32_16x16x32_bf16 v[112:115], v[180:183], v[188:191], v[112:115]
	v_mfma_f32_16x16x32_bf16 v[100:103], v[172:175], v[196:199], v[100:103]
	v_mfma_f32_16x16x32_bf16 v[96:99], v[180:183], v[196:199], v[96:99]
	v_mfma_f32_16x16x32_bf16 v[84:87], v[172:175], v[204:207], v[84:87]
	v_mfma_f32_16x16x32_bf16 v[80:83], v[180:183], v[204:207], v[80:83]
	v_mfma_f32_16x16x32_bf16 v[68:71], v[172:175], v[212:215], v[68:71]
	v_mfma_f32_16x16x32_bf16 v[64:67], v[180:183], v[212:215], v[64:67]
	s_barrier
	s_add_i32 s63, s53, s43
	v_lshl_add_u64 v[148:149], s[38:39], 0, v[132:133]
	s_mov_b32 m0, s63
	ds_read_b128 v[184:187], v155 offset:16384
	ds_read_b128 v[188:191], v155 offset:17408
	ds_read_b128 v[192:195], v155 offset:18432
	ds_read_b128 v[196:199], v155 offset:19456
	ds_read_b128 v[200:203], v155 offset:20480
	ds_read_b128 v[204:207], v155 offset:21504
	ds_read_b128 v[208:211], v155 offset:22528
	ds_read_b128 v[212:215], v155 offset:23552
	global_load_lds_dwordx4 v[148:149], off
	s_add_i32 m0, s63, 0x2000
	s_add_u32 s64, s38, 0x40000
	v_lshl_add_u64 v[216:217], s[38:39], 0, v[128:129]
	s_addc_u32 s65, s39, 0
	s_add_i32 s63, s56, s43
	global_load_lds_dwordx4 v[216:217], off
	v_lshl_add_u64 v[218:219], s[64:65], 0, v[132:133]
	s_mov_b32 m0, s63
	v_lshl_add_u64 v[220:221], s[40:41], 0, v[130:131]
	global_load_lds_dwordx4 v[218:219], off
	v_lshl_add_u64 v[218:219], s[64:65], 0, v[128:129]
	s_add_i32 m0, s63, 0x2000
	s_nop 0
	global_load_lds_dwordx4 v[218:219], off
	v_lshl_add_u64 v[218:219], s[40:41], 0, v[134:135]
	s_mov_b32 m0, s37
	s_nop 0
	global_load_lds_dwordx4 v[218:219], off
	s_mov_b32 m0, s45
	s_nop 0
	global_load_lds_dwordx4 v[220:221], off
	s_waitcnt vmcnt(8)
	s_waitcnt lgkmcnt(0)
	s_barrier
; #define PG8_STAGE(bufoff, gbase, voff) do { _Pragma("unroll") for (int _i = 0; _i < 2; ++_i) \
;         __builtin_amdgcn_global_load_lds((const unsigned*)((const char*)(gbase) + (voff)[_i]), (PG8_LAS unsigned*)(lds + (bufoff) + ldsw + _i * 8192), 16, 0, 0); } while (0)
; #define PG8_LDA(dst, b, h) do { _Pragma("unroll") for (int m = 0; m < 4; ++m) _Pragma("unroll") for (int k = 0; k < 2; ++k) dst[m][k] = *(const PG8_LAS bf16x8*)(lds + PG8_SA(b, h) + aoff + m * 2048 + k * 1024); } while (0)
; #define PG8_LDB(dst, b, h) do { _Pragma("unroll") for (int n = 0; n < 2; ++n) _Pragma("unroll") for (int k = 0; k < 2; ++k) dst[n][k] = *(const PG8_LAS bf16x8*)(lds + PG8_SB(b, h) + boff + n * 2048 + k * 1024); } while (0)
; #define PG8_MMA(ai, bj, At, Bt) do { __builtin_amdgcn_s_setprio(1); _Pragma("unroll") for (int m = 0; m < 4; ++m) _Pragma("unroll") for (int n = 0; n < 2; ++n) _Pragma("unroll") for (int k = 0; k < 2; ++k) \
;         acc[ai][bj][m][n] = __builtin_amdgcn_mfma_f32_16x16x32_bf16(Bt[n][k], At[m][k], acc[ai][bj][m][n], 0, 0, 0); __builtin_amdgcn_s_setprio(0); } while (0)
; #define PG8_WAIT_V(n) asm volatile("s_waitcnt vmcnt(" #n ")" ::: "memory")
; #define PG8_WAIT_L(n) asm volatile("s_waitcnt lgkmcnt(" #n ")" ::: "memory")
; #define PG8_BAR __builtin_amdgcn_s_barrier()
; #define PG8_SCHED __builtin_amdgcn_sched_barrier(0)
; template <class Epi, class Sched, bool ALIGN_EPI = false, bool SP2 = false>
; __device__ __forceinline__ void gemm_phase(PG8_LAS unsigned char* lds, const Gemm g, const Sched& S, const Epi& E, const int tid_in) {
;     ...
;             PG8_WAIT_V(8); PG8_WAIT_L(0); PG8_BAR; PG8_MMA(1, 0, At, B0); PG8_MMA(1, 1, At, B1); PG8_BAR; PG8_SCHED;
;             PG8_LDB(B0, 1, 0); PG8_LDB(B1, 1, 1); PG8_SCHED; PG8_LDA(At, 1, 0); PG8_STAGE(PG8_SA(0, 1), a2 + hstep, voffA);
;             PG8_WAIT_V(8); PG8_WAIT_L(0); PG8_BAR; PG8_MMA(0, 0, At, B0); PG8_MMA(0, 1, At, B1); PG8_BAR; PG8_SCHED;
	s_waitcnt lgkmcnt(0)
	v_mfma_f32_16x16x32_bf16 v[60:63], v[144:147], v[184:187], v[60:63]
	v_mfma_f32_16x16x32_bf16 v[56:59], v[160:163], v[184:187], v[56:59]
	v_mfma_f32_16x16x32_bf16 v[44:47], v[144:147], v[192:195], v[44:47]
	v_mfma_f32_16x16x32_bf16 v[40:43], v[160:163], v[192:195], v[40:43]
	v_mfma_f32_16x16x32_bf16 v[28:31], v[144:147], v[200:203], v[28:31]
	v_mfma_f32_16x16x32_bf16 v[24:27], v[160:163], v[200:203], v[24:27]
	v_mfma_f32_16x16x32_bf16 v[12:15], v[144:147], v[208:211], v[12:15]
	v_mfma_f32_16x16x32_bf16 v[8:11], v[160:163], v[208:211], v[8:11]
	v_mfma_f32_16x16x32_bf16 v[60:63], v[156:159], v[188:191], v[60:63]
	v_mfma_f32_16x16x32_bf16 v[56:59], v[164:167], v[188:191], v[56:59]
	v_mfma_f32_16x16x32_bf16 v[44:47], v[156:159], v[196:199], v[44:47]
	v_mfma_f32_16x16x32_bf16 v[40:43], v[164:167], v[196:199], v[40:43]
	v_mfma_f32_16x16x32_bf16 v[28:31], v[156:159], v[204:207], v[28:31]
	v_mfma_f32_16x16x32_bf16 v[24:27], v[164:167], v[204:207], v[24:27]
	v_mfma_f32_16x16x32_bf16 v[12:15], v[156:159], v[212:215], v[12:15]
	v_mfma_f32_16x16x32_bf16 v[8:11], v[164:167], v[212:215], v[8:11]
	v_mfma_f32_16x16x32_bf16 v[52:55], v[168:171], v[184:187], v[52:55]
	v_mfma_f32_16x16x32_bf16 v[48:51], v[176:179], v[184:187], v[48:51]
	v_mfma_f32_16x16x32_bf16 v[36:39], v[168:171], v[192:195], v[36:39]
	v_mfma_f32_16x16x32_bf16 v[32:35], v[176:179], v[192:195], v[32:35]
	v_mfma_f32_16x16x32_bf16 v[20:23], v[168:171], v[200:203], v[20:23]
	v_mfma_f32_16x16x32_bf16 v[16:19], v[176:179], v[200:203], v[16:19]
	v_mfma_f32_16x16x32_bf16 v[4:7], v[168:171], v[208:211], v[4:7]
	v_mfma_f32_16x16x32_bf16 v[0:3], v[176:179], v[208:211], v[0:3]
	v_mfma_f32_16x16x32_bf16 v[52:55], v[172:175], v[188:191], v[52:55]
	v_mfma_f32_16x16x32_bf16 v[48:51], v[180:183], v[188:191], v[48:51]
	v_mfma_f32_16x16x32_bf16 v[36:39], v[172:175], v[196:199], v[36:39]
	v_mfma_f32_16x16x32_bf16 v[32:35], v[180:183], v[196:199], v[32:35]
	v_mfma_f32_16x16x32_bf16 v[20:23], v[172:175], v[204:207], v[20:23]
	v_mfma_f32_16x16x32_bf16 v[16:19], v[180:183], v[204:207], v[16:19]
	v_mfma_f32_16x16x32_bf16 v[4:7], v[172:175], v[212:215], v[4:7]
	v_mfma_f32_16x16x32_bf16 v[0:3], v[180:183], v[212:215], v[0:3]
	s_barrier
	s_add_i32 s63, 0, 0x18000
	s_add_i32 s64, 0, 0x1c000
	v_add_u32_e32 v164, s63, v151
	v_add_u32_e32 v180, s64, v151
	ds_read_b128 v[144:147], v164
	ds_read_b128 v[156:159], v164 offset:1024
	ds_read_b128 v[160:163], v164 offset:2048
	ds_read_b128 v[164:167], v164 offset:3072
	ds_read_b128 v[168:171], v180
	ds_read_b128 v[172:175], v180 offset:1024
	ds_read_b128 v[176:179], v180 offset:2048
	ds_read_b128 v[180:183], v180 offset:3072
	s_add_u32 s40, s40, 0x40000
	s_addc_u32 s41, s41, 0
	s_mov_b32 m0, s46
	v_lshl_add_u64 v[222:223], s[40:41], 0, v[134:135]
	ds_read_b128 v[184:187], v155 offset:32768
	ds_read_b128 v[188:191], v155 offset:33792
	ds_read_b128 v[192:195], v155 offset:34816
	ds_read_b128 v[196:199], v155 offset:35840
	ds_read_b128 v[200:203], v155 offset:36864
	ds_read_b128 v[204:207], v155 offset:37888
	ds_read_b128 v[208:211], v155 offset:38912
	ds_read_b128 v[212:215], v155 offset:39936
	global_load_lds_dwordx4 v[222:223], off
	v_lshl_add_u64 v[222:223], s[40:41], 0, v[130:131]
	s_mov_b32 m0, s47
	s_nop 0
	global_load_lds_dwordx4 v[222:223], off
	s_waitcnt vmcnt(8)
	s_waitcnt lgkmcnt(0)
	s_barrier
	s_waitcnt lgkmcnt(0)
	v_mfma_f32_16x16x32_bf16 v[124:127], v[144:147], v[184:187], v[124:127]
	v_mfma_f32_16x16x32_bf16 v[120:123], v[160:163], v[184:187], v[120:123]
	v_mfma_f32_16x16x32_bf16 v[108:111], v[144:147], v[192:195], v[108:111]
	v_mfma_f32_16x16x32_bf16 v[104:107], v[160:163], v[192:195], v[104:107]
	v_mfma_f32_16x16x32_bf16 v[92:95], v[144:147], v[200:203], v[92:95]
	v_mfma_f32_16x16x32_bf16 v[88:91], v[160:163], v[200:203], v[88:91]
	v_mfma_f32_16x16x32_bf16 v[76:79], v[144:147], v[208:211], v[76:79]
	v_mfma_f32_16x16x32_bf16 v[72:75], v[160:163], v[208:211], v[72:75]
	v_mfma_f32_16x16x32_bf16 v[124:127], v[156:159], v[188:191], v[124:127]
	v_mfma_f32_16x16x32_bf16 v[120:123], v[164:167], v[188:191], v[120:123]
	v_mfma_f32_16x16x32_bf16 v[108:111], v[156:159], v[196:199], v[108:111]
	v_mfma_f32_16x16x32_bf16 v[104:107], v[164:167], v[196:199], v[104:107]
	v_mfma_f32_16x16x32_bf16 v[92:95], v[156:159], v[204:207], v[92:95]
	v_mfma_f32_16x16x32_bf16 v[88:91], v[164:167], v[204:207], v[88:91]
	v_mfma_f32_16x16x32_bf16 v[76:79], v[156:159], v[212:215], v[76:79]
	v_mfma_f32_16x16x32_bf16 v[72:75], v[164:167], v[212:215], v[72:75]
	v_mfma_f32_16x16x32_bf16 v[116:119], v[168:171], v[184:187], v[116:119]
	v_mfma_f32_16x16x32_bf16 v[112:115], v[176:179], v[184:187], v[112:115]
	v_mfma_f32_16x16x32_bf16 v[100:103], v[168:171], v[192:195], v[100:103]
	v_mfma_f32_16x16x32_bf16 v[96:99], v[176:179], v[192:195], v[96:99]
	v_mfma_f32_16x16x32_bf16 v[84:87], v[168:171], v[200:203], v[84:87]
	v_mfma_f32_16x16x32_bf16 v[80:83], v[176:179], v[200:203], v[80:83]
	v_mfma_f32_16x16x32_bf16 v[68:71], v[168:171], v[208:211], v[68:71]
	v_mfma_f32_16x16x32_bf16 v[64:67], v[176:179], v[208:211], v[64:67]
	v_mfma_f32_16x16x32_bf16 v[116:119], v[172:175], v[188:191], v[116:119]
	v_mfma_f32_16x16x32_bf16 v[112:115], v[180:183], v[188:191], v[112:115]
	v_mfma_f32_16x16x32_bf16 v[100:103], v[172:175], v[196:199], v[100:103]
	v_mfma_f32_16x16x32_bf16 v[96:99], v[180:183], v[196:199], v[96:99]
	v_mfma_f32_16x16x32_bf16 v[84:87], v[172:175], v[204:207], v[84:87]
	v_mfma_f32_16x16x32_bf16 v[80:83], v[180:183], v[204:207], v[80:83]
	v_mfma_f32_16x16x32_bf16 v[68:71], v[172:175], v[212:215], v[68:71]
	v_mfma_f32_16x16x32_bf16 v[64:67], v[180:183], v[212:215], v[64:67]
	s_barrier
; #define PG8_STAGE(bufoff, gbase, voff) do { _Pragma("unroll") for (int _i = 0; _i < 2; ++_i) \
;         __builtin_amdgcn_global_load_lds((const unsigned*)((const char*)(gbase) + (voff)[_i]), (PG8_LAS unsigned*)(lds + (bufoff) + ldsw + _i * 8192), 16, 0, 0); } while (0)
; #define PG8_LDA(dst, b, h) do { _Pragma("unroll") for (int m = 0; m < 4; ++m) _Pragma("unroll") for (int k = 0; k < 2; ++k) dst[m][k] = *(const PG8_LAS bf16x8*)(lds + PG8_SA(b, h) + aoff + m * 2048 + k * 1024); } while (0)
; #define PG8_MMA(ai, bj, At, Bt) do { __builtin_amdgcn_s_setprio(1); _Pragma("unroll") for (int m = 0; m < 4; ++m) _Pragma("unroll") for (int n = 0; n < 2; ++n) _Pragma("unroll") for (int k = 0; k < 2; ++k) \
;         acc[ai][bj][m][n] = __builtin_amdgcn_mfma_f32_16x16x32_bf16(Bt[n][k], At[m][k], acc[ai][bj][m][n], 0, 0, 0); __builtin_amdgcn_s_setprio(0); } while (0)
; #define PG8_WAIT_V(n) asm volatile("s_waitcnt vmcnt(" #n ")" ::: "memory")
; #define PG8_WAIT_L(n) asm volatile("s_waitcnt lgkmcnt(" #n ")" ::: "memory")
; #define PG8_BAR __builtin_amdgcn_s_barrier()
; #define PG8_SCHED __builtin_amdgcn_sched_barrier(0)
; template <class Epi, class Sched, bool ALIGN_EPI = false, bool SP2 = false>
; __device__ __forceinline__ void gemm_phase(PG8_LAS unsigned char* lds, const Gemm g, const Sched& S, const Epi& E, const int tid_in) {
;     ...
;         for (int t = 0; t < nt; t += 2) {
;             const bool last = (t == nt - 2);
;             const char* a1 = cA + (size_t)(t + 1) * kstep;
;             const char* a2 = last ? nA : cA + (size_t)(t + 2) * kstep; const char* b2 = last ? nB : cB + (size_t)(t + 2) * kstep;
;     ...
;             PG8_LDA(At, 1, 1); PG8_STAGE(PG8_SB(1, 0), b3, voffB); PG8_STAGE(PG8_SB(1, 1), b3 + hstep, voffB); PG8_STAGE(PG8_SA(1, 0), a3, voffA);
;             PG8_WAIT_V(8); PG8_WAIT_L(0); PG8_BAR; PG8_MMA(1, 0, At, B0); PG8_MMA(1, 1, At, B1); PG8_BAR; PG8_SCHED;
	s_add_i32 s40, s63, s43
	v_lshl_add_u64 v[148:149], v[148:149], 0, s[16:17]
	s_mov_b32 m0, s40
	ds_read_b128 v[184:187], v155 offset:49152
	ds_read_b128 v[188:191], v155 offset:50176
	ds_read_b128 v[192:195], v155 offset:51200
	ds_read_b128 v[196:199], v155 offset:52224
	ds_read_b128 v[200:203], v155 offset:53248
	ds_read_b128 v[204:207], v155 offset:54272
	ds_read_b128 v[208:211], v155 offset:55296
	ds_read_b128 v[212:215], v155 offset:56320
	global_load_lds_dwordx4 v[148:149], off
	s_add_i32 m0, s40, 0x2000
	s_add_u32 s38, s38, 0x40080
	v_lshl_add_u64 v[148:149], v[216:217], 0, s[16:17]
	s_addc_u32 s39, s39, 0
	s_add_i32 s40, s64, s43
	global_load_lds_dwordx4 v[148:149], off
	v_lshl_add_u64 v[148:149], s[38:39], 0, v[132:133]
	s_mov_b32 m0, s40
	s_nop 0
	global_load_lds_dwordx4 v[148:149], off
	v_lshl_add_u64 v[148:149], s[38:39], 0, v[128:129]
	s_add_i32 m0, s40, 0x2000
	s_nop 0
	global_load_lds_dwordx4 v[148:149], off
	v_lshl_add_u64 v[148:149], v[218:219], 0, s[16:17]
	s_mov_b32 m0, s50
	s_nop 0
	global_load_lds_dwordx4 v[148:149], off
	v_lshl_add_u64 v[148:149], v[220:221], 0, s[16:17]
	s_mov_b32 m0, s51
	s_nop 0
	global_load_lds_dwordx4 v[148:149], off
	s_waitcnt vmcnt(8)
	s_waitcnt lgkmcnt(0)
	s_barrier
	s_waitcnt lgkmcnt(0)
	v_mfma_f32_16x16x32_bf16 v[60:63], v[144:147], v[184:187], v[60:63]
	v_mfma_f32_16x16x32_bf16 v[56:59], v[160:163], v[184:187], v[56:59]
	v_mfma_f32_16x16x32_bf16 v[44:47], v[144:147], v[192:195], v[44:47]
	v_mfma_f32_16x16x32_bf16 v[40:43], v[160:163], v[192:195], v[40:43]
	v_mfma_f32_16x16x32_bf16 v[28:31], v[144:147], v[200:203], v[28:31]
	v_mfma_f32_16x16x32_bf16 v[24:27], v[160:163], v[200:203], v[24:27]
	v_mfma_f32_16x16x32_bf16 v[12:15], v[144:147], v[208:211], v[12:15]
	v_mfma_f32_16x16x32_bf16 v[8:11], v[160:163], v[208:211], v[8:11]
	v_mfma_f32_16x16x32_bf16 v[60:63], v[156:159], v[188:191], v[60:63]
	v_mfma_f32_16x16x32_bf16 v[56:59], v[164:167], v[188:191], v[56:59]
	v_mfma_f32_16x16x32_bf16 v[44:47], v[156:159], v[196:199], v[44:47]
	v_mfma_f32_16x16x32_bf16 v[40:43], v[164:167], v[196:199], v[40:43]
	v_mfma_f32_16x16x32_bf16 v[28:31], v[156:159], v[204:207], v[28:31]
	v_mfma_f32_16x16x32_bf16 v[24:27], v[164:167], v[204:207], v[24:27]
	v_mfma_f32_16x16x32_bf16 v[12:15], v[156:159], v[212:215], v[12:15]
	v_mfma_f32_16x16x32_bf16 v[8:11], v[164:167], v[212:215], v[8:11]
	v_mfma_f32_16x16x32_bf16 v[52:55], v[168:171], v[184:187], v[52:55]
	v_mfma_f32_16x16x32_bf16 v[48:51], v[176:179], v[184:187], v[48:51]
	v_mfma_f32_16x16x32_bf16 v[36:39], v[168:171], v[192:195], v[36:39]
	v_mfma_f32_16x16x32_bf16 v[32:35], v[176:179], v[192:195], v[32:35]
	v_mfma_f32_16x16x32_bf16 v[20:23], v[168:171], v[200:203], v[20:23]
	v_mfma_f32_16x16x32_bf16 v[16:19], v[176:179], v[200:203], v[16:19]
	v_mfma_f32_16x16x32_bf16 v[4:7], v[168:171], v[208:211], v[4:7]
	v_mfma_f32_16x16x32_bf16 v[0:3], v[176:179], v[208:211], v[0:3]
	v_mfma_f32_16x16x32_bf16 v[52:55], v[172:175], v[188:191], v[52:55]
	v_mfma_f32_16x16x32_bf16 v[48:51], v[180:183], v[188:191], v[48:51]
	v_mfma_f32_16x16x32_bf16 v[36:39], v[172:175], v[196:199], v[36:39]
	v_mfma_f32_16x16x32_bf16 v[32:35], v[180:183], v[196:199], v[32:35]
	v_mfma_f32_16x16x32_bf16 v[20:23], v[172:175], v[204:207], v[20:23]
	v_mfma_f32_16x16x32_bf16 v[16:19], v[180:183], v[204:207], v[16:19]
	v_mfma_f32_16x16x32_bf16 v[4:7], v[172:175], v[212:215], v[4:7]
	v_mfma_f32_16x16x32_bf16 v[0:3], v[180:183], v[212:215], v[0:3]
	s_add_i32 s62, s62, 2
	s_add_u32 s0, s0, 0x100
	s_addc_u32 s1, s1, 0
	s_add_u32 s60, s60, 0x100
	s_addc_u32 s61, s61, 0
	s_cmp_gt_u32 s62, 13
	s_barrier
	s_cbranch_scc0 .LBB0_391
	s_and_b64 vcc, exec, s[18:19]
	s_cbranch_vccz .LBB0_394
	s_barrier

; #define PG8_STAGE(bufoff, gbase, voff) do { _Pragma("unroll") for (int _i = 0; _i < 2; ++_i) \
;         __builtin_amdgcn_global_load_lds((const unsigned*)((const char*)(gbase) + (voff)[_i]), (PG8_LAS unsigned*)(lds + (bufoff) + ldsw + _i * 8192), 16, 0, 0); } while (0)
; #define PG8_LDA(dst, b, h) do { _Pragma("unroll") for (int m = 0; m < 4; ++m) _Pragma("unroll") for (int k = 0; k < 2; ++k) dst[m][k] = *(const PG8_LAS bf16x8*)(lds + PG8_SA(b, h) + aoff + m * 2048 + k * 1024); } while (0)
; #define PG8_LDB(dst, b, h) do { _Pragma("unroll") for (int n = 0; n < 2; ++n) _Pragma("unroll") for (int k = 0; k < 2; ++k) dst[n][k] = *(const PG8_LAS bf16x8*)(lds + PG8_SB(b, h) + boff + n * 2048 + k * 1024); } while (0)
; #define PG8_MMA(ai, bj, At, Bt) do { __builtin_amdgcn_s_setprio(1); _Pragma("unroll") for (int m = 0; m < 4; ++m) _Pragma("unroll") for (int n = 0; n < 2; ++n) _Pragma("unroll") for (int k = 0; k < 2; ++k) \
;         acc[ai][bj][m][n] = __builtin_amdgcn_mfma_f32_16x16x32_bf16(Bt[n][k], At[m][k], acc[ai][bj][m][n], 0, 0, 0); __builtin_amdgcn_s_setprio(0); } while (0)
; #define PG8_WAIT_V(n) asm volatile("s_waitcnt vmcnt(" #n ")" ::: "memory")
; #define PG8_WAIT_L(n) asm volatile("s_waitcnt lgkmcnt(" #n ")" ::: "memory")
; #define PG8_BAR __builtin_amdgcn_s_barrier()
; #define PG8_SCHED __builtin_amdgcn_sched_barrier(0)
; template <class Epi, class Sched, bool ALIGN_EPI = false, bool SP2 = false>
; __device__ __forceinline__ void gemm_phase(PG8_LAS unsigned char* lds, const Gemm g, const Sched& S, const Epi& E, const int tid_in) {
;     ...
;             PG8_LDB(B0, 0, 0); PG8_LDB(B1, 0, 1); PG8_SCHED; PG8_LDA(At, 0, 0); PG8_STAGE(PG8_SA(1, 1), a1 + hstep, voffA);
;             PG8_WAIT_V(8); PG8_WAIT_L(0); PG8_BAR; PG8_MMA(0, 0, At, B0); PG8_MMA(0, 1, At, B1); PG8_BAR; PG8_SCHED;
;             PG8_LDA(At, 0, 1); PG8_STAGE(PG8_SB(0, 0), b2, voffB); PG8_STAGE(PG8_SB(0, 1), b2 + hstep, voffB); PG8_STAGE(PG8_SA(0, 0), a2, voffA);
;             PG8_WAIT_V(8); PG8_WAIT_L(0); PG8_BAR; PG8_MMA(1, 0, At, B0); PG8_MMA(1, 1, At, B1); PG8_BAR; PG8_SCHED;
.LBB0_535:
	ds_read_b128 v[174:177], v170
	ds_read_b128 v[178:181], v170 offset:1024
	ds_read_b128 v[182:185], v170 offset:2048
	ds_read_b128 v[186:189], v170 offset:3072
	ds_read_b128 v[190:193], v171
	ds_read_b128 v[194:197], v171 offset:1024
	ds_read_b128 v[198:201], v171 offset:2048
	ds_read_b128 v[202:205], v171 offset:3072
	s_add_u32 s38, s0, 0xfffc0080
	s_addc_u32 s39, s1, -1
	s_cmp_eq_u32 s73, 12
	s_cselect_b32 s41, s29, s39
	s_cselect_b32 s40, s69, s38
	s_cselect_b32 s39, s27, s72
	s_cselect_b32 s38, s70, s71
	v_lshl_add_u64 v[144:145], s[0:1], 0, v[136:137]
	s_add_i32 m0, s37, 0xc000
	ds_read_b128 v[206:209], v172
	ds_read_b128 v[210:213], v172 offset:1024
	ds_read_b128 v[214:217], v172 offset:2048
	ds_read_b128 v[218:221], v172 offset:3072
	ds_read_b128 v[222:225], v172 offset:4096
	ds_read_b128 v[226:229], v172 offset:5120
	ds_read_b128 v[230:233], v172 offset:6144
	ds_read_b128 v[234:237], v172 offset:7168
	global_load_lds_dwordx4 v[144:145], off
	v_lshl_add_u64 v[144:145], s[0:1], 0, v[138:139]
	s_add_i32 m0, s37, 0xe000
	s_nop 0
	global_load_lds_dwordx4 v[144:145], off
	s_waitcnt vmcnt(8)
	s_waitcnt lgkmcnt(0)
	s_barrier
	s_waitcnt lgkmcnt(0)
	v_mfma_f32_16x16x32_bf16 v[124:127], v[174:177], v[206:209], v[124:127]
	v_mfma_f32_16x16x32_bf16 v[120:123], v[182:185], v[206:209], v[120:123]
	v_mfma_f32_16x16x32_bf16 v[116:119], v[174:177], v[214:217], v[116:119]
	v_mfma_f32_16x16x32_bf16 v[108:111], v[182:185], v[214:217], v[108:111]
	v_mfma_f32_16x16x32_bf16 v[100:103], v[174:177], v[222:225], v[100:103]
	v_mfma_f32_16x16x32_bf16 v[92:95], v[182:185], v[222:225], v[92:95]
	v_mfma_f32_16x16x32_bf16 v[84:87], v[174:177], v[230:233], v[84:87]
	v_mfma_f32_16x16x32_bf16 v[76:79], v[182:185], v[230:233], v[76:79]
	v_mfma_f32_16x16x32_bf16 v[124:127], v[178:181], v[210:213], v[124:127]
	v_mfma_f32_16x16x32_bf16 v[120:123], v[186:189], v[210:213], v[120:123]
	v_mfma_f32_16x16x32_bf16 v[116:119], v[178:181], v[218:221], v[116:119]
	v_mfma_f32_16x16x32_bf16 v[108:111], v[186:189], v[218:221], v[108:111]
	v_mfma_f32_16x16x32_bf16 v[100:103], v[178:181], v[226:229], v[100:103]
	v_mfma_f32_16x16x32_bf16 v[92:95], v[186:189], v[226:229], v[92:95]
	v_mfma_f32_16x16x32_bf16 v[84:87], v[178:181], v[234:237], v[84:87]
	v_mfma_f32_16x16x32_bf16 v[76:79], v[186:189], v[234:237], v[76:79]
	v_mfma_f32_16x16x32_bf16 v[112:115], v[190:193], v[206:209], v[112:115]
	v_mfma_f32_16x16x32_bf16 v[104:107], v[198:201], v[206:209], v[104:107]
	v_mfma_f32_16x16x32_bf16 v[96:99], v[190:193], v[214:217], v[96:99]
	v_mfma_f32_16x16x32_bf16 v[88:91], v[198:201], v[214:217], v[88:91]
	v_mfma_f32_16x16x32_bf16 v[80:83], v[190:193], v[222:225], v[80:83]
	v_mfma_f32_16x16x32_bf16 v[72:75], v[198:201], v[222:225], v[72:75]
	v_mfma_f32_16x16x32_bf16 v[68:71], v[190:193], v[230:233], v[68:71]
	v_mfma_f32_16x16x32_bf16 v[64:67], v[198:201], v[230:233], v[64:67]
	v_mfma_f32_16x16x32_bf16 v[112:115], v[194:197], v[210:213], v[112:115]
	v_mfma_f32_16x16x32_bf16 v[104:107], v[202:205], v[210:213], v[104:107]
	v_mfma_f32_16x16x32_bf16 v[96:99], v[194:197], v[218:221], v[96:99]
	v_mfma_f32_16x16x32_bf16 v[88:91], v[202:205], v[218:221], v[88:91]
	v_mfma_f32_16x16x32_bf16 v[80:83], v[194:197], v[226:229], v[80:83]
	v_mfma_f32_16x16x32_bf16 v[72:75], v[202:205], v[226:229], v[72:75]
	v_mfma_f32_16x16x32_bf16 v[68:71], v[194:197], v[234:237], v[68:71]
	v_mfma_f32_16x16x32_bf16 v[64:67], v[202:205], v[234:237], v[64:67]
	s_barrier
	s_add_i32 s74, s62, s51
	v_lshl_add_u64 v[144:145], s[38:39], 0, v[132:133]
	s_mov_b32 m0, s74
	ds_read_b128 v[206:209], v172 offset:16384
	ds_read_b128 v[210:213], v172 offset:17408
	ds_read_b128 v[214:217], v172 offset:18432
	ds_read_b128 v[218:221], v172 offset:19456
	ds_read_b128 v[222:225], v172 offset:20480
	ds_read_b128 v[226:229], v172 offset:21504
	ds_read_b128 v[230:233], v172 offset:22528
	ds_read_b128 v[234:237], v172 offset:23552
	global_load_lds_dwordx4 v[144:145], off
	s_add_i32 m0, s74, 0x2000
	s_add_u32 s74, s38, 0x40000
	v_lshl_add_u64 v[238:239], s[38:39], 0, v[128:129]
	s_addc_u32 s75, s39, 0
	s_add_i32 s76, s63, s51
	global_load_lds_dwordx4 v[238:239], off
	v_lshl_add_u64 v[240:241], s[74:75], 0, v[132:133]
	s_mov_b32 m0, s76
	v_lshl_add_u64 v[242:243], s[40:41], 0, v[130:131]
	global_load_lds_dwordx4 v[240:241], off
	v_lshl_add_u64 v[240:241], s[74:75], 0, v[128:129]
	s_add_i32 m0, s76, 0x2000
	s_nop 0
	global_load_lds_dwordx4 v[240:241], off
	v_lshl_add_u64 v[240:241], s[40:41], 0, v[134:135]
	s_mov_b32 m0, s37
	s_nop 0
	global_load_lds_dwordx4 v[240:241], off
	s_mov_b32 m0, s52
	s_nop 0
	global_load_lds_dwordx4 v[242:243], off
	s_waitcnt vmcnt(8)
	s_waitcnt lgkmcnt(0)
	s_barrier
; #define PG8_STAGE(bufoff, gbase, voff) do { _Pragma("unroll") for (int _i = 0; _i < 2; ++_i) \
;         __builtin_amdgcn_global_load_lds((const unsigned*)((const char*)(gbase) + (voff)[_i]), (PG8_LAS unsigned*)(lds + (bufoff) + ldsw + _i * 8192), 16, 0, 0); } while (0)
; #define PG8_LDA(dst, b, h) do { _Pragma("unroll") for (int m = 0; m < 4; ++m) _Pragma("unroll") for (int k = 0; k < 2; ++k) dst[m][k] = *(const PG8_LAS bf16x8*)(lds + PG8_SA(b, h) + aoff + m * 2048 + k * 1024); } while (0)
; #define PG8_LDB(dst, b, h) do { _Pragma("unroll") for (int n = 0; n < 2; ++n) _Pragma("unroll") for (int k = 0; k < 2; ++k) dst[n][k] = *(const PG8_LAS bf16x8*)(lds + PG8_SB(b, h) + boff + n * 2048 + k * 1024); } while (0)
; #define PG8_MMA(ai, bj, At, Bt) do { __builtin_amdgcn_s_setprio(1); _Pragma("unroll") for (int m = 0; m < 4; ++m) _Pragma("unroll") for (int n = 0; n < 2; ++n) _Pragma("unroll") for (int k = 0; k < 2; ++k) \
;         acc[ai][bj][m][n] = __builtin_amdgcn_mfma_f32_16x16x32_bf16(Bt[n][k], At[m][k], acc[ai][bj][m][n], 0, 0, 0); __builtin_amdgcn_s_setprio(0); } while (0)
; #define PG8_WAIT_V(n) asm volatile("s_waitcnt vmcnt(" #n ")" ::: "memory")
; #define PG8_WAIT_L(n) asm volatile("s_waitcnt lgkmcnt(" #n ")" ::: "memory")
; #define PG8_BAR __builtin_amdgcn_s_barrier()
; #define PG8_SCHED __builtin_amdgcn_sched_barrier(0)
; template <class Epi, class Sched, bool ALIGN_EPI = false, bool SP2 = false>
; __device__ __forceinline__ void gemm_phase(PG8_LAS unsigned char* lds, const Gemm g, const Sched& S, const Epi& E, const int tid_in) {
;     ...
;             PG8_WAIT_V(8); PG8_WAIT_L(0); PG8_BAR; PG8_MMA(1, 0, At, B0); PG8_MMA(1, 1, At, B1); PG8_BAR; PG8_SCHED;
;             PG8_LDB(B0, 1, 0); PG8_LDB(B1, 1, 1); PG8_SCHED; PG8_LDA(At, 1, 0); PG8_STAGE(PG8_SA(0, 1), a2 + hstep, voffA);
;             PG8_WAIT_V(8); PG8_WAIT_L(0); PG8_BAR; PG8_MMA(0, 0, At, B0); PG8_MMA(0, 1, At, B1); PG8_BAR; PG8_SCHED;
	s_waitcnt lgkmcnt(0)
	v_mfma_f32_16x16x32_bf16 v[60:63], v[174:177], v[206:209], v[60:63]
	v_mfma_f32_16x16x32_bf16 v[56:59], v[182:185], v[206:209], v[56:59]
	v_mfma_f32_16x16x32_bf16 v[52:55], v[174:177], v[214:217], v[52:55]
	v_mfma_f32_16x16x32_bf16 v[44:47], v[182:185], v[214:217], v[44:47]
	v_mfma_f32_16x16x32_bf16 v[36:39], v[174:177], v[222:225], v[36:39]
	v_mfma_f32_16x16x32_bf16 v[28:31], v[182:185], v[222:225], v[28:31]
	v_mfma_f32_16x16x32_bf16 v[20:23], v[174:177], v[230:233], v[20:23]
	v_mfma_f32_16x16x32_bf16 v[12:15], v[182:185], v[230:233], v[12:15]
	v_mfma_f32_16x16x32_bf16 v[60:63], v[178:181], v[210:213], v[60:63]
	v_mfma_f32_16x16x32_bf16 v[56:59], v[186:189], v[210:213], v[56:59]
	v_mfma_f32_16x16x32_bf16 v[52:55], v[178:181], v[218:221], v[52:55]
	v_mfma_f32_16x16x32_bf16 v[44:47], v[186:189], v[218:221], v[44:47]
	v_mfma_f32_16x16x32_bf16 v[36:39], v[178:181], v[226:229], v[36:39]
	v_mfma_f32_16x16x32_bf16 v[28:31], v[186:189], v[226:229], v[28:31]
	v_mfma_f32_16x16x32_bf16 v[20:23], v[178:181], v[234:237], v[20:23]
	v_mfma_f32_16x16x32_bf16 v[12:15], v[186:189], v[234:237], v[12:15]
	v_mfma_f32_16x16x32_bf16 v[48:51], v[190:193], v[206:209], v[48:51]
	v_mfma_f32_16x16x32_bf16 v[40:43], v[198:201], v[206:209], v[40:43]
	v_mfma_f32_16x16x32_bf16 v[32:35], v[190:193], v[214:217], v[32:35]
	v_mfma_f32_16x16x32_bf16 v[24:27], v[198:201], v[214:217], v[24:27]
	v_mfma_f32_16x16x32_bf16 v[16:19], v[190:193], v[222:225], v[16:19]
	v_mfma_f32_16x16x32_bf16 v[8:11], v[198:201], v[222:225], v[8:11]
	v_mfma_f32_16x16x32_bf16 v[4:7], v[190:193], v[230:233], v[4:7]
	v_mfma_f32_16x16x32_bf16 v[0:3], v[198:201], v[230:233], v[0:3]
	v_mfma_f32_16x16x32_bf16 v[48:51], v[194:197], v[210:213], v[48:51]
	v_mfma_f32_16x16x32_bf16 v[40:43], v[202:205], v[210:213], v[40:43]
	v_mfma_f32_16x16x32_bf16 v[32:35], v[194:197], v[218:221], v[32:35]
	v_mfma_f32_16x16x32_bf16 v[24:27], v[202:205], v[218:221], v[24:27]
	v_mfma_f32_16x16x32_bf16 v[16:19], v[194:197], v[226:229], v[16:19]
	v_mfma_f32_16x16x32_bf16 v[8:11], v[202:205], v[226:229], v[8:11]
	v_mfma_f32_16x16x32_bf16 v[4:7], v[194:197], v[234:237], v[4:7]
	v_mfma_f32_16x16x32_bf16 v[0:3], v[202:205], v[234:237], v[0:3]
	s_barrier
	s_add_i32 s74, 0, 0x18000
	v_add_u32_e32 v173, s74, v168
	s_add_i32 s75, 0, 0x1c000
	ds_read_b128 v[174:177], v173
	ds_read_b128 v[178:181], v173 offset:1024
	ds_read_b128 v[182:185], v173 offset:2048
	ds_read_b128 v[186:189], v173 offset:3072
	v_add_u32_e32 v173, s75, v168
	ds_read_b128 v[190:193], v173
	ds_read_b128 v[194:197], v173 offset:1024
	ds_read_b128 v[198:201], v173 offset:2048
	ds_read_b128 v[202:205], v173 offset:3072
	s_add_u32 s40, s40, 0x40000
	s_addc_u32 s41, s41, 0
	s_mov_b32 m0, s53
	v_lshl_add_u64 v[244:245], s[40:41], 0, v[134:135]
	ds_read_b128 v[206:209], v172 offset:32768
	ds_read_b128 v[210:213], v172 offset:33792
	ds_read_b128 v[214:217], v172 offset:34816
	ds_read_b128 v[218:221], v172 offset:35840
	ds_read_b128 v[222:225], v172 offset:36864
	ds_read_b128 v[226:229], v172 offset:37888
	ds_read_b128 v[230:233], v172 offset:38912
	ds_read_b128 v[234:237], v172 offset:39936
	global_load_lds_dwordx4 v[244:245], off
	v_lshl_add_u64 v[244:245], s[40:41], 0, v[130:131]
	s_mov_b32 m0, s56
	s_nop 0
	global_load_lds_dwordx4 v[244:245], off
	s_waitcnt vmcnt(8)
	s_waitcnt lgkmcnt(0)
	s_barrier
	s_waitcnt lgkmcnt(0)
	v_mfma_f32_16x16x32_bf16 v[124:127], v[174:177], v[206:209], v[124:127]
	v_mfma_f32_16x16x32_bf16 v[120:123], v[182:185], v[206:209], v[120:123]
	v_mfma_f32_16x16x32_bf16 v[116:119], v[174:177], v[214:217], v[116:119]
	v_mfma_f32_16x16x32_bf16 v[108:111], v[182:185], v[214:217], v[108:111]
	v_mfma_f32_16x16x32_bf16 v[100:103], v[174:177], v[222:225], v[100:103]
	v_mfma_f32_16x16x32_bf16 v[92:95], v[182:185], v[222:225], v[92:95]
	v_mfma_f32_16x16x32_bf16 v[84:87], v[174:177], v[230:233], v[84:87]
	v_mfma_f32_16x16x32_bf16 v[76:79], v[182:185], v[230:233], v[76:79]
	v_mfma_f32_16x16x32_bf16 v[124:127], v[178:181], v[210:213], v[124:127]
	v_mfma_f32_16x16x32_bf16 v[120:123], v[186:189], v[210:213], v[120:123]
	v_mfma_f32_16x16x32_bf16 v[116:119], v[178:181], v[218:221], v[116:119]
	v_mfma_f32_16x16x32_bf16 v[108:111], v[186:189], v[218:221], v[108:111]
	v_mfma_f32_16x16x32_bf16 v[100:103], v[178:181], v[226:229], v[100:103]
	v_mfma_f32_16x16x32_bf16 v[92:95], v[186:189], v[226:229], v[92:95]
	v_mfma_f32_16x16x32_bf16 v[84:87], v[178:181], v[234:237], v[84:87]
	v_mfma_f32_16x16x32_bf16 v[76:79], v[186:189], v[234:237], v[76:79]
	v_mfma_f32_16x16x32_bf16 v[112:115], v[190:193], v[206:209], v[112:115]
	v_mfma_f32_16x16x32_bf16 v[104:107], v[198:201], v[206:209], v[104:107]
	v_mfma_f32_16x16x32_bf16 v[96:99], v[190:193], v[214:217], v[96:99]
	v_mfma_f32_16x16x32_bf16 v[88:91], v[198:201], v[214:217], v[88:91]
	v_mfma_f32_16x16x32_bf16 v[80:83], v[190:193], v[222:225], v[80:83]
	v_mfma_f32_16x16x32_bf16 v[72:75], v[198:201], v[222:225], v[72:75]
	v_mfma_f32_16x16x32_bf16 v[68:71], v[190:193], v[230:233], v[68:71]
	v_mfma_f32_16x16x32_bf16 v[64:67], v[198:201], v[230:233], v[64:67]
	v_mfma_f32_16x16x32_bf16 v[112:115], v[194:197], v[210:213], v[112:115]
	v_mfma_f32_16x16x32_bf16 v[104:107], v[202:205], v[210:213], v[104:107]
	v_mfma_f32_16x16x32_bf16 v[96:99], v[194:197], v[218:221], v[96:99]
	v_mfma_f32_16x16x32_bf16 v[88:91], v[202:205], v[218:221], v[88:91]
	v_mfma_f32_16x16x32_bf16 v[80:83], v[194:197], v[226:229], v[80:83]
	v_mfma_f32_16x16x32_bf16 v[72:75], v[202:205], v[226:229], v[72:75]
	v_mfma_f32_16x16x32_bf16 v[68:71], v[194:197], v[234:237], v[68:71]
	v_mfma_f32_16x16x32_bf16 v[64:67], v[202:205], v[234:237], v[64:67]
	s_barrier
; #define PG8_STAGE(bufoff, gbase, voff) do { _Pragma("unroll") for (int _i = 0; _i < 2; ++_i) \
;         __builtin_amdgcn_global_load_lds((const unsigned*)((const char*)(gbase) + (voff)[_i]), (PG8_LAS unsigned*)(lds + (bufoff) + ldsw + _i * 8192), 16, 0, 0); } while (0)
; #define PG8_LDA(dst, b, h) do { _Pragma("unroll") for (int m = 0; m < 4; ++m) _Pragma("unroll") for (int k = 0; k < 2; ++k) dst[m][k] = *(const PG8_LAS bf16x8*)(lds + PG8_SA(b, h) + aoff + m * 2048 + k * 1024); } while (0)
; #define PG8_MMA(ai, bj, At, Bt) do { __builtin_amdgcn_s_setprio(1); _Pragma("unroll") for (int m = 0; m < 4; ++m) _Pragma("unroll") for (int n = 0; n < 2; ++n) _Pragma("unroll") for (int k = 0; k < 2; ++k) \
;         acc[ai][bj][m][n] = __builtin_amdgcn_mfma_f32_16x16x32_bf16(Bt[n][k], At[m][k], acc[ai][bj][m][n], 0, 0, 0); __builtin_amdgcn_s_setprio(0); } while (0)
; #define PG8_WAIT_V(n) asm volatile("s_waitcnt vmcnt(" #n ")" ::: "memory")
; #define PG8_WAIT_L(n) asm volatile("s_waitcnt lgkmcnt(" #n ")" ::: "memory")
; #define PG8_BAR __builtin_amdgcn_s_barrier()
; #define PG8_SCHED __builtin_amdgcn_sched_barrier(0)
; template <class Epi, class Sched, bool ALIGN_EPI = false, bool SP2 = false>
; __device__ __forceinline__ void gemm_phase(PG8_LAS unsigned char* lds, const Gemm g, const Sched& S, const Epi& E, const int tid_in) {
;     ...
;         for (int t = 0; t < nt; t += 2) {
;             const bool last = (t == nt - 2);
;             const char* a1 = cA + (size_t)(t + 1) * kstep;
;             const char* a2 = last ? nA : cA + (size_t)(t + 2) * kstep; const char* b2 = last ? nB : cB + (size_t)(t + 2) * kstep;
;     ...
;             PG8_LDA(At, 1, 1); PG8_STAGE(PG8_SB(1, 0), b3, voffB); PG8_STAGE(PG8_SB(1, 1), b3 + hstep, voffB); PG8_STAGE(PG8_SA(1, 0), a3, voffA);
;             PG8_WAIT_V(8); PG8_WAIT_L(0); PG8_BAR; PG8_MMA(1, 0, At, B0); PG8_MMA(1, 1, At, B1); PG8_BAR; PG8_SCHED;
	s_add_i32 s40, s74, s51
	v_lshl_add_u64 v[144:145], v[144:145], 0, s[16:17]
	s_mov_b32 m0, s40
	ds_read_b128 v[206:209], v172 offset:49152
	ds_read_b128 v[210:213], v172 offset:50176
	ds_read_b128 v[214:217], v172 offset:51200
	ds_read_b128 v[218:221], v172 offset:52224
	ds_read_b128 v[222:225], v172 offset:53248
	ds_read_b128 v[226:229], v172 offset:54272
	ds_read_b128 v[230:233], v172 offset:55296
	ds_read_b128 v[234:237], v172 offset:56320
	global_load_lds_dwordx4 v[144:145], off
	s_add_i32 m0, s40, 0x2000
	s_add_u32 s38, s38, 0x40080
	v_lshl_add_u64 v[144:145], v[238:239], 0, s[16:17]
	s_addc_u32 s39, s39, 0
	s_add_i32 s40, s75, s51
	global_load_lds_dwordx4 v[144:145], off
	v_lshl_add_u64 v[144:145], s[38:39], 0, v[132:133]
	s_mov_b32 m0, s40
	s_nop 0
	global_load_lds_dwordx4 v[144:145], off
	v_lshl_add_u64 v[144:145], s[38:39], 0, v[128:129]
	s_add_i32 m0, s40, 0x2000
	s_nop 0
	global_load_lds_dwordx4 v[144:145], off
	v_lshl_add_u64 v[144:145], v[240:241], 0, s[16:17]
	s_mov_b32 m0, s59
	s_nop 0
	global_load_lds_dwordx4 v[144:145], off
	v_lshl_add_u64 v[144:145], v[242:243], 0, s[16:17]
	s_mov_b32 m0, s60
	s_nop 0
	global_load_lds_dwordx4 v[144:145], off
	s_waitcnt vmcnt(8)
	s_waitcnt lgkmcnt(0)
	s_barrier
	s_waitcnt lgkmcnt(0)
	v_mfma_f32_16x16x32_bf16 v[60:63], v[174:177], v[206:209], v[60:63]
	v_mfma_f32_16x16x32_bf16 v[56:59], v[182:185], v[206:209], v[56:59]
	v_mfma_f32_16x16x32_bf16 v[52:55], v[174:177], v[214:217], v[52:55]
	v_mfma_f32_16x16x32_bf16 v[44:47], v[182:185], v[214:217], v[44:47]
	v_mfma_f32_16x16x32_bf16 v[36:39], v[174:177], v[222:225], v[36:39]
	v_mfma_f32_16x16x32_bf16 v[28:31], v[182:185], v[222:225], v[28:31]
	v_mfma_f32_16x16x32_bf16 v[20:23], v[174:177], v[230:233], v[20:23]
	v_mfma_f32_16x16x32_bf16 v[12:15], v[182:185], v[230:233], v[12:15]
	v_mfma_f32_16x16x32_bf16 v[60:63], v[178:181], v[210:213], v[60:63]
	v_mfma_f32_16x16x32_bf16 v[56:59], v[186:189], v[210:213], v[56:59]
	v_mfma_f32_16x16x32_bf16 v[52:55], v[178:181], v[218:221], v[52:55]
	v_mfma_f32_16x16x32_bf16 v[44:47], v[186:189], v[218:221], v[44:47]
	v_mfma_f32_16x16x32_bf16 v[36:39], v[178:181], v[226:229], v[36:39]
	v_mfma_f32_16x16x32_bf16 v[28:31], v[186:189], v[226:229], v[28:31]
	v_mfma_f32_16x16x32_bf16 v[20:23], v[178:181], v[234:237], v[20:23]
	v_mfma_f32_16x16x32_bf16 v[12:15], v[186:189], v[234:237], v[12:15]
	v_mfma_f32_16x16x32_bf16 v[48:51], v[190:193], v[206:209], v[48:51]
	v_mfma_f32_16x16x32_bf16 v[40:43], v[198:201], v[206:209], v[40:43]
	v_mfma_f32_16x16x32_bf16 v[32:35], v[190:193], v[214:217], v[32:35]
	v_mfma_f32_16x16x32_bf16 v[24:27], v[198:201], v[214:217], v[24:27]
	v_mfma_f32_16x16x32_bf16 v[16:19], v[190:193], v[222:225], v[16:19]
	v_mfma_f32_16x16x32_bf16 v[8:11], v[198:201], v[222:225], v[8:11]
	v_mfma_f32_16x16x32_bf16 v[4:7], v[190:193], v[230:233], v[4:7]
	v_mfma_f32_16x16x32_bf16 v[0:3], v[198:201], v[230:233], v[0:3]
	v_mfma_f32_16x16x32_bf16 v[48:51], v[194:197], v[210:213], v[48:51]
	v_mfma_f32_16x16x32_bf16 v[40:43], v[202:205], v[210:213], v[40:43]
	v_mfma_f32_16x16x32_bf16 v[32:35], v[194:197], v[218:221], v[32:35]
	v_mfma_f32_16x16x32_bf16 v[24:27], v[202:205], v[218:221], v[24:27]
	v_mfma_f32_16x16x32_bf16 v[16:19], v[194:197], v[226:229], v[16:19]
	v_mfma_f32_16x16x32_bf16 v[8:11], v[202:205], v[226:229], v[8:11]
	v_mfma_f32_16x16x32_bf16 v[4:7], v[194:197], v[234:237], v[4:7]
	v_mfma_f32_16x16x32_bf16 v[0:3], v[202:205], v[234:237], v[0:3]
	s_add_i32 s73, s73, 2
	s_add_u32 s0, s0, 0x100
	s_addc_u32 s1, s1, 0
	s_add_u32 s71, s71, 0x100
	s_addc_u32 s72, s72, 0
	s_cmp_gt_u32 s73, 13
	s_barrier
	s_cbranch_scc0 .LBB0_535
	s_and_b64 vcc, exec, s[18:19]
	s_cbranch_vccz .LBB0_538
	s_barrier

; #define PG8_STAGE(bufoff, gbase, voff) do { _Pragma("unroll") for (int _i = 0; _i < 2; ++_i) \
;         __builtin_amdgcn_global_load_lds((const unsigned*)((const char*)(gbase) + (voff)[_i]), (PG8_LAS unsigned*)(lds + (bufoff) + ldsw + _i * 8192), 16, 0, 0); } while (0)
; #define PG8_LDA(dst, b, h) do { _Pragma("unroll") for (int m = 0; m < 4; ++m) _Pragma("unroll") for (int k = 0; k < 2; ++k) dst[m][k] = *(const PG8_LAS bf16x8*)(lds + PG8_SA(b, h) + aoff + m * 2048 + k * 1024); } while (0)
; #define PG8_LDB(dst, b, h) do { _Pragma("unroll") for (int n = 0; n < 2; ++n) _Pragma("unroll") for (int k = 0; k < 2; ++k) dst[n][k] = *(const PG8_LAS bf16x8*)(lds + PG8_SB(b, h) + boff + n * 2048 + k * 1024); } while (0)
; #define PG8_MMA(ai, bj, At, Bt) do { __builtin_amdgcn_s_setprio(1); _Pragma("unroll") for (int m = 0; m < 4; ++m) _Pragma("unroll") for (int n = 0; n < 2; ++n) _Pragma("unroll") for (int k = 0; k < 2; ++k) \
;         acc[ai][bj][m][n] = __builtin_amdgcn_mfma_f32_16x16x32_bf16(Bt[n][k], At[m][k], acc[ai][bj][m][n], 0, 0, 0); __builtin_amdgcn_s_setprio(0); } while (0)
; #define PG8_WAIT_V(n) asm volatile("s_waitcnt vmcnt(" #n ")" ::: "memory")
; #define PG8_WAIT_L(n) asm volatile("s_waitcnt lgkmcnt(" #n ")" ::: "memory")
; #define PG8_BAR __builtin_amdgcn_s_barrier()
; #define PG8_SCHED __builtin_amdgcn_sched_barrier(0)
; template <class Epi, class Sched, bool ALIGN_EPI = false, bool SP2 = false>
; __device__ __forceinline__ void gemm_phase(PG8_LAS unsigned char* lds, const Gemm g, const Sched& S, const Epi& E, const int tid_in) {
;     ...
;             PG8_LDB(B0, 0, 0); PG8_LDB(B1, 0, 1); PG8_SCHED; PG8_LDA(At, 0, 0); PG8_STAGE(PG8_SA(1, 1), a1 + hstep, voffA);
;             PG8_WAIT_V(8); PG8_WAIT_L(0); PG8_BAR; PG8_MMA(0, 0, At, B0); PG8_MMA(0, 1, At, B1); PG8_BAR; PG8_SCHED;
;             PG8_LDA(At, 0, 1); PG8_STAGE(PG8_SB(0, 0), b2, voffB); PG8_STAGE(PG8_SB(0, 1), b2 + hstep, voffB); PG8_STAGE(PG8_SA(0, 0), a2, voffA);
;             PG8_WAIT_V(8); PG8_WAIT_L(0); PG8_BAR; PG8_MMA(1, 0, At, B0); PG8_MMA(1, 1, At, B1); PG8_BAR; PG8_SCHED;
.LBB0_555:
	ds_read_b128 v[158:161], v146
	ds_read_b128 v[162:165], v146 offset:1024
	ds_read_b128 v[166:169], v146 offset:2048
	ds_read_b128 v[170:173], v146 offset:3072
	ds_read_b128 v[174:177], v147
	ds_read_b128 v[178:181], v147 offset:1024
	ds_read_b128 v[182:185], v147 offset:2048
	ds_read_b128 v[186:189], v147 offset:3072
	s_add_u32 s34, s0, 0xfffc0080
	s_addc_u32 s35, s1, -1
	s_cmp_eq_u32 s61, 12
	s_cselect_b32 s37, s27, s35
	s_cselect_b32 s36, s26, s34
	s_cselect_b32 s35, s23, s60
	s_cselect_b32 s34, s25, s59
	v_lshl_add_u64 v[144:145], s[0:1], 0, v[136:137]
	s_add_i32 m0, s31, 0xc000
	ds_read_b128 v[190:193], v148
	ds_read_b128 v[194:197], v148 offset:1024
	ds_read_b128 v[198:201], v148 offset:2048
	ds_read_b128 v[202:205], v148 offset:3072
	ds_read_b128 v[206:209], v148 offset:4096
	ds_read_b128 v[210:213], v148 offset:5120
	ds_read_b128 v[214:217], v148 offset:6144
	ds_read_b128 v[218:221], v148 offset:7168
	global_load_lds_dwordx4 v[144:145], off
	v_lshl_add_u64 v[144:145], s[0:1], 0, v[138:139]
	s_add_i32 m0, s31, 0xe000
	s_nop 0
	global_load_lds_dwordx4 v[144:145], off
	s_waitcnt vmcnt(8)
	s_waitcnt lgkmcnt(0)
	s_barrier
	s_waitcnt lgkmcnt(0)
	v_mfma_f32_16x16x32_bf16 v[124:127], v[158:161], v[190:193], v[124:127]
	v_mfma_f32_16x16x32_bf16 v[120:123], v[166:169], v[190:193], v[120:123]
	v_mfma_f32_16x16x32_bf16 v[116:119], v[158:161], v[198:201], v[116:119]
	v_mfma_f32_16x16x32_bf16 v[108:111], v[166:169], v[198:201], v[108:111]
	v_mfma_f32_16x16x32_bf16 v[100:103], v[158:161], v[206:209], v[100:103]
	v_mfma_f32_16x16x32_bf16 v[92:95], v[166:169], v[206:209], v[92:95]
	v_mfma_f32_16x16x32_bf16 v[84:87], v[158:161], v[214:217], v[84:87]
	v_mfma_f32_16x16x32_bf16 v[76:79], v[166:169], v[214:217], v[76:79]
	v_mfma_f32_16x16x32_bf16 v[124:127], v[162:165], v[194:197], v[124:127]
	v_mfma_f32_16x16x32_bf16 v[120:123], v[170:173], v[194:197], v[120:123]
	v_mfma_f32_16x16x32_bf16 v[116:119], v[162:165], v[202:205], v[116:119]
	v_mfma_f32_16x16x32_bf16 v[108:111], v[170:173], v[202:205], v[108:111]
	v_mfma_f32_16x16x32_bf16 v[100:103], v[162:165], v[210:213], v[100:103]
	v_mfma_f32_16x16x32_bf16 v[92:95], v[170:173], v[210:213], v[92:95]
	v_mfma_f32_16x16x32_bf16 v[84:87], v[162:165], v[218:221], v[84:87]
	v_mfma_f32_16x16x32_bf16 v[76:79], v[170:173], v[218:221], v[76:79]
	v_mfma_f32_16x16x32_bf16 v[112:115], v[174:177], v[190:193], v[112:115]
	v_mfma_f32_16x16x32_bf16 v[104:107], v[182:185], v[190:193], v[104:107]
	v_mfma_f32_16x16x32_bf16 v[96:99], v[174:177], v[198:201], v[96:99]
	v_mfma_f32_16x16x32_bf16 v[88:91], v[182:185], v[198:201], v[88:91]
	v_mfma_f32_16x16x32_bf16 v[80:83], v[174:177], v[206:209], v[80:83]
	v_mfma_f32_16x16x32_bf16 v[72:75], v[182:185], v[206:209], v[72:75]
	v_mfma_f32_16x16x32_bf16 v[68:71], v[174:177], v[214:217], v[68:71]
	v_mfma_f32_16x16x32_bf16 v[64:67], v[182:185], v[214:217], v[64:67]
	v_mfma_f32_16x16x32_bf16 v[112:115], v[178:181], v[194:197], v[112:115]
	v_mfma_f32_16x16x32_bf16 v[104:107], v[186:189], v[194:197], v[104:107]
	v_mfma_f32_16x16x32_bf16 v[96:99], v[178:181], v[202:205], v[96:99]
	v_mfma_f32_16x16x32_bf16 v[88:91], v[186:189], v[202:205], v[88:91]
	v_mfma_f32_16x16x32_bf16 v[80:83], v[178:181], v[210:213], v[80:83]
	v_mfma_f32_16x16x32_bf16 v[72:75], v[186:189], v[210:213], v[72:75]
	v_mfma_f32_16x16x32_bf16 v[68:71], v[178:181], v[218:221], v[68:71]
	v_mfma_f32_16x16x32_bf16 v[64:67], v[186:189], v[218:221], v[64:67]
	s_barrier
	s_add_i32 s62, s56, s45
	v_lshl_add_u64 v[144:145], s[34:35], 0, v[132:133]
	s_mov_b32 m0, s62
	ds_read_b128 v[190:193], v148 offset:16384
	ds_read_b128 v[194:197], v148 offset:17408
	ds_read_b128 v[198:201], v148 offset:18432
	ds_read_b128 v[202:205], v148 offset:19456
	ds_read_b128 v[206:209], v148 offset:20480
	ds_read_b128 v[210:213], v148 offset:21504
	ds_read_b128 v[214:217], v148 offset:22528
	ds_read_b128 v[218:221], v148 offset:23552
	global_load_lds_dwordx4 v[144:145], off
	s_add_i32 m0, s62, 0x2000
	s_add_u32 s62, s34, 0x40000
	v_lshl_add_u64 v[150:151], s[34:35], 0, v[128:129]
	s_addc_u32 s63, s35, 0
	s_add_i32 s64, s57, s45
	global_load_lds_dwordx4 v[150:151], off
	v_lshl_add_u64 v[154:155], s[62:63], 0, v[132:133]
	s_mov_b32 m0, s64
	v_lshl_add_u64 v[222:223], s[36:37], 0, v[130:131]
	global_load_lds_dwordx4 v[154:155], off
	v_lshl_add_u64 v[154:155], s[62:63], 0, v[128:129]
	s_add_i32 m0, s64, 0x2000
	s_nop 0
	global_load_lds_dwordx4 v[154:155], off
	v_lshl_add_u64 v[154:155], s[36:37], 0, v[134:135]
	s_mov_b32 m0, s31
	s_nop 0
	global_load_lds_dwordx4 v[154:155], off
	s_mov_b32 m0, s43
	s_nop 0
	global_load_lds_dwordx4 v[222:223], off
	s_waitcnt vmcnt(8)
	s_waitcnt lgkmcnt(0)
	s_barrier
; #define PG8_STAGE(bufoff, gbase, voff) do { _Pragma("unroll") for (int _i = 0; _i < 2; ++_i) \
;         __builtin_amdgcn_global_load_lds((const unsigned*)((const char*)(gbase) + (voff)[_i]), (PG8_LAS unsigned*)(lds + (bufoff) + ldsw + _i * 8192), 16, 0, 0); } while (0)
; #define PG8_LDA(dst, b, h) do { _Pragma("unroll") for (int m = 0; m < 4; ++m) _Pragma("unroll") for (int k = 0; k < 2; ++k) dst[m][k] = *(const PG8_LAS bf16x8*)(lds + PG8_SA(b, h) + aoff + m * 2048 + k * 1024); } while (0)
; #define PG8_LDB(dst, b, h) do { _Pragma("unroll") for (int n = 0; n < 2; ++n) _Pragma("unroll") for (int k = 0; k < 2; ++k) dst[n][k] = *(const PG8_LAS bf16x8*)(lds + PG8_SB(b, h) + boff + n * 2048 + k * 1024); } while (0)
; #define PG8_MMA(ai, bj, At, Bt) do { __builtin_amdgcn_s_setprio(1); _Pragma("unroll") for (int m = 0; m < 4; ++m) _Pragma("unroll") for (int n = 0; n < 2; ++n) _Pragma("unroll") for (int k = 0; k < 2; ++k) \
;         acc[ai][bj][m][n] = __builtin_amdgcn_mfma_f32_16x16x32_bf16(Bt[n][k], At[m][k], acc[ai][bj][m][n], 0, 0, 0); __builtin_amdgcn_s_setprio(0); } while (0)
; #define PG8_BAR __builtin_amdgcn_s_barrier()
; template <class Epi, class Sched, bool ALIGN_EPI = false, bool SP2 = false>
; __device__ __forceinline__ void gemm_phase(PG8_LAS unsigned char* lds, const Gemm g, const Sched& S, const Epi& E, const int tid_in) {
;     ...
;             PG8_LDB(B0, 0, 0); PG8_LDB(B1, 0, 1); PG8_SCHED; PG8_LDA(At, 0, 0); PG8_STAGE(PG8_SA(1, 1), a1 + hstep, voffA);
;             PG8_WAIT_V(8); PG8_WAIT_L(0); PG8_BAR; PG8_MMA(0, 0, At, B0); PG8_MMA(0, 1, At, B1); PG8_BAR; PG8_SCHED;
;             PG8_LDA(At, 0, 1); PG8_STAGE(PG8_SB(0, 0), b2, voffB); PG8_STAGE(PG8_SB(0, 1), b2 + hstep, voffB); PG8_STAGE(PG8_SA(0, 0), a2, voffA);
;             PG8_WAIT_V(8); PG8_WAIT_L(0); PG8_BAR; PG8_MMA(1, 0, At, B0); PG8_MMA(1, 1, At, B1); PG8_BAR; PG8_SCHED;
;             PG8_LDB(B0, 1, 0); PG8_LDB(B1, 1, 1); PG8_SCHED; PG8_LDA(At, 1, 0); PG8_STAGE(PG8_SA(0, 1), a2 + hstep, voffA);
;             PG8_WAIT_V(8); PG8_WAIT_L(0); PG8_BAR; PG8_MMA(0, 0, At, B0); PG8_MMA(0, 1, At, B1); PG8_BAR; PG8_SCHED;
;             PG8_LDA(At, 1, 1); PG8_STAGE(PG8_SB(1, 0), b3, voffB); PG8_STAGE(PG8_SB(1, 1), b3 + hstep, voffB); PG8_STAGE(PG8_SA(1, 0), a3, voffA);
;             PG8_WAIT_V(8); PG8_WAIT_L(0); PG8_BAR; PG8_MMA(1, 0, At, B0); PG8_MMA(1, 1, At, B1); PG8_BAR; PG8_SCHED;
	s_waitcnt lgkmcnt(0)
	v_mfma_f32_16x16x32_bf16 v[60:63], v[158:161], v[190:193], v[60:63]
	v_mfma_f32_16x16x32_bf16 v[56:59], v[166:169], v[190:193], v[56:59]
	v_mfma_f32_16x16x32_bf16 v[52:55], v[158:161], v[198:201], v[52:55]
	v_mfma_f32_16x16x32_bf16 v[44:47], v[166:169], v[198:201], v[44:47]
	v_mfma_f32_16x16x32_bf16 v[36:39], v[158:161], v[206:209], v[36:39]
	v_mfma_f32_16x16x32_bf16 v[28:31], v[166:169], v[206:209], v[28:31]
	v_mfma_f32_16x16x32_bf16 v[20:23], v[158:161], v[214:217], v[20:23]
	v_mfma_f32_16x16x32_bf16 v[12:15], v[166:169], v[214:217], v[12:15]
	v_mfma_f32_16x16x32_bf16 v[60:63], v[162:165], v[194:197], v[60:63]
	v_mfma_f32_16x16x32_bf16 v[56:59], v[170:173], v[194:197], v[56:59]
	v_mfma_f32_16x16x32_bf16 v[52:55], v[162:165], v[202:205], v[52:55]
	v_mfma_f32_16x16x32_bf16 v[44:47], v[170:173], v[202:205], v[44:47]
	v_mfma_f32_16x16x32_bf16 v[36:39], v[162:165], v[210:213], v[36:39]
	v_mfma_f32_16x16x32_bf16 v[28:31], v[170:173], v[210:213], v[28:31]
	v_mfma_f32_16x16x32_bf16 v[20:23], v[162:165], v[218:221], v[20:23]
	v_mfma_f32_16x16x32_bf16 v[12:15], v[170:173], v[218:221], v[12:15]
	v_mfma_f32_16x16x32_bf16 v[48:51], v[174:177], v[190:193], v[48:51]
	v_mfma_f32_16x16x32_bf16 v[40:43], v[182:185], v[190:193], v[40:43]
	v_mfma_f32_16x16x32_bf16 v[32:35], v[174:177], v[198:201], v[32:35]
	v_mfma_f32_16x16x32_bf16 v[24:27], v[182:185], v[198:201], v[24:27]
	v_mfma_f32_16x16x32_bf16 v[16:19], v[174:177], v[206:209], v[16:19]
	v_mfma_f32_16x16x32_bf16 v[8:11], v[182:185], v[206:209], v[8:11]
	v_mfma_f32_16x16x32_bf16 v[4:7], v[174:177], v[214:217], v[4:7]
	v_mfma_f32_16x16x32_bf16 v[0:3], v[182:185], v[214:217], v[0:3]
	v_mfma_f32_16x16x32_bf16 v[48:51], v[178:181], v[194:197], v[48:51]
	v_mfma_f32_16x16x32_bf16 v[40:43], v[186:189], v[194:197], v[40:43]
	v_mfma_f32_16x16x32_bf16 v[32:35], v[178:181], v[202:205], v[32:35]
	v_mfma_f32_16x16x32_bf16 v[24:27], v[186:189], v[202:205], v[24:27]
	v_mfma_f32_16x16x32_bf16 v[16:19], v[178:181], v[210:213], v[16:19]
	v_mfma_f32_16x16x32_bf16 v[8:11], v[186:189], v[210:213], v[8:11]
	v_mfma_f32_16x16x32_bf16 v[4:7], v[178:181], v[218:221], v[4:7]
	v_mfma_f32_16x16x32_bf16 v[0:3], v[186:189], v[218:221], v[0:3]
	s_barrier
	s_add_i32 s62, 0, 0x18000
	v_add_u32_e32 v149, s62, v153
	s_add_i32 s63, 0, 0x1c000
	ds_read_b128 v[158:161], v149
	ds_read_b128 v[162:165], v149 offset:1024
	ds_read_b128 v[166:169], v149 offset:2048
	ds_read_b128 v[170:173], v149 offset:3072
	v_add_u32_e32 v149, s63, v153
	ds_read_b128 v[174:177], v149
	ds_read_b128 v[178:181], v149 offset:1024
	ds_read_b128 v[182:185], v149 offset:2048
	ds_read_b128 v[186:189], v149 offset:3072
	s_add_u32 s36, s36, 0x40000
	s_addc_u32 s37, s37, 0
	s_mov_b32 m0, s44
	v_lshl_add_u64 v[224:225], s[36:37], 0, v[134:135]
	ds_read_b128 v[190:193], v148 offset:32768
	ds_read_b128 v[194:197], v148 offset:33792
	ds_read_b128 v[198:201], v148 offset:34816
	ds_read_b128 v[202:205], v148 offset:35840
	ds_read_b128 v[206:209], v148 offset:36864
	ds_read_b128 v[210:213], v148 offset:37888
	ds_read_b128 v[214:217], v148 offset:38912
	ds_read_b128 v[218:221], v148 offset:39936
	global_load_lds_dwordx4 v[224:225], off
	v_lshl_add_u64 v[224:225], s[36:37], 0, v[130:131]
	s_mov_b32 m0, s46
	s_nop 0
	global_load_lds_dwordx4 v[224:225], off
	s_waitcnt vmcnt(8)
	s_waitcnt lgkmcnt(0)
	s_barrier
	s_waitcnt lgkmcnt(0)
	v_mfma_f32_16x16x32_bf16 v[124:127], v[158:161], v[190:193], v[124:127]
	v_mfma_f32_16x16x32_bf16 v[120:123], v[166:169], v[190:193], v[120:123]
	v_mfma_f32_16x16x32_bf16 v[116:119], v[158:161], v[198:201], v[116:119]
	v_mfma_f32_16x16x32_bf16 v[108:111], v[166:169], v[198:201], v[108:111]
	v_mfma_f32_16x16x32_bf16 v[100:103], v[158:161], v[206:209], v[100:103]
	v_mfma_f32_16x16x32_bf16 v[92:95], v[166:169], v[206:209], v[92:95]
	v_mfma_f32_16x16x32_bf16 v[84:87], v[158:161], v[214:217], v[84:87]
	v_mfma_f32_16x16x32_bf16 v[76:79], v[166:169], v[214:217], v[76:79]
	v_mfma_f32_16x16x32_bf16 v[124:127], v[162:165], v[194:197], v[124:127]
	v_mfma_f32_16x16x32_bf16 v[120:123], v[170:173], v[194:197], v[120:123]
	v_mfma_f32_16x16x32_bf16 v[116:119], v[162:165], v[202:205], v[116:119]
	v_mfma_f32_16x16x32_bf16 v[108:111], v[170:173], v[202:205], v[108:111]
	v_mfma_f32_16x16x32_bf16 v[100:103], v[162:165], v[210:213], v[100:103]
	v_mfma_f32_16x16x32_bf16 v[92:95], v[170:173], v[210:213], v[92:95]
	v_mfma_f32_16x16x32_bf16 v[84:87], v[162:165], v[218:221], v[84:87]
	v_mfma_f32_16x16x32_bf16 v[76:79], v[170:173], v[218:221], v[76:79]
	v_mfma_f32_16x16x32_bf16 v[112:115], v[174:177], v[190:193], v[112:115]
	v_mfma_f32_16x16x32_bf16 v[104:107], v[182:185], v[190:193], v[104:107]
	v_mfma_f32_16x16x32_bf16 v[96:99], v[174:177], v[198:201], v[96:99]
	v_mfma_f32_16x16x32_bf16 v[88:91], v[182:185], v[198:201], v[88:91]
	v_mfma_f32_16x16x32_bf16 v[80:83], v[174:177], v[206:209], v[80:83]
	v_mfma_f32_16x16x32_bf16 v[72:75], v[182:185], v[206:209], v[72:75]
	v_mfma_f32_16x16x32_bf16 v[68:71], v[174:177], v[214:217], v[68:71]
	v_mfma_f32_16x16x32_bf16 v[64:67], v[182:185], v[214:217], v[64:67]
	v_mfma_f32_16x16x32_bf16 v[112:115], v[178:181], v[194:197], v[112:115]
	v_mfma_f32_16x16x32_bf16 v[104:107], v[186:189], v[194:197], v[104:107]
	v_mfma_f32_16x16x32_bf16 v[96:99], v[178:181], v[202:205], v[96:99]
	v_mfma_f32_16x16x32_bf16 v[88:91], v[186:189], v[202:205], v[88:91]
	v_mfma_f32_16x16x32_bf16 v[80:83], v[178:181], v[210:213], v[80:83]
	v_mfma_f32_16x16x32_bf16 v[72:75], v[186:189], v[210:213], v[72:75]
	v_mfma_f32_16x16x32_bf16 v[68:71], v[178:181], v[218:221], v[68:71]
	v_mfma_f32_16x16x32_bf16 v[64:67], v[186:189], v[218:221], v[64:67]
	s_barrier
; #define PG8_STAGE(bufoff, gbase, voff) do { _Pragma("unroll") for (int _i = 0; _i < 2; ++_i) \
;         __builtin_amdgcn_global_load_lds((const unsigned*)((const char*)(gbase) + (voff)[_i]), (PG8_LAS unsigned*)(lds + (bufoff) + ldsw + _i * 8192), 16, 0, 0); } while (0)
; #define PG8_LDA(dst, b, h) do { _Pragma("unroll") for (int m = 0; m < 4; ++m) _Pragma("unroll") for (int k = 0; k < 2; ++k) dst[m][k] = *(const PG8_LAS bf16x8*)(lds + PG8_SA(b, h) + aoff + m * 2048 + k * 1024); } while (0)
; #define PG8_MMA(ai, bj, At, Bt) do { __builtin_amdgcn_s_setprio(1); _Pragma("unroll") for (int m = 0; m < 4; ++m) _Pragma("unroll") for (int n = 0; n < 2; ++n) _Pragma("unroll") for (int k = 0; k < 2; ++k) \
;         acc[ai][bj][m][n] = __builtin_amdgcn_mfma_f32_16x16x32_bf16(Bt[n][k], At[m][k], acc[ai][bj][m][n], 0, 0, 0); __builtin_amdgcn_s_setprio(0); } while (0)
; #define PG8_WAIT_V(n) asm volatile("s_waitcnt vmcnt(" #n ")" ::: "memory")
; #define PG8_WAIT_L(n) asm volatile("s_waitcnt lgkmcnt(" #n ")" ::: "memory")
; #define PG8_BAR __builtin_amdgcn_s_barrier()
; #define PG8_SCHED __builtin_amdgcn_sched_barrier(0)
; template <class Epi, class Sched, bool ALIGN_EPI = false, bool SP2 = false>
; __device__ __forceinline__ void gemm_phase(PG8_LAS unsigned char* lds, const Gemm g, const Sched& S, const Epi& E, const int tid_in) {
;     ...
;         for (int t = 0; t < nt; t += 2) {
;             const bool last = (t == nt - 2);
;             const char* a1 = cA + (size_t)(t + 1) * kstep;
;             const char* a2 = last ? nA : cA + (size_t)(t + 2) * kstep; const char* b2 = last ? nB : cB + (size_t)(t + 2) * kstep;
;             const char* a3 = a2 + kstep; const char* b3 = b2 + kstep;
;             if (last && has_next) S.a_ready(nxt);
;     ...
;             PG8_LDA(At, 1, 1); PG8_STAGE(PG8_SB(1, 0), b3, voffB); PG8_STAGE(PG8_SB(1, 1), b3 + hstep, voffB); PG8_STAGE(PG8_SA(1, 0), a3, voffA);
;             PG8_WAIT_V(8); PG8_WAIT_L(0); PG8_BAR; PG8_MMA(1, 0, At, B0); PG8_MMA(1, 1, At, B1); PG8_BAR; PG8_SCHED;
	s_add_i32 s36, s62, s45
	v_lshl_add_u64 v[144:145], v[144:145], 0, s[10:11]
	s_mov_b32 m0, s36
	ds_read_b128 v[190:193], v148 offset:49152
	ds_read_b128 v[194:197], v148 offset:50176
	ds_read_b128 v[198:201], v148 offset:51200
	ds_read_b128 v[202:205], v148 offset:52224
	ds_read_b128 v[206:209], v148 offset:53248
	ds_read_b128 v[210:213], v148 offset:54272
	ds_read_b128 v[214:217], v148 offset:55296
	ds_read_b128 v[218:221], v148 offset:56320
	global_load_lds_dwordx4 v[144:145], off
	s_add_i32 m0, s36, 0x2000
	s_add_u32 s34, s34, 0x40080
	v_lshl_add_u64 v[144:145], v[150:151], 0, s[10:11]
	s_addc_u32 s35, s35, 0
	s_add_i32 s36, s63, s45
	global_load_lds_dwordx4 v[144:145], off
	v_lshl_add_u64 v[144:145], s[34:35], 0, v[132:133]
	s_mov_b32 m0, s36
	s_nop 0
	global_load_lds_dwordx4 v[144:145], off
	v_lshl_add_u64 v[144:145], s[34:35], 0, v[128:129]
	s_add_i32 m0, s36, 0x2000
	s_nop 0
	global_load_lds_dwordx4 v[144:145], off
	v_lshl_add_u64 v[144:145], v[154:155], 0, s[10:11]
	s_mov_b32 m0, s52
	s_nop 0
	global_load_lds_dwordx4 v[144:145], off
	v_lshl_add_u64 v[144:145], v[222:223], 0, s[10:11]
	s_mov_b32 m0, s53
	s_nop 0
	global_load_lds_dwordx4 v[144:145], off
	s_waitcnt vmcnt(8)
	s_waitcnt lgkmcnt(0)
	s_barrier
	s_waitcnt lgkmcnt(0)
	v_mfma_f32_16x16x32_bf16 v[60:63], v[158:161], v[190:193], v[60:63]
	v_mfma_f32_16x16x32_bf16 v[56:59], v[166:169], v[190:193], v[56:59]
	v_mfma_f32_16x16x32_bf16 v[52:55], v[158:161], v[198:201], v[52:55]
	v_mfma_f32_16x16x32_bf16 v[44:47], v[166:169], v[198:201], v[44:47]
	v_mfma_f32_16x16x32_bf16 v[36:39], v[158:161], v[206:209], v[36:39]
	v_mfma_f32_16x16x32_bf16 v[28:31], v[166:169], v[206:209], v[28:31]
	v_mfma_f32_16x16x32_bf16 v[20:23], v[158:161], v[214:217], v[20:23]
	v_mfma_f32_16x16x32_bf16 v[12:15], v[166:169], v[214:217], v[12:15]
	v_mfma_f32_16x16x32_bf16 v[60:63], v[162:165], v[194:197], v[60:63]
	v_mfma_f32_16x16x32_bf16 v[56:59], v[170:173], v[194:197], v[56:59]
	v_mfma_f32_16x16x32_bf16 v[52:55], v[162:165], v[202:205], v[52:55]
	v_mfma_f32_16x16x32_bf16 v[44:47], v[170:173], v[202:205], v[44:47]
	v_mfma_f32_16x16x32_bf16 v[36:39], v[162:165], v[210:213], v[36:39]
	v_mfma_f32_16x16x32_bf16 v[28:31], v[170:173], v[210:213], v[28:31]
	v_mfma_f32_16x16x32_bf16 v[20:23], v[162:165], v[218:221], v[20:23]
	v_mfma_f32_16x16x32_bf16 v[12:15], v[170:173], v[218:221], v[12:15]
	v_mfma_f32_16x16x32_bf16 v[48:51], v[174:177], v[190:193], v[48:51]
	v_mfma_f32_16x16x32_bf16 v[40:43], v[182:185], v[190:193], v[40:43]
	v_mfma_f32_16x16x32_bf16 v[32:35], v[174:177], v[198:201], v[32:35]
	v_mfma_f32_16x16x32_bf16 v[24:27], v[182:185], v[198:201], v[24:27]
	v_mfma_f32_16x16x32_bf16 v[16:19], v[174:177], v[206:209], v[16:19]
	v_mfma_f32_16x16x32_bf16 v[8:11], v[182:185], v[206:209], v[8:11]
	v_mfma_f32_16x16x32_bf16 v[4:7], v[174:177], v[214:217], v[4:7]
	v_mfma_f32_16x16x32_bf16 v[0:3], v[182:185], v[214:217], v[0:3]
	v_mfma_f32_16x16x32_bf16 v[48:51], v[178:181], v[194:197], v[48:51]
	v_mfma_f32_16x16x32_bf16 v[40:43], v[186:189], v[194:197], v[40:43]
	v_mfma_f32_16x16x32_bf16 v[32:35], v[178:181], v[202:205], v[32:35]
	v_mfma_f32_16x16x32_bf16 v[24:27], v[186:189], v[202:205], v[24:27]
	v_mfma_f32_16x16x32_bf16 v[16:19], v[178:181], v[210:213], v[16:19]
	v_mfma_f32_16x16x32_bf16 v[8:11], v[186:189], v[210:213], v[8:11]
	v_mfma_f32_16x16x32_bf16 v[4:7], v[178:181], v[218:221], v[4:7]
	v_mfma_f32_16x16x32_bf16 v[0:3], v[186:189], v[218:221], v[0:3]
	s_add_i32 s61, s61, 2
	s_add_u32 s0, s0, 0x100
	s_addc_u32 s1, s1, 0
	s_add_u32 s59, s59, 0x100
	s_addc_u32 s60, s60, 0
	s_cmp_gt_u32 s61, 13
	s_barrier
	s_cbranch_scc0 .LBB0_555
	s_and_b64 vcc, exec, s[12:13]
	s_cbranch_vccz .LBB0_558
	s_barrier

; #define PG8_STAGE(bufoff, gbase, voff) do { _Pragma("unroll") for (int _i = 0; _i < 2; ++_i) \
;         __builtin_amdgcn_global_load_lds((const unsigned*)((const char*)(gbase) + (voff)[_i]), (PG8_LAS unsigned*)(lds + (bufoff) + ldsw + _i * 8192), 16, 0, 0); } while (0)
; #define PG8_LDA(dst, b, h) do { _Pragma("unroll") for (int m = 0; m < 4; ++m) _Pragma("unroll") for (int k = 0; k < 2; ++k) dst[m][k] = *(const PG8_LAS bf16x8*)(lds + PG8_SA(b, h) + aoff + m * 2048 + k * 1024); } while (0)
; #define PG8_LDB(dst, b, h) do { _Pragma("unroll") for (int n = 0; n < 2; ++n) _Pragma("unroll") for (int k = 0; k < 2; ++k) dst[n][k] = *(const PG8_LAS bf16x8*)(lds + PG8_SB(b, h) + boff + n * 2048 + k * 1024); } while (0)
; #define PG8_WAIT_V(n) asm volatile("s_waitcnt vmcnt(" #n ")" ::: "memory")
; #define PG8_WAIT_L(n) asm volatile("s_waitcnt lgkmcnt(" #n ")" ::: "memory")
; #define PG8_BAR __builtin_amdgcn_s_barrier()
; #define PG8_SCHED __builtin_amdgcn_sched_barrier(0)
; template <class Epi, class Sched, bool ALIGN_EPI = false, bool SP2 = false>
; __device__ __forceinline__ void gemm_phase(PG8_LAS unsigned char* lds, const Gemm g, const Sched& S, const Epi& E, const int tid_in) {
;     ...
;         const char* nA = has_next ? (const char*)g.asel(nxt.pn) + (size_t)nxt.pm * tstep : cA; const char* nB = has_next ? (const char*)g.Bt + (size_t)nxt.pn * tstep : cB;
;         for (int t = 0; t < nt; t += 2) {
;             const bool last = (t == nt - 2);
;             const char* a1 = cA + (size_t)(t + 1) * kstep;
;             const char* a2 = last ? nA : cA + (size_t)(t + 2) * kstep; const char* b2 = last ? nB : cB + (size_t)(t + 2) * kstep;
;             const char* a3 = a2 + kstep; const char* b3 = b2 + kstep;
;             if (last && has_next) S.a_ready(nxt);
;             if constexpr (SP2) {
;             PG8_LDB(B0, 0, 0); PG8_LDB(B1, 0, 1); PG8_SCHED; PG8_LDA(At, 0, 0); PG8_STAGE(PG8_SA(1, 1), a1 + hstep, voffA);
;             PG8_WAIT_V(8); PG8_WAIT_L(0); PG8_BAR; PG8_MMA(0, 0, At, B0); PG8_MMA(0, 1, At, B1); PG8_BAR; PG8_SCHED;
;             PG8_LDA(At, 0, 1); PG8_STAGE(PG8_SB(0, 0), b2, voffB); PG8_STAGE(PG8_SB(0, 1), b2 + hstep, voffB); PG8_STAGE(PG8_SA(0, 0), a2, voffA);
;             PG8_WAIT_V(8); PG8_WAIT_L(0); PG8_BAR; PG8_MMA(1, 0, At, B0); PG8_MMA(1, 1, At, B1); PG8_BAR; PG8_SCHED;
.LBB0_739:
	ds_read_b128 v[152:155], v149
	ds_read_b128 v[156:159], v149 offset:1024
	ds_read_b128 v[160:163], v149 offset:2048
	ds_read_b128 v[164:167], v149 offset:3072
	ds_read_b128 v[168:171], v150
	ds_read_b128 v[172:175], v150 offset:1024
	ds_read_b128 v[176:179], v150 offset:2048
	ds_read_b128 v[180:183], v150 offset:3072
	s_add_u32 s30, s0, 0xfffc0080
	s_addc_u32 s31, s1, -1
	s_cmp_eq_u32 s68, 12
	s_cselect_b32 s35, s23, s31
	s_cselect_b32 s34, s64, s30
	s_cselect_b32 s31, s21, s67
	s_cselect_b32 s30, s65, s66
	v_lshl_add_u64 v[144:145], s[0:1], 0, v[136:137]
	s_add_i32 m0, s29, 0xc000
	ds_read_b128 v[184:187], v151
	ds_read_b128 v[188:191], v151 offset:1024
	ds_read_b128 v[192:195], v151 offset:2048
	ds_read_b128 v[196:199], v151 offset:3072
	ds_read_b128 v[200:203], v151 offset:4096
	ds_read_b128 v[204:207], v151 offset:5120
	ds_read_b128 v[208:211], v151 offset:6144
	ds_read_b128 v[212:215], v151 offset:7168
	global_load_lds_dwordx4 v[144:145], off
	v_lshl_add_u64 v[144:145], s[0:1], 0, v[138:139]
	s_add_i32 m0, s29, 0xe000
	s_nop 0
	global_load_lds_dwordx4 v[144:145], off
	s_waitcnt vmcnt(8)
	s_waitcnt lgkmcnt(0)
	s_barrier
	s_waitcnt lgkmcnt(0)
	v_mfma_f32_16x16x32_bf16 v[124:127], v[152:155], v[184:187], v[124:127]
	v_mfma_f32_16x16x32_bf16 v[120:123], v[160:163], v[184:187], v[120:123]
	v_mfma_f32_16x16x32_bf16 v[116:119], v[152:155], v[192:195], v[116:119]
	v_mfma_f32_16x16x32_bf16 v[108:111], v[160:163], v[192:195], v[108:111]
	v_mfma_f32_16x16x32_bf16 v[100:103], v[152:155], v[200:203], v[100:103]
	v_mfma_f32_16x16x32_bf16 v[92:95], v[160:163], v[200:203], v[92:95]
	v_mfma_f32_16x16x32_bf16 v[84:87], v[152:155], v[208:211], v[84:87]
	v_mfma_f32_16x16x32_bf16 v[76:79], v[160:163], v[208:211], v[76:79]
	v_mfma_f32_16x16x32_bf16 v[124:127], v[156:159], v[188:191], v[124:127]
	v_mfma_f32_16x16x32_bf16 v[120:123], v[164:167], v[188:191], v[120:123]
	v_mfma_f32_16x16x32_bf16 v[116:119], v[156:159], v[196:199], v[116:119]
	v_mfma_f32_16x16x32_bf16 v[108:111], v[164:167], v[196:199], v[108:111]
	v_mfma_f32_16x16x32_bf16 v[100:103], v[156:159], v[204:207], v[100:103]
	v_mfma_f32_16x16x32_bf16 v[92:95], v[164:167], v[204:207], v[92:95]
	v_mfma_f32_16x16x32_bf16 v[84:87], v[156:159], v[212:215], v[84:87]
	v_mfma_f32_16x16x32_bf16 v[76:79], v[164:167], v[212:215], v[76:79]
	v_mfma_f32_16x16x32_bf16 v[112:115], v[168:171], v[184:187], v[112:115]
	v_mfma_f32_16x16x32_bf16 v[104:107], v[176:179], v[184:187], v[104:107]
	v_mfma_f32_16x16x32_bf16 v[96:99], v[168:171], v[192:195], v[96:99]
	v_mfma_f32_16x16x32_bf16 v[88:91], v[176:179], v[192:195], v[88:91]
	v_mfma_f32_16x16x32_bf16 v[80:83], v[168:171], v[200:203], v[80:83]
	v_mfma_f32_16x16x32_bf16 v[72:75], v[176:179], v[200:203], v[72:75]
	v_mfma_f32_16x16x32_bf16 v[68:71], v[168:171], v[208:211], v[68:71]
	v_mfma_f32_16x16x32_bf16 v[64:67], v[176:179], v[208:211], v[64:67]
	v_mfma_f32_16x16x32_bf16 v[112:115], v[172:175], v[188:191], v[112:115]
	v_mfma_f32_16x16x32_bf16 v[104:107], v[180:183], v[188:191], v[104:107]
	v_mfma_f32_16x16x32_bf16 v[96:99], v[172:175], v[196:199], v[96:99]
	v_mfma_f32_16x16x32_bf16 v[88:91], v[180:183], v[196:199], v[88:91]
	v_mfma_f32_16x16x32_bf16 v[80:83], v[172:175], v[204:207], v[80:83]
	v_mfma_f32_16x16x32_bf16 v[72:75], v[180:183], v[204:207], v[72:75]
	v_mfma_f32_16x16x32_bf16 v[68:71], v[172:175], v[212:215], v[68:71]
	v_mfma_f32_16x16x32_bf16 v[64:67], v[180:183], v[212:215], v[64:67]
	s_barrier
	s_add_i32 s69, s57, s41
	v_lshl_add_u64 v[144:145], s[30:31], 0, v[132:133]
	s_mov_b32 m0, s69
	ds_read_b128 v[184:187], v151 offset:16384
	ds_read_b128 v[188:191], v151 offset:17408
	ds_read_b128 v[192:195], v151 offset:18432
	ds_read_b128 v[196:199], v151 offset:19456
	ds_read_b128 v[200:203], v151 offset:20480
	ds_read_b128 v[204:207], v151 offset:21504
	ds_read_b128 v[208:211], v151 offset:22528
	ds_read_b128 v[212:215], v151 offset:23552
	global_load_lds_dwordx4 v[144:145], off
	s_add_i32 m0, s69, 0x2000
	s_add_u32 s70, s30, 0x40000
	v_lshl_add_u64 v[216:217], s[30:31], 0, v[128:129]
	s_addc_u32 s71, s31, 0
	s_add_i32 s69, s58, s41
	global_load_lds_dwordx4 v[216:217], off
	v_lshl_add_u64 v[218:219], s[70:71], 0, v[132:133]
	s_mov_b32 m0, s69
	v_lshl_add_u64 v[220:221], s[34:35], 0, v[130:131]
	global_load_lds_dwordx4 v[218:219], off
	v_lshl_add_u64 v[218:219], s[70:71], 0, v[128:129]
	s_add_i32 m0, s69, 0x2000
	s_nop 0
	global_load_lds_dwordx4 v[218:219], off
	v_lshl_add_u64 v[218:219], s[34:35], 0, v[134:135]
	s_mov_b32 m0, s29
	s_nop 0
	global_load_lds_dwordx4 v[218:219], off
	s_mov_b32 m0, s43
	s_nop 0
	global_load_lds_dwordx4 v[220:221], off
	s_waitcnt vmcnt(8)
	s_waitcnt lgkmcnt(0)
	s_barrier
; #define PG8_STAGE(bufoff, gbase, voff) do { _Pragma("unroll") for (int _i = 0; _i < 2; ++_i) \
;         __builtin_amdgcn_global_load_lds((const unsigned*)((const char*)(gbase) + (voff)[_i]), (PG8_LAS unsigned*)(lds + (bufoff) + ldsw + _i * 8192), 16, 0, 0); } while (0)
; #define PG8_LDA(dst, b, h) do { _Pragma("unroll") for (int m = 0; m < 4; ++m) _Pragma("unroll") for (int k = 0; k < 2; ++k) dst[m][k] = *(const PG8_LAS bf16x8*)(lds + PG8_SA(b, h) + aoff + m * 2048 + k * 1024); } while (0)
; #define PG8_LDB(dst, b, h) do { _Pragma("unroll") for (int n = 0; n < 2; ++n) _Pragma("unroll") for (int k = 0; k < 2; ++k) dst[n][k] = *(const PG8_LAS bf16x8*)(lds + PG8_SB(b, h) + boff + n * 2048 + k * 1024); } while (0)
; #define PG8_MMA(ai, bj, At, Bt) do { __builtin_amdgcn_s_setprio(1); _Pragma("unroll") for (int m = 0; m < 4; ++m) _Pragma("unroll") for (int n = 0; n < 2; ++n) _Pragma("unroll") for (int k = 0; k < 2; ++k) \
;         acc[ai][bj][m][n] = __builtin_amdgcn_mfma_f32_16x16x32_bf16(Bt[n][k], At[m][k], acc[ai][bj][m][n], 0, 0, 0); __builtin_amdgcn_s_setprio(0); } while (0)
; #define PG8_WAIT_V(n) asm volatile("s_waitcnt vmcnt(" #n ")" ::: "memory")
; #define PG8_WAIT_L(n) asm volatile("s_waitcnt lgkmcnt(" #n ")" ::: "memory")
; #define PG8_BAR __builtin_amdgcn_s_barrier()
; #define PG8_SCHED __builtin_amdgcn_sched_barrier(0)
; template <class Epi, class Sched, bool ALIGN_EPI = false, bool SP2 = false>
; __device__ __forceinline__ void gemm_phase(PG8_LAS unsigned char* lds, const Gemm g, const Sched& S, const Epi& E, const int tid_in) {
;     ...
;             PG8_WAIT_V(8); PG8_WAIT_L(0); PG8_BAR; PG8_MMA(1, 0, At, B0); PG8_MMA(1, 1, At, B1); PG8_BAR; PG8_SCHED;
;             PG8_LDB(B0, 1, 0); PG8_LDB(B1, 1, 1); PG8_SCHED; PG8_LDA(At, 1, 0); PG8_STAGE(PG8_SA(0, 1), a2 + hstep, voffA);
;             PG8_WAIT_V(8); PG8_WAIT_L(0); PG8_BAR; PG8_MMA(0, 0, At, B0); PG8_MMA(0, 1, At, B1); PG8_BAR; PG8_SCHED;
;             PG8_LDA(At, 1, 1); PG8_STAGE(PG8_SB(1, 0), b3, voffB); PG8_STAGE(PG8_SB(1, 1), b3 + hstep, voffB); PG8_STAGE(PG8_SA(1, 0), a3, voffA);
;             PG8_WAIT_V(8); PG8_WAIT_L(0); PG8_BAR; PG8_MMA(1, 0, At, B0); PG8_MMA(1, 1, At, B1); PG8_BAR; PG8_SCHED;
	s_waitcnt lgkmcnt(0)
	v_mfma_f32_16x16x32_bf16 v[60:63], v[152:155], v[184:187], v[60:63]
	v_mfma_f32_16x16x32_bf16 v[56:59], v[160:163], v[184:187], v[56:59]
	v_mfma_f32_16x16x32_bf16 v[52:55], v[152:155], v[192:195], v[52:55]
	v_mfma_f32_16x16x32_bf16 v[44:47], v[160:163], v[192:195], v[44:47]
	v_mfma_f32_16x16x32_bf16 v[36:39], v[152:155], v[200:203], v[36:39]
	v_mfma_f32_16x16x32_bf16 v[28:31], v[160:163], v[200:203], v[28:31]
	v_mfma_f32_16x16x32_bf16 v[20:23], v[152:155], v[208:211], v[20:23]
	v_mfma_f32_16x16x32_bf16 v[12:15], v[160:163], v[208:211], v[12:15]
	v_mfma_f32_16x16x32_bf16 v[60:63], v[156:159], v[188:191], v[60:63]
	v_mfma_f32_16x16x32_bf16 v[56:59], v[164:167], v[188:191], v[56:59]
	v_mfma_f32_16x16x32_bf16 v[52:55], v[156:159], v[196:199], v[52:55]
	v_mfma_f32_16x16x32_bf16 v[44:47], v[164:167], v[196:199], v[44:47]
	v_mfma_f32_16x16x32_bf16 v[36:39], v[156:159], v[204:207], v[36:39]
	v_mfma_f32_16x16x32_bf16 v[28:31], v[164:167], v[204:207], v[28:31]
	v_mfma_f32_16x16x32_bf16 v[20:23], v[156:159], v[212:215], v[20:23]
	v_mfma_f32_16x16x32_bf16 v[12:15], v[164:167], v[212:215], v[12:15]
	v_mfma_f32_16x16x32_bf16 v[48:51], v[168:171], v[184:187], v[48:51]
	v_mfma_f32_16x16x32_bf16 v[40:43], v[176:179], v[184:187], v[40:43]
	v_mfma_f32_16x16x32_bf16 v[32:35], v[168:171], v[192:195], v[32:35]
	v_mfma_f32_16x16x32_bf16 v[24:27], v[176:179], v[192:195], v[24:27]
	v_mfma_f32_16x16x32_bf16 v[16:19], v[168:171], v[200:203], v[16:19]
	v_mfma_f32_16x16x32_bf16 v[8:11], v[176:179], v[200:203], v[8:11]
	v_mfma_f32_16x16x32_bf16 v[4:7], v[168:171], v[208:211], v[4:7]
	v_mfma_f32_16x16x32_bf16 v[0:3], v[176:179], v[208:211], v[0:3]
	v_mfma_f32_16x16x32_bf16 v[48:51], v[172:175], v[188:191], v[48:51]
	v_mfma_f32_16x16x32_bf16 v[40:43], v[180:183], v[188:191], v[40:43]
	v_mfma_f32_16x16x32_bf16 v[32:35], v[172:175], v[196:199], v[32:35]
	v_mfma_f32_16x16x32_bf16 v[24:27], v[180:183], v[196:199], v[24:27]
	v_mfma_f32_16x16x32_bf16 v[16:19], v[172:175], v[204:207], v[16:19]
	v_mfma_f32_16x16x32_bf16 v[8:11], v[180:183], v[204:207], v[8:11]
	v_mfma_f32_16x16x32_bf16 v[4:7], v[172:175], v[212:215], v[4:7]
	v_mfma_f32_16x16x32_bf16 v[0:3], v[180:183], v[212:215], v[0:3]
	s_barrier
	s_add_i32 s69, 0, 0x18000
	s_add_i32 s70, 0, 0x1c000
	v_add_u32_e32 v164, s69, v147
	v_add_u32_e32 v180, s70, v147
	ds_read_b128 v[152:155], v164
	ds_read_b128 v[156:159], v164 offset:1024
	ds_read_b128 v[160:163], v164 offset:2048
	ds_read_b128 v[164:167], v164 offset:3072
	ds_read_b128 v[168:171], v180
	ds_read_b128 v[172:175], v180 offset:1024
	ds_read_b128 v[176:179], v180 offset:2048
	ds_read_b128 v[180:183], v180 offset:3072
	s_add_u32 s34, s34, 0x40000
	s_addc_u32 s35, s35, 0
	s_mov_b32 m0, s44
	v_lshl_add_u64 v[222:223], s[34:35], 0, v[134:135]
	ds_read_b128 v[184:187], v151 offset:32768
	ds_read_b128 v[188:191], v151 offset:33792
	ds_read_b128 v[192:195], v151 offset:34816
	ds_read_b128 v[196:199], v151 offset:35840
	ds_read_b128 v[200:203], v151 offset:36864
	ds_read_b128 v[204:207], v151 offset:37888
	ds_read_b128 v[208:211], v151 offset:38912
	ds_read_b128 v[212:215], v151 offset:39936
	global_load_lds_dwordx4 v[222:223], off
	v_lshl_add_u64 v[222:223], s[34:35], 0, v[130:131]
	s_mov_b32 m0, s45
	s_nop 0
	global_load_lds_dwordx4 v[222:223], off
	s_waitcnt vmcnt(8)
	s_waitcnt lgkmcnt(0)
	s_barrier
	s_waitcnt lgkmcnt(0)
	v_mfma_f32_16x16x32_bf16 v[124:127], v[152:155], v[184:187], v[124:127]
	v_mfma_f32_16x16x32_bf16 v[120:123], v[160:163], v[184:187], v[120:123]
	v_mfma_f32_16x16x32_bf16 v[116:119], v[152:155], v[192:195], v[116:119]
	v_mfma_f32_16x16x32_bf16 v[108:111], v[160:163], v[192:195], v[108:111]
	v_mfma_f32_16x16x32_bf16 v[100:103], v[152:155], v[200:203], v[100:103]
	v_mfma_f32_16x16x32_bf16 v[92:95], v[160:163], v[200:203], v[92:95]
	v_mfma_f32_16x16x32_bf16 v[84:87], v[152:155], v[208:211], v[84:87]
	v_mfma_f32_16x16x32_bf16 v[76:79], v[160:163], v[208:211], v[76:79]
	v_mfma_f32_16x16x32_bf16 v[124:127], v[156:159], v[188:191], v[124:127]
	v_mfma_f32_16x16x32_bf16 v[120:123], v[164:167], v[188:191], v[120:123]
	v_mfma_f32_16x16x32_bf16 v[116:119], v[156:159], v[196:199], v[116:119]
	v_mfma_f32_16x16x32_bf16 v[108:111], v[164:167], v[196:199], v[108:111]
	v_mfma_f32_16x16x32_bf16 v[100:103], v[156:159], v[204:207], v[100:103]
	v_mfma_f32_16x16x32_bf16 v[92:95], v[164:167], v[204:207], v[92:95]
	v_mfma_f32_16x16x32_bf16 v[84:87], v[156:159], v[212:215], v[84:87]
	v_mfma_f32_16x16x32_bf16 v[76:79], v[164:167], v[212:215], v[76:79]
	v_mfma_f32_16x16x32_bf16 v[112:115], v[168:171], v[184:187], v[112:115]
	v_mfma_f32_16x16x32_bf16 v[104:107], v[176:179], v[184:187], v[104:107]
	v_mfma_f32_16x16x32_bf16 v[96:99], v[168:171], v[192:195], v[96:99]
	v_mfma_f32_16x16x32_bf16 v[88:91], v[176:179], v[192:195], v[88:91]
	v_mfma_f32_16x16x32_bf16 v[80:83], v[168:171], v[200:203], v[80:83]
	v_mfma_f32_16x16x32_bf16 v[72:75], v[176:179], v[200:203], v[72:75]
	v_mfma_f32_16x16x32_bf16 v[68:71], v[168:171], v[208:211], v[68:71]
	v_mfma_f32_16x16x32_bf16 v[64:67], v[176:179], v[208:211], v[64:67]
	v_mfma_f32_16x16x32_bf16 v[112:115], v[172:175], v[188:191], v[112:115]
	v_mfma_f32_16x16x32_bf16 v[104:107], v[180:183], v[188:191], v[104:107]
	v_mfma_f32_16x16x32_bf16 v[96:99], v[172:175], v[196:199], v[96:99]
	v_mfma_f32_16x16x32_bf16 v[88:91], v[180:183], v[196:199], v[88:91]
	v_mfma_f32_16x16x32_bf16 v[80:83], v[172:175], v[204:207], v[80:83]
	v_mfma_f32_16x16x32_bf16 v[72:75], v[180:183], v[204:207], v[72:75]
	v_mfma_f32_16x16x32_bf16 v[68:71], v[172:175], v[212:215], v[68:71]
	v_mfma_f32_16x16x32_bf16 v[64:67], v[180:183], v[212:215], v[64:67]
	s_barrier
; #define PG8_STAGE(bufoff, gbase, voff) do { _Pragma("unroll") for (int _i = 0; _i < 2; ++_i) \
;         __builtin_amdgcn_global_load_lds((const unsigned*)((const char*)(gbase) + (voff)[_i]), (PG8_LAS unsigned*)(lds + (bufoff) + ldsw + _i * 8192), 16, 0, 0); } while (0)
; #define PG8_LDA(dst, b, h) do { _Pragma("unroll") for (int m = 0; m < 4; ++m) _Pragma("unroll") for (int k = 0; k < 2; ++k) dst[m][k] = *(const PG8_LAS bf16x8*)(lds + PG8_SA(b, h) + aoff + m * 2048 + k * 1024); } while (0)
; #define PG8_MMA(ai, bj, At, Bt) do { __builtin_amdgcn_s_setprio(1); _Pragma("unroll") for (int m = 0; m < 4; ++m) _Pragma("unroll") for (int n = 0; n < 2; ++n) _Pragma("unroll") for (int k = 0; k < 2; ++k) \
;         acc[ai][bj][m][n] = __builtin_amdgcn_mfma_f32_16x16x32_bf16(Bt[n][k], At[m][k], acc[ai][bj][m][n], 0, 0, 0); __builtin_amdgcn_s_setprio(0); } while (0)
; #define PG8_WAIT_V(n) asm volatile("s_waitcnt vmcnt(" #n ")" ::: "memory")
; #define PG8_WAIT_L(n) asm volatile("s_waitcnt lgkmcnt(" #n ")" ::: "memory")
; #define PG8_BAR __builtin_amdgcn_s_barrier()
; #define PG8_SCHED __builtin_amdgcn_sched_barrier(0)
; template <class Epi, class Sched, bool ALIGN_EPI = false, bool SP2 = false>
; __device__ __forceinline__ void gemm_phase(PG8_LAS unsigned char* lds, const Gemm g, const Sched& S, const Epi& E, const int tid_in) {
;     ...
;         for (int t = 0; t < nt; t += 2) {
;             const bool last = (t == nt - 2);
;             const char* a1 = cA + (size_t)(t + 1) * kstep;
;             const char* a2 = last ? nA : cA + (size_t)(t + 2) * kstep; const char* b2 = last ? nB : cB + (size_t)(t + 2) * kstep;
;             const char* a3 = a2 + kstep; const char* b3 = b2 + kstep;
;             if (last && has_next) S.a_ready(nxt);
;     ...
;             PG8_LDA(At, 1, 1); PG8_STAGE(PG8_SB(1, 0), b3, voffB); PG8_STAGE(PG8_SB(1, 1), b3 + hstep, voffB); PG8_STAGE(PG8_SA(1, 0), a3, voffA);
;             PG8_WAIT_V(8); PG8_WAIT_L(0); PG8_BAR; PG8_MMA(1, 0, At, B0); PG8_MMA(1, 1, At, B1); PG8_BAR; PG8_SCHED;
	s_add_i32 s34, s69, s41
	v_lshl_add_u64 v[144:145], v[144:145], 0, s[4:5]
	s_mov_b32 m0, s34
	ds_read_b128 v[184:187], v151 offset:49152
	ds_read_b128 v[188:191], v151 offset:50176
	ds_read_b128 v[192:195], v151 offset:51200
	ds_read_b128 v[196:199], v151 offset:52224
	ds_read_b128 v[200:203], v151 offset:53248
	ds_read_b128 v[204:207], v151 offset:54272
	ds_read_b128 v[208:211], v151 offset:55296
	ds_read_b128 v[212:215], v151 offset:56320
	global_load_lds_dwordx4 v[144:145], off
	s_add_i32 m0, s34, 0x2000
	s_add_u32 s30, s30, 0x40080
	v_lshl_add_u64 v[144:145], v[216:217], 0, s[4:5]
	s_addc_u32 s31, s31, 0
	s_add_i32 s34, s70, s41
	global_load_lds_dwordx4 v[144:145], off
	v_lshl_add_u64 v[144:145], s[30:31], 0, v[132:133]
	s_mov_b32 m0, s34
	s_nop 0
	global_load_lds_dwordx4 v[144:145], off
	v_lshl_add_u64 v[144:145], s[30:31], 0, v[128:129]
	s_add_i32 m0, s34, 0x2000
	s_nop 0
	global_load_lds_dwordx4 v[144:145], off
	v_lshl_add_u64 v[144:145], v[218:219], 0, s[4:5]
	s_mov_b32 m0, s52
	s_nop 0
	global_load_lds_dwordx4 v[144:145], off
	v_lshl_add_u64 v[144:145], v[220:221], 0, s[4:5]
	s_mov_b32 m0, s53
	s_nop 0
	global_load_lds_dwordx4 v[144:145], off
	s_waitcnt vmcnt(8)
	s_waitcnt lgkmcnt(0)
	s_barrier
	s_waitcnt lgkmcnt(0)
	v_mfma_f32_16x16x32_bf16 v[60:63], v[152:155], v[184:187], v[60:63]
	v_mfma_f32_16x16x32_bf16 v[56:59], v[160:163], v[184:187], v[56:59]
	v_mfma_f32_16x16x32_bf16 v[52:55], v[152:155], v[192:195], v[52:55]
	v_mfma_f32_16x16x32_bf16 v[44:47], v[160:163], v[192:195], v[44:47]
	v_mfma_f32_16x16x32_bf16 v[36:39], v[152:155], v[200:203], v[36:39]
	v_mfma_f32_16x16x32_bf16 v[28:31], v[160:163], v[200:203], v[28:31]
	v_mfma_f32_16x16x32_bf16 v[20:23], v[152:155], v[208:211], v[20:23]
	v_mfma_f32_16x16x32_bf16 v[12:15], v[160:163], v[208:211], v[12:15]
	v_mfma_f32_16x16x32_bf16 v[60:63], v[156:159], v[188:191], v[60:63]
	v_mfma_f32_16x16x32_bf16 v[56:59], v[164:167], v[188:191], v[56:59]
	v_mfma_f32_16x16x32_bf16 v[52:55], v[156:159], v[196:199], v[52:55]
	v_mfma_f32_16x16x32_bf16 v[44:47], v[164:167], v[196:199], v[44:47]
	v_mfma_f32_16x16x32_bf16 v[36:39], v[156:159], v[204:207], v[36:39]
	v_mfma_f32_16x16x32_bf16 v[28:31], v[164:167], v[204:207], v[28:31]
	v_mfma_f32_16x16x32_bf16 v[20:23], v[156:159], v[212:215], v[20:23]
	v_mfma_f32_16x16x32_bf16 v[12:15], v[164:167], v[212:215], v[12:15]
	v_mfma_f32_16x16x32_bf16 v[48:51], v[168:171], v[184:187], v[48:51]
	v_mfma_f32_16x16x32_bf16 v[40:43], v[176:179], v[184:187], v[40:43]
	v_mfma_f32_16x16x32_bf16 v[32:35], v[168:171], v[192:195], v[32:35]
	v_mfma_f32_16x16x32_bf16 v[24:27], v[176:179], v[192:195], v[24:27]
	v_mfma_f32_16x16x32_bf16 v[16:19], v[168:171], v[200:203], v[16:19]
	v_mfma_f32_16x16x32_bf16 v[8:11], v[176:179], v[200:203], v[8:11]
	v_mfma_f32_16x16x32_bf16 v[4:7], v[168:171], v[208:211], v[4:7]
	v_mfma_f32_16x16x32_bf16 v[0:3], v[176:179], v[208:211], v[0:3]
	v_mfma_f32_16x16x32_bf16 v[48:51], v[172:175], v[188:191], v[48:51]
	v_mfma_f32_16x16x32_bf16 v[40:43], v[180:183], v[188:191], v[40:43]
	v_mfma_f32_16x16x32_bf16 v[32:35], v[172:175], v[196:199], v[32:35]
	v_mfma_f32_16x16x32_bf16 v[24:27], v[180:183], v[196:199], v[24:27]
	v_mfma_f32_16x16x32_bf16 v[16:19], v[172:175], v[204:207], v[16:19]
	v_mfma_f32_16x16x32_bf16 v[8:11], v[180:183], v[204:207], v[8:11]
	v_mfma_f32_16x16x32_bf16 v[4:7], v[172:175], v[212:215], v[4:7]
	v_mfma_f32_16x16x32_bf16 v[0:3], v[180:183], v[212:215], v[0:3]
	s_add_i32 s68, s68, 2
	s_add_u32 s0, s0, 0x100
	s_addc_u32 s1, s1, 0
	s_add_u32 s66, s66, 0x100
	s_addc_u32 s67, s67, 0
	s_cmp_gt_u32 s68, 13
	s_barrier
	s_cbranch_scc0 .LBB0_739
	s_and_b64 vcc, exec, s[6:7]
	s_cbranch_vccz .LBB0_742
	s_barrier

; #define PG8_STAGE(bufoff, gbase, voff) do { _Pragma("unroll") for (int _i = 0; _i < 2; ++_i) \
;         __builtin_amdgcn_global_load_lds((const unsigned*)((const char*)(gbase) + (voff)[_i]), (PG8_LAS unsigned*)(lds + (bufoff) + ldsw + _i * 8192), 16, 0, 0); } while (0)
; #define PG8_LDA(dst, b, h) do { _Pragma("unroll") for (int m = 0; m < 4; ++m) _Pragma("unroll") for (int k = 0; k < 2; ++k) dst[m][k] = *(const PG8_LAS bf16x8*)(lds + PG8_SA(b, h) + aoff + m * 2048 + k * 1024); } while (0)
; #define PG8_LDB(dst, b, h) do { _Pragma("unroll") for (int n = 0; n < 2; ++n) _Pragma("unroll") for (int k = 0; k < 2; ++k) dst[n][k] = *(const PG8_LAS bf16x8*)(lds + PG8_SB(b, h) + boff + n * 2048 + k * 1024); } while (0)
; #define PG8_MMA(ai, bj, At, Bt) do { __builtin_amdgcn_s_setprio(1); _Pragma("unroll") for (int m = 0; m < 4; ++m) _Pragma("unroll") for (int n = 0; n < 2; ++n) _Pragma("unroll") for (int k = 0; k < 2; ++k) \
;         acc[ai][bj][m][n] = __builtin_amdgcn_mfma_f32_16x16x32_bf16(Bt[n][k], At[m][k], acc[ai][bj][m][n], 0, 0, 0); __builtin_amdgcn_s_setprio(0); } while (0)
; #define PG8_WAIT_V(n) asm volatile("s_waitcnt vmcnt(" #n ")" ::: "memory")
; #define PG8_WAIT_L(n) asm volatile("s_waitcnt lgkmcnt(" #n ")" ::: "memory")
; #define PG8_BAR __builtin_amdgcn_s_barrier()
; #define PG8_SCHED __builtin_amdgcn_sched_barrier(0)
; template <class Epi, class Sched, bool ALIGN_EPI = false, bool SP2 = false>
; __device__ __forceinline__ void gemm_phase(PG8_LAS unsigned char* lds, const Gemm g, const Sched& S, const Epi& E, const int tid_in) {
;     ...
;             PG8_LDB(B0, 0, 0); PG8_LDB(B1, 0, 1); PG8_SCHED; PG8_LDA(At, 0, 0); PG8_STAGE(PG8_SA(1, 1), a1 + hstep, voffA);
;             PG8_WAIT_V(8); PG8_WAIT_L(0); PG8_BAR; PG8_MMA(0, 0, At, B0); PG8_MMA(0, 1, At, B1); PG8_BAR; PG8_SCHED;
;             PG8_LDA(At, 0, 1); PG8_STAGE(PG8_SB(0, 0), b2, voffB); PG8_STAGE(PG8_SB(0, 1), b2 + hstep, voffB); PG8_STAGE(PG8_SA(0, 0), a2, voffA);
;             PG8_WAIT_V(8); PG8_WAIT_L(0); PG8_BAR; PG8_MMA(1, 0, At, B0); PG8_MMA(1, 1, At, B1); PG8_BAR; PG8_SCHED;
;             PG8_LDB(B0, 1, 0); PG8_LDB(B1, 1, 1); PG8_SCHED; PG8_LDA(At, 1, 0); PG8_STAGE(PG8_SA(0, 1), a2 + hstep, voffA);
;             PG8_WAIT_V(8); PG8_WAIT_L(0); PG8_BAR; PG8_MMA(0, 0, At, B0); PG8_MMA(0, 1, At, B1); PG8_BAR; PG8_SCHED;
.Lmy_rb_done:
	s_barrier
	s_waitcnt lgkmcnt(0)
	v_mfma_f32_16x16x32_bf16 v[124:127], v[144:147], v[200:203], v[124:127]
	v_mfma_f32_16x16x32_bf16 v[120:123], v[176:179], v[200:203], v[120:123]
	v_mfma_f32_16x16x32_bf16 v[116:119], v[144:147], v[208:211], v[116:119]
	v_mfma_f32_16x16x32_bf16 v[104:107], v[176:179], v[208:211], v[104:107]
	v_mfma_f32_16x16x32_bf16 v[100:103], v[144:147], v[216:219], v[100:103]
	v_mfma_f32_16x16x32_bf16 v[88:91], v[176:179], v[216:219], v[88:91]
	v_mfma_f32_16x16x32_bf16 v[84:87], v[144:147], v[224:227], v[84:87]
	v_mfma_f32_16x16x32_bf16 v[72:75], v[176:179], v[224:227], v[72:75]
	v_mfma_f32_16x16x32_bf16 v[124:127], v[172:175], v[204:207], v[124:127]
	v_mfma_f32_16x16x32_bf16 v[120:123], v[180:183], v[204:207], v[120:123]
	v_mfma_f32_16x16x32_bf16 v[116:119], v[172:175], v[212:215], v[116:119]
	v_mfma_f32_16x16x32_bf16 v[104:107], v[180:183], v[212:215], v[104:107]
	v_mfma_f32_16x16x32_bf16 v[100:103], v[172:175], v[220:223], v[100:103]
	v_mfma_f32_16x16x32_bf16 v[88:91], v[180:183], v[220:223], v[88:91]
	v_mfma_f32_16x16x32_bf16 v[84:87], v[172:175], v[228:231], v[84:87]
	v_mfma_f32_16x16x32_bf16 v[72:75], v[180:183], v[228:231], v[72:75]
	v_mfma_f32_16x16x32_bf16 v[112:115], v[184:187], v[200:203], v[112:115]
	v_mfma_f32_16x16x32_bf16 v[108:111], v[192:195], v[200:203], v[108:111]
	v_mfma_f32_16x16x32_bf16 v[96:99], v[184:187], v[208:211], v[96:99]
	v_mfma_f32_16x16x32_bf16 v[92:95], v[192:195], v[208:211], v[92:95]
	v_mfma_f32_16x16x32_bf16 v[80:83], v[184:187], v[216:219], v[80:83]
	v_mfma_f32_16x16x32_bf16 v[76:79], v[192:195], v[216:219], v[76:79]
	v_mfma_f32_16x16x32_bf16 v[68:71], v[184:187], v[224:227], v[68:71]
	v_mfma_f32_16x16x32_bf16 v[64:67], v[192:195], v[224:227], v[64:67]
	v_mfma_f32_16x16x32_bf16 v[112:115], v[188:191], v[204:207], v[112:115]
	v_mfma_f32_16x16x32_bf16 v[108:111], v[196:199], v[204:207], v[108:111]
	v_mfma_f32_16x16x32_bf16 v[96:99], v[188:191], v[212:215], v[96:99]
	v_mfma_f32_16x16x32_bf16 v[92:95], v[196:199], v[212:215], v[92:95]
	v_mfma_f32_16x16x32_bf16 v[80:83], v[188:191], v[220:223], v[80:83]
	v_mfma_f32_16x16x32_bf16 v[76:79], v[196:199], v[220:223], v[76:79]
	v_mfma_f32_16x16x32_bf16 v[68:71], v[188:191], v[228:231], v[68:71]
	v_mfma_f32_16x16x32_bf16 v[64:67], v[196:199], v[228:231], v[64:67]
	s_barrier
	s_add_i32 s71, s63, s56
	v_lshl_add_u64 v[148:149], s[42:43], 0, v[132:133]
	s_mov_b32 m0, s71
	ds_read_b128 v[200:203], v170 offset:16384
	ds_read_b128 v[204:207], v170 offset:17408
	ds_read_b128 v[208:211], v170 offset:18432
	ds_read_b128 v[212:215], v170 offset:19456
	ds_read_b128 v[216:219], v170 offset:20480
	ds_read_b128 v[220:223], v170 offset:21504
	ds_read_b128 v[224:227], v170 offset:22528
	ds_read_b128 v[228:231], v170 offset:23552
	global_load_lds_dwordx4 v[148:149], off
	s_add_i32 m0, s71, 0x2000
	s_add_u32 s72, s42, 0x40000
	v_lshl_add_u64 v[232:233], s[42:43], 0, v[128:129]
	s_addc_u32 s73, s43, 0
	s_add_i32 s71, s64, s56
	global_load_lds_dwordx4 v[232:233], off
	v_lshl_add_u64 v[234:235], s[72:73], 0, v[132:133]
	s_mov_b32 m0, s71
	v_lshl_add_u64 v[236:237], s[44:45], 0, v[130:131]
	global_load_lds_dwordx4 v[234:235], off
	v_lshl_add_u64 v[234:235], s[72:73], 0, v[128:129]
	s_add_i32 m0, s71, 0x2000
	s_nop 0
	global_load_lds_dwordx4 v[234:235], off
	v_lshl_add_u64 v[234:235], s[44:45], 0, v[134:135]
	s_mov_b32 m0, s41
	s_nop 0
	global_load_lds_dwordx4 v[234:235], off
	s_mov_b32 m0, s57
	s_nop 0
	global_load_lds_dwordx4 v[236:237], off
	s_waitcnt vmcnt(8)
	s_waitcnt lgkmcnt(0)
	global_load_dwordx4 v[242:245], v[240:241], off
	global_load_dwordx4 v[246:249], v[240:241], off offset:256
	s_mov_b32 s98, 0x8000
	s_cmp_eq_u32 s70, 4
	s_cselect_b32 s98, 0x28000, s98
	v_add_co_u32_e32 v240, vcc, s98, v240
	s_nop 1
	v_addc_co_u32_e32 v241, vcc, 0, v241, vcc
	s_barrier
	s_waitcnt lgkmcnt(0)
	v_mfma_f32_16x16x32_bf16 v[60:63], v[144:147], v[200:203], v[60:63]
	v_mfma_f32_16x16x32_bf16 v[56:59], v[176:179], v[200:203], v[56:59]
	v_mfma_f32_16x16x32_bf16 v[52:55], v[144:147], v[208:211], v[52:55]
	v_mfma_f32_16x16x32_bf16 v[40:43], v[176:179], v[208:211], v[40:43]
	v_mfma_f32_16x16x32_bf16 v[36:39], v[144:147], v[216:219], v[36:39]
	v_mfma_f32_16x16x32_bf16 v[24:27], v[176:179], v[216:219], v[24:27]
	v_mfma_f32_16x16x32_bf16 v[20:23], v[144:147], v[224:227], v[20:23]
	v_mfma_f32_16x16x32_bf16 v[8:11], v[176:179], v[224:227], v[8:11]
	v_mfma_f32_16x16x32_bf16 v[60:63], v[172:175], v[204:207], v[60:63]
	v_mfma_f32_16x16x32_bf16 v[56:59], v[180:183], v[204:207], v[56:59]
	v_mfma_f32_16x16x32_bf16 v[52:55], v[172:175], v[212:215], v[52:55]
	v_mfma_f32_16x16x32_bf16 v[40:43], v[180:183], v[212:215], v[40:43]
	v_mfma_f32_16x16x32_bf16 v[36:39], v[172:175], v[220:223], v[36:39]
	v_mfma_f32_16x16x32_bf16 v[24:27], v[180:183], v[220:223], v[24:27]
	v_mfma_f32_16x16x32_bf16 v[20:23], v[172:175], v[228:231], v[20:23]
	v_mfma_f32_16x16x32_bf16 v[8:11], v[180:183], v[228:231], v[8:11]
	v_mfma_f32_16x16x32_bf16 v[48:51], v[184:187], v[200:203], v[48:51]
	v_mfma_f32_16x16x32_bf16 v[44:47], v[192:195], v[200:203], v[44:47]
	v_mfma_f32_16x16x32_bf16 v[32:35], v[184:187], v[208:211], v[32:35]
	v_mfma_f32_16x16x32_bf16 v[28:31], v[192:195], v[208:211], v[28:31]
	v_mfma_f32_16x16x32_bf16 v[16:19], v[184:187], v[216:219], v[16:19]
	v_mfma_f32_16x16x32_bf16 v[12:15], v[192:195], v[216:219], v[12:15]
	v_mfma_f32_16x16x32_bf16 v[4:7], v[184:187], v[224:227], v[4:7]
	v_mfma_f32_16x16x32_bf16 v[0:3], v[192:195], v[224:227], v[0:3]
	v_mfma_f32_16x16x32_bf16 v[48:51], v[188:191], v[204:207], v[48:51]
	v_mfma_f32_16x16x32_bf16 v[44:47], v[196:199], v[204:207], v[44:47]
	v_mfma_f32_16x16x32_bf16 v[32:35], v[188:191], v[212:215], v[32:35]
	v_mfma_f32_16x16x32_bf16 v[28:31], v[196:199], v[212:215], v[28:31]
	v_mfma_f32_16x16x32_bf16 v[16:19], v[188:191], v[220:223], v[16:19]
	v_mfma_f32_16x16x32_bf16 v[12:15], v[196:199], v[220:223], v[12:15]
	v_mfma_f32_16x16x32_bf16 v[4:7], v[188:191], v[228:231], v[4:7]
	v_mfma_f32_16x16x32_bf16 v[0:3], v[196:199], v[228:231], v[0:3]
	s_barrier
; #define PG8_STAGE(bufoff, gbase, voff) do { _Pragma("unroll") for (int _i = 0; _i < 2; ++_i) \
;         __builtin_amdgcn_global_load_lds((const unsigned*)((const char*)(gbase) + (voff)[_i]), (PG8_LAS unsigned*)(lds + (bufoff) + ldsw + _i * 8192), 16, 0, 0); } while (0)
; #define PG8_LDA(dst, b, h) do { _Pragma("unroll") for (int m = 0; m < 4; ++m) _Pragma("unroll") for (int k = 0; k < 2; ++k) dst[m][k] = *(const PG8_LAS bf16x8*)(lds + PG8_SA(b, h) + aoff + m * 2048 + k * 1024); } while (0)
; #define PG8_LDB(dst, b, h) do { _Pragma("unroll") for (int n = 0; n < 2; ++n) _Pragma("unroll") for (int k = 0; k < 2; ++k) dst[n][k] = *(const PG8_LAS bf16x8*)(lds + PG8_SB(b, h) + boff + n * 2048 + k * 1024); } while (0)
; #define PG8_MMA(ai, bj, At, Bt) do { __builtin_amdgcn_s_setprio(1); _Pragma("unroll") for (int m = 0; m < 4; ++m) _Pragma("unroll") for (int n = 0; n < 2; ++n) _Pragma("unroll") for (int k = 0; k < 2; ++k) \
;         acc[ai][bj][m][n] = __builtin_amdgcn_mfma_f32_16x16x32_bf16(Bt[n][k], At[m][k], acc[ai][bj][m][n], 0, 0, 0); __builtin_amdgcn_s_setprio(0); } while (0)
; #define PG8_WAIT_V(n) asm volatile("s_waitcnt vmcnt(" #n ")" ::: "memory")
; #define PG8_WAIT_L(n) asm volatile("s_waitcnt lgkmcnt(" #n ")" ::: "memory")
; #define PG8_BAR __builtin_amdgcn_s_barrier()
; #define PG8_SCHED __builtin_amdgcn_sched_barrier(0)
; template <class Epi, class Sched, bool ALIGN_EPI = false, bool SP2 = false>
; __device__ __forceinline__ void gemm_phase(PG8_LAS unsigned char* lds, const Gemm g, const Sched& S, const Epi& E, const int tid_in) {
;     ...
;             PG8_LDB(B0, 1, 0); PG8_LDB(B1, 1, 1); PG8_SCHED; PG8_LDA(At, 1, 0); PG8_STAGE(PG8_SA(0, 1), a2 + hstep, voffA);
;             PG8_WAIT_V(8); PG8_WAIT_L(0); PG8_BAR; PG8_MMA(0, 0, At, B0); PG8_MMA(0, 1, At, B1); PG8_BAR; PG8_SCHED;
;             PG8_LDA(At, 1, 1); PG8_STAGE(PG8_SB(1, 0), b3, voffB); PG8_STAGE(PG8_SB(1, 1), b3 + hstep, voffB); PG8_STAGE(PG8_SA(1, 0), a3, voffA);
;             PG8_WAIT_V(8); PG8_WAIT_L(0); PG8_BAR; PG8_MMA(1, 0, At, B0); PG8_MMA(1, 1, At, B1); PG8_BAR; PG8_SCHED;
	s_add_i32 s71, 0, 0x18000
	v_add_u32_e32 v171, s71, v166
	s_add_i32 s72, 0, 0x1c000
	ds_read_b128 v[144:147], v171
	ds_read_b128 v[172:175], v171 offset:1024
	ds_read_b128 v[176:179], v171 offset:2048
	ds_read_b128 v[180:183], v171 offset:3072
	v_add_u32_e32 v171, s72, v166
	ds_read_b128 v[184:187], v171
	ds_read_b128 v[188:191], v171 offset:1024
	ds_read_b128 v[192:195], v171 offset:2048
	ds_read_b128 v[196:199], v171 offset:3072
	s_add_u32 s44, s44, 0x40000
	s_addc_u32 s45, s45, 0
	s_mov_b32 m0, s58
	v_lshl_add_u64 v[238:239], s[44:45], 0, v[134:135]
	ds_read_b128 v[200:203], v170 offset:32768
	ds_read_b128 v[204:207], v170 offset:33792
	ds_read_b128 v[208:211], v170 offset:34816
	ds_read_b128 v[212:215], v170 offset:35840
	ds_read_b128 v[216:219], v170 offset:36864
	ds_read_b128 v[220:223], v170 offset:37888
	ds_read_b128 v[224:227], v170 offset:38912
	ds_read_b128 v[228:231], v170 offset:39936
	global_load_lds_dwordx4 v[238:239], off
	v_lshl_add_u64 v[238:239], s[44:45], 0, v[130:131]
	s_mov_b32 m0, s59
	s_nop 0
	global_load_lds_dwordx4 v[238:239], off
	s_waitcnt vmcnt(10)
	s_waitcnt lgkmcnt(0)
	s_barrier
	s_waitcnt lgkmcnt(0)
	v_mfma_f32_16x16x32_bf16 v[124:127], v[144:147], v[200:203], v[124:127]
	v_mfma_f32_16x16x32_bf16 v[120:123], v[176:179], v[200:203], v[120:123]
	v_mfma_f32_16x16x32_bf16 v[116:119], v[144:147], v[208:211], v[116:119]
	v_mfma_f32_16x16x32_bf16 v[104:107], v[176:179], v[208:211], v[104:107]
	v_mfma_f32_16x16x32_bf16 v[100:103], v[144:147], v[216:219], v[100:103]
	v_mfma_f32_16x16x32_bf16 v[88:91], v[176:179], v[216:219], v[88:91]
	v_mfma_f32_16x16x32_bf16 v[84:87], v[144:147], v[224:227], v[84:87]
	v_mfma_f32_16x16x32_bf16 v[72:75], v[176:179], v[224:227], v[72:75]
	v_mfma_f32_16x16x32_bf16 v[124:127], v[172:175], v[204:207], v[124:127]
	v_mfma_f32_16x16x32_bf16 v[120:123], v[180:183], v[204:207], v[120:123]
	v_mfma_f32_16x16x32_bf16 v[116:119], v[172:175], v[212:215], v[116:119]
	v_mfma_f32_16x16x32_bf16 v[104:107], v[180:183], v[212:215], v[104:107]
	v_mfma_f32_16x16x32_bf16 v[100:103], v[172:175], v[220:223], v[100:103]
	v_mfma_f32_16x16x32_bf16 v[88:91], v[180:183], v[220:223], v[88:91]
	v_mfma_f32_16x16x32_bf16 v[84:87], v[172:175], v[228:231], v[84:87]
	v_mfma_f32_16x16x32_bf16 v[72:75], v[180:183], v[228:231], v[72:75]
	v_mfma_f32_16x16x32_bf16 v[112:115], v[184:187], v[200:203], v[112:115]
	v_mfma_f32_16x16x32_bf16 v[108:111], v[192:195], v[200:203], v[108:111]
	v_mfma_f32_16x16x32_bf16 v[96:99], v[184:187], v[208:211], v[96:99]
	v_mfma_f32_16x16x32_bf16 v[92:95], v[192:195], v[208:211], v[92:95]
	v_mfma_f32_16x16x32_bf16 v[80:83], v[184:187], v[216:219], v[80:83]
	v_mfma_f32_16x16x32_bf16 v[76:79], v[192:195], v[216:219], v[76:79]
	v_mfma_f32_16x16x32_bf16 v[68:71], v[184:187], v[224:227], v[68:71]
	v_mfma_f32_16x16x32_bf16 v[64:67], v[192:195], v[224:227], v[64:67]
	v_mfma_f32_16x16x32_bf16 v[112:115], v[188:191], v[204:207], v[112:115]
	v_mfma_f32_16x16x32_bf16 v[108:111], v[196:199], v[204:207], v[108:111]
	v_mfma_f32_16x16x32_bf16 v[96:99], v[188:191], v[212:215], v[96:99]
	v_mfma_f32_16x16x32_bf16 v[92:95], v[196:199], v[212:215], v[92:95]
	v_mfma_f32_16x16x32_bf16 v[80:83], v[188:191], v[220:223], v[80:83]
	v_mfma_f32_16x16x32_bf16 v[76:79], v[196:199], v[220:223], v[76:79]
	v_mfma_f32_16x16x32_bf16 v[68:71], v[188:191], v[228:231], v[68:71]
	v_mfma_f32_16x16x32_bf16 v[64:67], v[196:199], v[228:231], v[64:67]
	s_barrier
; #define PG8_STAGE(bufoff, gbase, voff) do { _Pragma("unroll") for (int _i = 0; _i < 2; ++_i) \
;         __builtin_amdgcn_global_load_lds((const unsigned*)((const char*)(gbase) + (voff)[_i]), (PG8_LAS unsigned*)(lds + (bufoff) + ldsw + _i * 8192), 16, 0, 0); } while (0)
; #define PG8_LDA(dst, b, h) do { _Pragma("unroll") for (int m = 0; m < 4; ++m) _Pragma("unroll") for (int k = 0; k < 2; ++k) dst[m][k] = *(const PG8_LAS bf16x8*)(lds + PG8_SA(b, h) + aoff + m * 2048 + k * 1024); } while (0)
; #define PG8_MMA(ai, bj, At, Bt) do { __builtin_amdgcn_s_setprio(1); _Pragma("unroll") for (int m = 0; m < 4; ++m) _Pragma("unroll") for (int n = 0; n < 2; ++n) _Pragma("unroll") for (int k = 0; k < 2; ++k) \
;         acc[ai][bj][m][n] = __builtin_amdgcn_mfma_f32_16x16x32_bf16(Bt[n][k], At[m][k], acc[ai][bj][m][n], 0, 0, 0); __builtin_amdgcn_s_setprio(0); } while (0)
; #define PG8_WAIT_V(n) asm volatile("s_waitcnt vmcnt(" #n ")" ::: "memory")
; #define PG8_WAIT_L(n) asm volatile("s_waitcnt lgkmcnt(" #n ")" ::: "memory")
; #define PG8_BAR __builtin_amdgcn_s_barrier()
; #define PG8_SCHED __builtin_amdgcn_sched_barrier(0)
; template <class Epi, class Sched, bool ALIGN_EPI = false, bool SP2 = false>
; __device__ __forceinline__ void gemm_phase(PG8_LAS unsigned char* lds, const Gemm g, const Sched& S, const Epi& E, const int tid_in) {
;     ...
;         for (int t = 0; t < nt; t += 2) {
;             const bool last = (t == nt - 2);
;             const char* a1 = cA + (size_t)(t + 1) * kstep;
;             const char* a2 = last ? nA : cA + (size_t)(t + 2) * kstep; const char* b2 = last ? nB : cB + (size_t)(t + 2) * kstep;
;             const char* a3 = a2 + kstep; const char* b3 = b2 + kstep;
;             if (last && has_next) S.a_ready(nxt);
;     ...
;             PG8_LDA(At, 1, 1); PG8_STAGE(PG8_SB(1, 0), b3, voffB); PG8_STAGE(PG8_SB(1, 1), b3 + hstep, voffB); PG8_STAGE(PG8_SA(1, 0), a3, voffA);
;             PG8_WAIT_V(8); PG8_WAIT_L(0); PG8_BAR; PG8_MMA(1, 0, At, B0); PG8_MMA(1, 1, At, B1); PG8_BAR; PG8_SCHED;
	s_add_i32 s44, s71, s56
	v_lshl_add_u64 v[148:149], v[148:149], 0, s[20:21]
	s_mov_b32 m0, s44
	ds_read_b128 v[200:203], v170 offset:49152
	ds_read_b128 v[204:207], v170 offset:50176
	ds_read_b128 v[208:211], v170 offset:51200
	ds_read_b128 v[212:215], v170 offset:52224
	ds_read_b128 v[216:219], v170 offset:53248
	ds_read_b128 v[220:223], v170 offset:54272
	ds_read_b128 v[224:227], v170 offset:55296
	ds_read_b128 v[228:231], v170 offset:56320
	global_load_lds_dwordx4 v[148:149], off
	s_add_i32 m0, s44, 0x2000
	s_add_u32 s42, s42, 0x40080
	v_lshl_add_u64 v[148:149], v[232:233], 0, s[20:21]
	s_addc_u32 s43, s43, 0
	s_add_i32 s44, s72, s56
	global_load_lds_dwordx4 v[148:149], off
	v_lshl_add_u64 v[148:149], s[42:43], 0, v[132:133]
	s_mov_b32 m0, s44
	s_nop 0
	global_load_lds_dwordx4 v[148:149], off
	v_lshl_add_u64 v[148:149], s[42:43], 0, v[128:129]
	s_add_i32 m0, s44, 0x2000
	s_nop 0
	global_load_lds_dwordx4 v[148:149], off
	v_lshl_add_u64 v[148:149], v[234:235], 0, s[20:21]
	s_mov_b32 m0, s60
	s_nop 0
	global_load_lds_dwordx4 v[148:149], off
	v_lshl_add_u64 v[148:149], v[236:237], 0, s[20:21]
	s_mov_b32 m0, s61
	s_nop 0
	global_load_lds_dwordx4 v[148:149], off
	s_waitcnt vmcnt(10)
	s_waitcnt lgkmcnt(0)
	s_barrier
	s_waitcnt lgkmcnt(0)
	v_mfma_f32_16x16x32_bf16 v[60:63], v[144:147], v[200:203], v[60:63]
	v_mfma_f32_16x16x32_bf16 v[56:59], v[176:179], v[200:203], v[56:59]
	v_mfma_f32_16x16x32_bf16 v[52:55], v[144:147], v[208:211], v[52:55]
	v_mfma_f32_16x16x32_bf16 v[40:43], v[176:179], v[208:211], v[40:43]
	v_mfma_f32_16x16x32_bf16 v[36:39], v[144:147], v[216:219], v[36:39]
	v_mfma_f32_16x16x32_bf16 v[24:27], v[176:179], v[216:219], v[24:27]
	v_mfma_f32_16x16x32_bf16 v[20:23], v[144:147], v[224:227], v[20:23]
	v_mfma_f32_16x16x32_bf16 v[8:11], v[176:179], v[224:227], v[8:11]
	v_mfma_f32_16x16x32_bf16 v[60:63], v[172:175], v[204:207], v[60:63]
	v_mfma_f32_16x16x32_bf16 v[56:59], v[180:183], v[204:207], v[56:59]
	v_mfma_f32_16x16x32_bf16 v[52:55], v[172:175], v[212:215], v[52:55]
	v_mfma_f32_16x16x32_bf16 v[40:43], v[180:183], v[212:215], v[40:43]
	v_mfma_f32_16x16x32_bf16 v[36:39], v[172:175], v[220:223], v[36:39]
	v_mfma_f32_16x16x32_bf16 v[24:27], v[180:183], v[220:223], v[24:27]
	v_mfma_f32_16x16x32_bf16 v[20:23], v[172:175], v[228:231], v[20:23]
	v_mfma_f32_16x16x32_bf16 v[8:11], v[180:183], v[228:231], v[8:11]
	v_mfma_f32_16x16x32_bf16 v[48:51], v[184:187], v[200:203], v[48:51]
	v_mfma_f32_16x16x32_bf16 v[44:47], v[192:195], v[200:203], v[44:47]
	v_mfma_f32_16x16x32_bf16 v[32:35], v[184:187], v[208:211], v[32:35]
	v_mfma_f32_16x16x32_bf16 v[28:31], v[192:195], v[208:211], v[28:31]
	v_mfma_f32_16x16x32_bf16 v[16:19], v[184:187], v[216:219], v[16:19]
	v_mfma_f32_16x16x32_bf16 v[12:15], v[192:195], v[216:219], v[12:15]
	v_mfma_f32_16x16x32_bf16 v[4:7], v[184:187], v[224:227], v[4:7]
	v_mfma_f32_16x16x32_bf16 v[0:3], v[192:195], v[224:227], v[0:3]
	v_mfma_f32_16x16x32_bf16 v[48:51], v[188:191], v[204:207], v[48:51]
	v_mfma_f32_16x16x32_bf16 v[44:47], v[196:199], v[204:207], v[44:47]
	v_mfma_f32_16x16x32_bf16 v[32:35], v[188:191], v[212:215], v[32:35]
	v_mfma_f32_16x16x32_bf16 v[28:31], v[196:199], v[212:215], v[28:31]
	v_mfma_f32_16x16x32_bf16 v[16:19], v[188:191], v[220:223], v[16:19]
	v_mfma_f32_16x16x32_bf16 v[12:15], v[196:199], v[220:223], v[12:15]
	v_mfma_f32_16x16x32_bf16 v[4:7], v[188:191], v[228:231], v[4:7]
	v_mfma_f32_16x16x32_bf16 v[0:3], v[196:199], v[228:231], v[0:3]
	s_add_i32 s70, s70, 2
	s_add_u32 s0, s0, 0x100
	s_addc_u32 s1, s1, 0
	s_add_u32 s68, s68, 0x100
	s_addc_u32 s69, s69, 0
	s_cmp_gt_u32 s70, 13
	s_barrier
	s_cbranch_scc0 .LBB0_1080
	s_and_b64 vcc, exec, s[22:23]
	s_cbranch_vccz .LBB0_1083
	s_barrier
